# v17: v16 + GEMM K-loop LDS-DMA staging rebalanced 2/6/2/6 -> 4/4/4/4 pieces per super-phase (A half-tiles staged one phase later, SP2 waits vmcnt(4))
# speedup vs baseline: 1.0131x; 1.0015x over previous
; #define PG8_WAIT_V(n) asm volatile("s_waitcnt vmcnt(" #n ")" ::: "memory")
; #define PG8_WAIT_L(n) asm volatile("s_waitcnt lgkmcnt(" #n ")" ::: "memory")
; #define PG8_BAR __builtin_amdgcn_s_barrier()
; #define PG8_SCHED __builtin_amdgcn_sched_barrier(0)
;     ...
;             PG8_LDB(B0, 0, 0); PG8_LDB(B1, 0, 1); PG8_SCHED; PG8_LDA(At, 0, 0); PG8_STAGE(PG8_SA(1, 1), a1 + hstepA, voffA);
;             PG8_WAIT_V(8); PG8_WAIT_L(0); PG8_BAR; PG8_MMA(0, 0, At, B0); PG8_MMA(0, 1, At, B1); PG8_BAR; PG8_SCHED;
;             if constexpr (!HALFU) PG8_LDA(At, 0, 1); PG8_STAGE(PG8_SB(0, 0), b2, voffB); PG8_STAGE(PG8_SB(0, 1), b2 + hstep, voffB); PG8_STAGE(PG8_SA(0, 0), a2, voffA);
;             PG8_WAIT_V(8); PG8_WAIT_L(0); PG8_BAR; if constexpr (!HALFU) { PG8_MMA(1, 0, At, B0); PG8_MMA(1, 1, At, B1); } PG8_BAR; PG8_SCHED;
.LBB0_317:
	s_add_u32 s98, s14, 0x80
	s_addc_u32 s99, s15, 0
	s_mov_b32 m0, s49
	s_nop 0
	global_load_lds_dwordx4 v252, s[98:99]
	s_mov_b32 m0, s50
	s_nop 0
	global_load_lds_dwordx4 v146, s[98:99]
	ds_read_b128 v[128:131], v155
	ds_read_b128 v[132:135], v155 offset:1024
	ds_read_b128 v[164:167], v155 offset:2048
	ds_read_b128 v[168:171], v155 offset:3072
	ds_read_b128 v[172:175], v156
	ds_read_b128 v[176:179], v156 offset:1024
	ds_read_b128 v[180:183], v156 offset:2048
	ds_read_b128 v[184:187], v156 offset:3072
	s_add_u32 s30, s14, 0x100
	s_addc_u32 s31, s15, 0
	s_cmp_eq_u32 s58, 28
	s_cselect_b32 s38, s23, s30
	s_cselect_b32 s39, s7, s31
	s_cselect_b32 s36, s55, s56
	s_cselect_b32 s37, s21, s57
	s_add_u32 s34, s38, 0x80
	s_addc_u32 s35, s39, 0
	s_add_u32 s14, s14, 0x80080
	s_addc_u32 s15, s15, 0
	s_add_i32 m0, s29, 0xc000
	ds_read_b128 v[188:191], v157
	ds_read_b128 v[192:195], v157 offset:1024
	ds_read_b128 v[196:199], v157 offset:2048
	ds_read_b128 v[200:203], v157 offset:3072
	ds_read_b128 v[204:207], v157 offset:4096
	ds_read_b128 v[208:211], v157 offset:5120
	ds_read_b128 v[212:215], v157 offset:6144
	ds_read_b128 v[216:219], v157 offset:7168
	global_load_lds_dwordx4 v252, s[14:15]
	s_add_i32 m0, s29, 0xe000
	s_nop 0
	global_load_lds_dwordx4 v146, s[14:15]
	s_waitcnt vmcnt(8)
	s_waitcnt lgkmcnt(0)
	s_barrier
	s_setprio 1
	s_waitcnt lgkmcnt(0)
	v_mfma_scale_f32_16x16x128_f8f6f4 v[124:127], v[128:135], v[188:195], v[124:127], v158, v158 op_sel_hi:[0,0,0]
	v_mfma_scale_f32_16x16x128_f8f6f4 v[120:123], v[164:171], v[188:195], v[120:123], v158, v158 op_sel_hi:[0,0,0]
	v_mfma_scale_f32_16x16x128_f8f6f4 v[108:111], v[128:135], v[196:203], v[108:111], v158, v158 op_sel_hi:[0,0,0]
	v_mfma_scale_f32_16x16x128_f8f6f4 v[104:107], v[164:171], v[196:203], v[104:107], v158, v158 op_sel_hi:[0,0,0]
	v_mfma_scale_f32_16x16x128_f8f6f4 v[136:139], v[128:135], v[204:211], v[92:95], v158, v158 op_sel_hi:[0,0,0]
	v_mfma_scale_f32_16x16x128_f8f6f4 v[220:223], v[164:171], v[204:211], v[88:91], v158, v158 op_sel_hi:[0,0,0]
	v_mfma_scale_f32_16x16x128_f8f6f4 v[224:227], v[128:135], v[212:219], v[76:79], v158, v158 op_sel_hi:[0,0,0]
	v_mfma_scale_f32_16x16x128_f8f6f4 v[228:231], v[164:171], v[212:219], v[72:75], v158, v158 op_sel_hi:[0,0,0]
	s_setprio 0
	s_setprio 1
	v_mfma_scale_f32_16x16x128_f8f6f4 v[116:119], v[172:179], v[188:195], v[116:119], v158, v158 op_sel_hi:[0,0,0]
	v_mfma_scale_f32_16x16x128_f8f6f4 v[112:115], v[180:187], v[188:195], v[112:115], v158, v158 op_sel_hi:[0,0,0]
	v_mfma_scale_f32_16x16x128_f8f6f4 v[100:103], v[172:179], v[196:203], v[100:103], v158, v158 op_sel_hi:[0,0,0]
	v_mfma_scale_f32_16x16x128_f8f6f4 v[96:99], v[180:187], v[196:203], v[96:99], v158, v158 op_sel_hi:[0,0,0]
	v_mfma_scale_f32_16x16x128_f8f6f4 v[188:191], v[172:179], v[204:211], v[84:87], v158, v158 op_sel_hi:[0,0,0]
	v_mfma_scale_f32_16x16x128_f8f6f4 v[192:195], v[180:187], v[204:211], v[80:83], v158, v158 op_sel_hi:[0,0,0]
	v_mfma_scale_f32_16x16x128_f8f6f4 v[196:199], v[172:179], v[212:219], v[68:71], v158, v158 op_sel_hi:[0,0,0]
	v_mfma_scale_f32_16x16x128_f8f6f4 v[200:203], v[180:187], v[212:219], v[64:67], v158, v158 op_sel_hi:[0,0,0]
	s_setprio 0
	s_barrier
	s_add_i32 s14, s53, s40
	s_mov_b32 m0, s14
	s_nop 1
	ds_read_b128 v[64:67], v157 offset:16384
	ds_read_b128 v[68:71], v157 offset:17408
	ds_read_b128 v[72:75], v157 offset:18432
	ds_read_b128 v[76:79], v157 offset:19456
	ds_read_b128 v[80:83], v157 offset:20480
	ds_read_b128 v[84:87], v157 offset:21504
	ds_read_b128 v[88:91], v157 offset:22528
	ds_read_b128 v[92:95], v157 offset:23552
	global_load_lds_dwordx4 v144, s[36:37]
	s_add_i32 m0, s14, 0x2000
	s_add_u32 s14, s36, 0x80000
	s_addc_u32 s15, s37, 0
	s_add_i32 s59, s54, s40
	global_load_lds_dwordx4 v148, s[36:37]
	s_mov_b32 m0, s59
	s_nop 0
	global_load_lds_dwordx4 v144, s[14:15]
	s_add_i32 m0, s59, 0x2000
	s_nop 0
	global_load_lds_dwordx4 v148, s[14:15]
	s_waitcnt vmcnt(4)
	s_waitcnt lgkmcnt(0)
	s_barrier
	s_setprio 1
	s_waitcnt lgkmcnt(0)
	v_mfma_scale_f32_16x16x128_f8f6f4 v[60:63], v[128:135], v[64:71], v[60:63], v158, v158 op_sel_hi:[0,0,0]
	v_mfma_scale_f32_16x16x128_f8f6f4 v[56:59], v[164:171], v[64:71], v[56:59], v158, v158 op_sel_hi:[0,0,0]
	v_mfma_scale_f32_16x16x128_f8f6f4 v[204:207], v[128:135], v[72:79], v[44:47], v158, v158 op_sel_hi:[0,0,0]
	v_mfma_scale_f32_16x16x128_f8f6f4 v[208:211], v[164:171], v[72:79], v[40:43], v158, v158 op_sel_hi:[0,0,0]
	v_mfma_scale_f32_16x16x128_f8f6f4 v[212:215], v[128:135], v[80:87], v[28:31], v158, v158 op_sel_hi:[0,0,0]
	v_mfma_scale_f32_16x16x128_f8f6f4 v[216:219], v[164:171], v[80:87], v[24:27], v158, v158 op_sel_hi:[0,0,0]
	v_mfma_scale_f32_16x16x128_f8f6f4 v[232:235], v[128:135], v[88:95], v[12:15], v158, v158 op_sel_hi:[0,0,0]
	v_mfma_scale_f32_16x16x128_f8f6f4 v[236:239], v[164:171], v[88:95], v[8:11], v158, v158 op_sel_hi:[0,0,0]
	s_setprio 0
	s_setprio 1
	v_mfma_scale_f32_16x16x128_f8f6f4 v[52:55], v[172:179], v[64:71], v[52:55], v158, v158 op_sel_hi:[0,0,0]
	v_mfma_scale_f32_16x16x128_f8f6f4 v[48:51], v[180:187], v[64:71], v[48:51], v158, v158 op_sel_hi:[0,0,0]
	v_mfma_scale_f32_16x16x128_f8f6f4 v[240:243], v[172:179], v[72:79], v[36:39], v158, v158 op_sel_hi:[0,0,0]
	v_mfma_scale_f32_16x16x128_f8f6f4 v[244:247], v[180:187], v[72:79], v[32:35], v158, v158 op_sel_hi:[0,0,0]
	v_mfma_scale_f32_16x16x128_f8f6f4 v[248:251], v[172:179], v[80:87], v[20:23], v158, v158 op_sel_hi:[0,0,0]
	v_mfma_scale_f32_16x16x128_f8f6f4 v[150:153], v[180:187], v[80:87], v[16:19], v158, v158 op_sel_hi:[0,0,0]
	v_mfma_scale_f32_16x16x128_f8f6f4 v[160:163], v[172:179], v[88:95], v[4:7], v158, v158 op_sel_hi:[0,0,0]
	v_mfma_scale_f32_16x16x128_f8f6f4 v[140:143], v[180:187], v[88:95], v[0:3], v158, v158 op_sel_hi:[0,0,0]
	s_setprio 0
	s_barrier
; #define PG8_WAIT_V(n) asm volatile("s_waitcnt vmcnt(" #n ")" ::: "memory")
; #define PG8_WAIT_L(n) asm volatile("s_waitcnt lgkmcnt(" #n ")" ::: "memory")
; #define PG8_BAR __builtin_amdgcn_s_barrier()
; #define PG8_SCHED __builtin_amdgcn_sched_barrier(0)
;     ...
;         for (int t = 0; t < nt; t += 2) {
;             const bool last = (t == nt - 2);
;             const char* a1 = cA + (size_t)(t + 1) * kstep;
;             const char* a2 = last ? nA : cA + (size_t)(t + 2) * kstep; const char* b2 = last ? nB : cB + (size_t)(t + 2) * kstep;
;             const char* a3 = a2 + kstep; const char* b3 = b2 + kstep;
;     ...
;             PG8_LDB(B0, 1, 0); PG8_LDB(B1, 1, 1); PG8_SCHED; PG8_LDA(At, 1, 0); PG8_STAGE(PG8_SA(0, 1), a2 + hstepA, voffA);
;             PG8_WAIT_V(8); PG8_WAIT_L(0); PG8_BAR; PG8_MMA(0, 0, At, B0); PG8_MMA(0, 1, At, B1); PG8_BAR; PG8_SCHED;
;             if constexpr (!HALFU) PG8_LDA(At, 1, 1); PG8_STAGE(PG8_SB(1, 0), b3, voffB); PG8_STAGE(PG8_SB(1, 1), b3 + hstep, voffB); PG8_STAGE(PG8_SA(1, 0), a3, voffA);
;             PG8_WAIT_V(8); PG8_WAIT_L(0); PG8_BAR; if constexpr (!HALFU) { PG8_MMA(1, 0, At, B0); PG8_MMA(1, 1, At, B1); } PG8_BAR; PG8_SCHED;
	s_mov_b32 m0, s29
	s_nop 0
	global_load_lds_dwordx4 v252, s[38:39]
	s_mov_b32 m0, s41
	s_nop 0
	global_load_lds_dwordx4 v146, s[38:39]
	s_add_i32 s59, 0, 0x18000
	v_add_u32_e32 v8, s59, v154
	s_add_i32 s60, 0, 0x1c000
	s_nop 1
	ds_read_b128 v[0:3], v8
	ds_read_b128 v[4:7], v8 offset:1024
	ds_read_b128 v[16:19], v8 offset:2048
	ds_read_b128 v[20:23], v8 offset:3072
	v_add_u32_e32 v8, s60, v154
	ds_read_b128 v[128:131], v8
	ds_read_b128 v[132:135], v8 offset:1024
	ds_read_b128 v[164:167], v8 offset:2048
	ds_read_b128 v[168:171], v8 offset:3072
	s_add_u32 s14, s38, 0x80000
	s_addc_u32 s15, s39, 0
	s_mov_b32 m0, s42
	ds_read_b128 v[8:11], v157 offset:32768
	ds_read_b128 v[12:15], v157 offset:33792
	ds_read_b128 v[24:27], v157 offset:34816
	ds_read_b128 v[28:31], v157 offset:35840
	ds_read_b128 v[32:35], v157 offset:36864
	ds_read_b128 v[36:39], v157 offset:37888
	ds_read_b128 v[40:43], v157 offset:38912
	ds_read_b128 v[44:47], v157 offset:39936
	global_load_lds_dwordx4 v252, s[14:15]
	s_mov_b32 m0, s43
	s_nop 0
	global_load_lds_dwordx4 v146, s[14:15]
	s_waitcnt vmcnt(8)
	s_waitcnt lgkmcnt(0)
	s_barrier
	s_setprio 1
	s_waitcnt lgkmcnt(0)
	v_mfma_scale_f32_16x16x128_f8f6f4 v[124:127], v[0:7], v[8:15], v[124:127], v158, v158 op_sel_hi:[0,0,0]
	v_mfma_scale_f32_16x16x128_f8f6f4 v[120:123], v[16:23], v[8:15], v[120:123], v158, v158 op_sel_hi:[0,0,0]
	v_mfma_scale_f32_16x16x128_f8f6f4 v[108:111], v[0:7], v[24:31], v[108:111], v158, v158 op_sel_hi:[0,0,0]
	v_mfma_scale_f32_16x16x128_f8f6f4 v[104:107], v[16:23], v[24:31], v[104:107], v158, v158 op_sel_hi:[0,0,0]
	v_mfma_scale_f32_16x16x128_f8f6f4 v[92:95], v[0:7], v[32:39], v[136:139], v158, v158 op_sel_hi:[0,0,0]
	v_mfma_scale_f32_16x16x128_f8f6f4 v[88:91], v[16:23], v[32:39], v[220:223], v158, v158 op_sel_hi:[0,0,0]
	v_mfma_scale_f32_16x16x128_f8f6f4 v[76:79], v[0:7], v[40:47], v[224:227], v158, v158 op_sel_hi:[0,0,0]
	v_mfma_scale_f32_16x16x128_f8f6f4 v[72:75], v[16:23], v[40:47], v[228:231], v158, v158 op_sel_hi:[0,0,0]
	s_setprio 0
	s_setprio 1
	v_mfma_scale_f32_16x16x128_f8f6f4 v[116:119], v[128:135], v[8:15], v[116:119], v158, v158 op_sel_hi:[0,0,0]
	v_mfma_scale_f32_16x16x128_f8f6f4 v[112:115], v[164:171], v[8:15], v[112:115], v158, v158 op_sel_hi:[0,0,0]
	v_mfma_scale_f32_16x16x128_f8f6f4 v[100:103], v[128:135], v[24:31], v[100:103], v158, v158 op_sel_hi:[0,0,0]
	v_mfma_scale_f32_16x16x128_f8f6f4 v[96:99], v[164:171], v[24:31], v[96:99], v158, v158 op_sel_hi:[0,0,0]
	v_mfma_scale_f32_16x16x128_f8f6f4 v[84:87], v[128:135], v[32:39], v[188:191], v158, v158 op_sel_hi:[0,0,0]
	v_mfma_scale_f32_16x16x128_f8f6f4 v[80:83], v[164:171], v[32:39], v[192:195], v158, v158 op_sel_hi:[0,0,0]
	v_mfma_scale_f32_16x16x128_f8f6f4 v[68:71], v[128:135], v[40:47], v[196:199], v158, v158 op_sel_hi:[0,0,0]
	v_mfma_scale_f32_16x16x128_f8f6f4 v[64:67], v[164:171], v[40:47], v[200:203], v158, v158 op_sel_hi:[0,0,0]
	s_setprio 0
	s_barrier
	s_add_u32 s14, s36, 0x80
	s_addc_u32 s15, s37, 0
	s_add_i32 s38, s59, s40
	s_mov_b32 m0, s38
	ds_read_b128 v[32:35], v157 offset:49152
	ds_read_b128 v[36:39], v157 offset:50176
	ds_read_b128 v[172:175], v157 offset:51200
	ds_read_b128 v[176:179], v157 offset:52224
	ds_read_b128 v[180:183], v157 offset:53248
	ds_read_b128 v[184:187], v157 offset:54272
	ds_read_b128 v[188:191], v157 offset:55296
	ds_read_b128 v[192:195], v157 offset:56320
	global_load_lds_dwordx4 v144, s[14:15]
	s_add_i32 m0, s38, 0x2000
	v_lshl_add_u64 v[8:9], s[14:15], 0, v[148:149]
	s_add_u32 s14, s36, 0x80080
	s_addc_u32 s15, s37, 0
	s_add_i32 s36, s60, s40
	global_load_lds_dwordx4 v[8:9], off
	s_mov_b32 m0, s36
	s_nop 0
	global_load_lds_dwordx4 v144, s[14:15]
	s_add_i32 m0, s36, 0x2000
	s_nop 0
	global_load_lds_dwordx4 v148, s[14:15]
	s_waitcnt vmcnt(4)
	s_waitcnt lgkmcnt(0)
	s_barrier
	s_setprio 1
	s_waitcnt lgkmcnt(0)
	v_mfma_scale_f32_16x16x128_f8f6f4 v[60:63], v[0:7], v[32:39], v[60:63], v158, v158 op_sel_hi:[0,0,0]
	v_mfma_scale_f32_16x16x128_f8f6f4 v[56:59], v[16:23], v[32:39], v[56:59], v158, v158 op_sel_hi:[0,0,0]
	v_mfma_scale_f32_16x16x128_f8f6f4 v[44:47], v[0:7], v[172:179], v[204:207], v158, v158 op_sel_hi:[0,0,0]
	v_mfma_scale_f32_16x16x128_f8f6f4 v[40:43], v[16:23], v[172:179], v[208:211], v158, v158 op_sel_hi:[0,0,0]
	v_mfma_scale_f32_16x16x128_f8f6f4 v[28:31], v[0:7], v[180:187], v[212:215], v158, v158 op_sel_hi:[0,0,0]
	v_mfma_scale_f32_16x16x128_f8f6f4 v[24:27], v[16:23], v[180:187], v[216:219], v158, v158 op_sel_hi:[0,0,0]
	v_mfma_scale_f32_16x16x128_f8f6f4 v[12:15], v[0:7], v[188:195], v[232:235], v158, v158 op_sel_hi:[0,0,0]
	v_mfma_scale_f32_16x16x128_f8f6f4 v[8:11], v[16:23], v[188:195], v[236:239], v158, v158 op_sel_hi:[0,0,0]
	s_setprio 0
	s_setprio 1
	v_mfma_scale_f32_16x16x128_f8f6f4 v[52:55], v[128:135], v[32:39], v[52:55], v158, v158 op_sel_hi:[0,0,0]
	v_mfma_scale_f32_16x16x128_f8f6f4 v[48:51], v[164:171], v[32:39], v[48:51], v158, v158 op_sel_hi:[0,0,0]
	v_mfma_scale_f32_16x16x128_f8f6f4 v[36:39], v[128:135], v[172:179], v[240:243], v158, v158 op_sel_hi:[0,0,0]
	v_mfma_scale_f32_16x16x128_f8f6f4 v[32:35], v[164:171], v[172:179], v[244:247], v158, v158 op_sel_hi:[0,0,0]
	v_mfma_scale_f32_16x16x128_f8f6f4 v[20:23], v[128:135], v[180:187], v[248:251], v158, v158 op_sel_hi:[0,0,0]
	v_mfma_scale_f32_16x16x128_f8f6f4 v[16:19], v[164:171], v[180:187], v[150:153], v158, v158 op_sel_hi:[0,0,0]
	v_mfma_scale_f32_16x16x128_f8f6f4 v[4:7], v[128:135], v[188:195], v[160:163], v158, v158 op_sel_hi:[0,0,0]
	v_mfma_scale_f32_16x16x128_f8f6f4 v[0:3], v[164:171], v[188:195], v[140:143], v158, v158 op_sel_hi:[0,0,0]
	s_setprio 0
	s_barrier
	s_add_i32 s58, s58, 2
	s_add_u32 s56, s56, 0x100
	s_addc_u32 s57, s57, 0
	s_cmp_gt_u32 s58, 29
	s_mov_b64 s[14:15], s[30:31]
	s_cbranch_scc0 .LBB0_317
	s_and_b64 vcc, exec, s[16:17]
	s_cbranch_vccz .LBB0_320
	s_barrier

; #define PG8_WAIT_V(n) asm volatile("s_waitcnt vmcnt(" #n ")" ::: "memory")
; #define PG8_WAIT_L(n) asm volatile("s_waitcnt lgkmcnt(" #n ")" ::: "memory")
; #define PG8_BAR __builtin_amdgcn_s_barrier()
; #define PG8_SCHED __builtin_amdgcn_sched_barrier(0)
;     ...
;             PG8_LDB(B0, 0, 0); PG8_LDB(B1, 0, 1); PG8_SCHED; PG8_LDA(At, 0, 0); PG8_STAGE(PG8_SA(1, 1), a1 + hstepA, voffA);
;             PG8_WAIT_V(8); PG8_WAIT_L(0); PG8_BAR; PG8_MMA(0, 0, At, B0); PG8_MMA(0, 1, At, B1); PG8_BAR; PG8_SCHED;
;             if constexpr (!HALFU) PG8_LDA(At, 0, 1); PG8_STAGE(PG8_SB(0, 0), b2, voffB); PG8_STAGE(PG8_SB(0, 1), b2 + hstep, voffB); PG8_STAGE(PG8_SA(0, 0), a2, voffA);
;             PG8_WAIT_V(8); PG8_WAIT_L(0); PG8_BAR; if constexpr (!HALFU) { PG8_MMA(1, 0, At, B0); PG8_MMA(1, 1, At, B1); } PG8_BAR; PG8_SCHED;
.LBB0_542:
	s_add_u32 s98, s28, 0x80
	s_addc_u32 s99, s29, 0
	s_mov_b32 m0, s53
	s_nop 0
	global_load_lds_dwordx4 v128, s[98:99]
	s_mov_b32 m0, s54
	s_nop 0
	global_load_lds_dwordx4 v130, s[98:99]
	ds_read_b128 v[142:145], v137
	ds_read_b128 v[146:149], v137 offset:1024
	ds_read_b128 v[150:153], v137 offset:2048
	ds_read_b128 v[154:157], v137 offset:3072
	ds_read_b128 v[158:161], v138
	ds_read_b128 v[162:165], v138 offset:1024
	ds_read_b128 v[166:169], v138 offset:2048
	ds_read_b128 v[170:173], v138 offset:3072
	s_add_u32 s30, s28, 0x100
	s_addc_u32 s31, s29, 0
	s_cmp_eq_u32 s61, 12
	s_cselect_b32 s40, s57, s30
	s_cselect_b32 s41, s23, s31
	s_cselect_b32 s38, s58, s59
	s_cselect_b32 s39, s21, s60
	s_add_u32 s36, s40, 0x80
	s_addc_u32 s37, s41, 0
	s_add_u32 s28, s28, 0x40080
	s_addc_u32 s29, s29, 0
	s_add_i32 m0, s45, 0xc000
	ds_read_b128 v[174:177], v139
	ds_read_b128 v[178:181], v139 offset:1024
	ds_read_b128 v[182:185], v139 offset:2048
	ds_read_b128 v[186:189], v139 offset:3072
	ds_read_b128 v[190:193], v139 offset:4096
	ds_read_b128 v[194:197], v139 offset:5120
	ds_read_b128 v[198:201], v139 offset:6144
	ds_read_b128 v[202:205], v139 offset:7168
	global_load_lds_dwordx4 v128, s[28:29]
	s_add_i32 m0, s45, 0xe000
	s_nop 0
	global_load_lds_dwordx4 v130, s[28:29]
	s_waitcnt vmcnt(8)
	s_waitcnt lgkmcnt(0)
	s_barrier
	s_setprio 1
	s_waitcnt lgkmcnt(0)
	v_mfma_scale_f32_16x16x128_f8f6f4 v[124:127], v[142:149], v[174:181], v[124:127], v140, v140 op_sel_hi:[0,0,0]
	v_mfma_scale_f32_16x16x128_f8f6f4 v[120:123], v[150:157], v[174:181], v[120:123], v140, v140 op_sel_hi:[0,0,0]
	v_mfma_scale_f32_16x16x128_f8f6f4 v[108:111], v[142:149], v[182:189], v[108:111], v140, v140 op_sel_hi:[0,0,0]
	v_mfma_scale_f32_16x16x128_f8f6f4 v[104:107], v[150:157], v[182:189], v[104:107], v140, v140 op_sel_hi:[0,0,0]
	v_mfma_scale_f32_16x16x128_f8f6f4 v[96:99], v[142:149], v[190:197], v[96:99], v140, v140 op_sel_hi:[0,0,0]
	v_mfma_scale_f32_16x16x128_f8f6f4 v[206:209], v[150:157], v[190:197], v[88:91], v140, v140 op_sel_hi:[0,0,0]
	v_mfma_scale_f32_16x16x128_f8f6f4 v[210:213], v[142:149], v[198:205], v[80:83], v140, v140 op_sel_hi:[0,0,0]
	v_mfma_scale_f32_16x16x128_f8f6f4 v[214:217], v[150:157], v[198:205], v[72:75], v140, v140 op_sel_hi:[0,0,0]
	s_setprio 0
	s_setprio 1
	v_mfma_scale_f32_16x16x128_f8f6f4 v[116:119], v[158:165], v[174:181], v[116:119], v140, v140 op_sel_hi:[0,0,0]
	v_mfma_scale_f32_16x16x128_f8f6f4 v[112:115], v[166:173], v[174:181], v[112:115], v140, v140 op_sel_hi:[0,0,0]
	v_mfma_scale_f32_16x16x128_f8f6f4 v[100:103], v[158:165], v[182:189], v[100:103], v140, v140 op_sel_hi:[0,0,0]
	v_mfma_scale_f32_16x16x128_f8f6f4 v[174:177], v[166:173], v[182:189], v[92:95], v140, v140 op_sel_hi:[0,0,0]
	v_mfma_scale_f32_16x16x128_f8f6f4 v[178:181], v[158:165], v[190:197], v[84:87], v140, v140 op_sel_hi:[0,0,0]
	v_mfma_scale_f32_16x16x128_f8f6f4 v[182:185], v[166:173], v[190:197], v[76:79], v140, v140 op_sel_hi:[0,0,0]
	v_mfma_scale_f32_16x16x128_f8f6f4 v[186:189], v[158:165], v[198:205], v[68:71], v140, v140 op_sel_hi:[0,0,0]
	v_mfma_scale_f32_16x16x128_f8f6f4 v[190:193], v[166:173], v[198:205], v[64:67], v140, v140 op_sel_hi:[0,0,0]
	s_setprio 0
	s_barrier
	s_add_i32 s28, s55, s43
	s_mov_b32 m0, s28
	s_nop 1
	ds_read_b128 v[64:67], v139 offset:16384
	ds_read_b128 v[68:71], v139 offset:17408
	ds_read_b128 v[72:75], v139 offset:18432
	ds_read_b128 v[76:79], v139 offset:19456
	ds_read_b128 v[80:83], v139 offset:20480
	ds_read_b128 v[84:87], v139 offset:21504
	ds_read_b128 v[88:91], v139 offset:22528
	ds_read_b128 v[92:95], v139 offset:23552
	global_load_lds_dwordx4 v128, s[38:39]
	s_add_i32 m0, s28, 0x2000
	s_add_u32 s28, s38, 0x40000
	s_addc_u32 s29, s39, 0
	s_add_i32 s62, s56, s43
	global_load_lds_dwordx4 v130, s[38:39]
	s_mov_b32 m0, s62
	s_nop 0
	global_load_lds_dwordx4 v128, s[28:29]
	s_add_i32 m0, s62, 0x2000
	s_nop 0
	global_load_lds_dwordx4 v130, s[28:29]
	s_waitcnt vmcnt(4)
	s_waitcnt lgkmcnt(0)
	s_barrier
	s_setprio 1
	s_waitcnt lgkmcnt(0)
	v_mfma_scale_f32_16x16x128_f8f6f4 v[60:63], v[142:149], v[64:71], v[60:63], v140, v140 op_sel_hi:[0,0,0]
	v_mfma_scale_f32_16x16x128_f8f6f4 v[56:59], v[150:157], v[64:71], v[56:59], v140, v140 op_sel_hi:[0,0,0]
	v_mfma_scale_f32_16x16x128_f8f6f4 v[48:51], v[142:149], v[72:79], v[48:51], v140, v140 op_sel_hi:[0,0,0]
	v_mfma_scale_f32_16x16x128_f8f6f4 v[194:197], v[150:157], v[72:79], v[40:43], v140, v140 op_sel_hi:[0,0,0]
	v_mfma_scale_f32_16x16x128_f8f6f4 v[198:201], v[142:149], v[80:87], v[32:35], v140, v140 op_sel_hi:[0,0,0]
	v_mfma_scale_f32_16x16x128_f8f6f4 v[202:205], v[150:157], v[80:87], v[24:27], v140, v140 op_sel_hi:[0,0,0]
	v_mfma_scale_f32_16x16x128_f8f6f4 v[218:221], v[142:149], v[88:95], v[16:19], v140, v140 op_sel_hi:[0,0,0]
	v_mfma_scale_f32_16x16x128_f8f6f4 v[222:225], v[150:157], v[88:95], v[8:11], v140, v140 op_sel_hi:[0,0,0]
	s_setprio 0
	s_setprio 1
	v_mfma_scale_f32_16x16x128_f8f6f4 v[52:55], v[158:165], v[64:71], v[52:55], v140, v140 op_sel_hi:[0,0,0]
	v_mfma_scale_f32_16x16x128_f8f6f4 v[226:229], v[166:173], v[64:71], v[44:47], v140, v140 op_sel_hi:[0,0,0]
	v_mfma_scale_f32_16x16x128_f8f6f4 v[230:233], v[158:165], v[72:79], v[36:39], v140, v140 op_sel_hi:[0,0,0]
	v_mfma_scale_f32_16x16x128_f8f6f4 v[234:237], v[166:173], v[72:79], v[28:31], v140, v140 op_sel_hi:[0,0,0]
	v_mfma_scale_f32_16x16x128_f8f6f4 v[238:241], v[158:165], v[80:87], v[20:23], v140, v140 op_sel_hi:[0,0,0]
	v_mfma_scale_f32_16x16x128_f8f6f4 v[242:245], v[166:173], v[80:87], v[12:15], v140, v140 op_sel_hi:[0,0,0]
	v_mfma_scale_f32_16x16x128_f8f6f4 v[246:249], v[158:165], v[88:95], v[4:7], v140, v140 op_sel_hi:[0,0,0]
	v_mfma_scale_f32_16x16x128_f8f6f4 v[250:253], v[166:173], v[88:95], v[0:3], v140, v140 op_sel_hi:[0,0,0]
	s_setprio 0
	s_barrier
; #define PG8_WAIT_V(n) asm volatile("s_waitcnt vmcnt(" #n ")" ::: "memory")
; #define PG8_WAIT_L(n) asm volatile("s_waitcnt lgkmcnt(" #n ")" ::: "memory")
; #define PG8_BAR __builtin_amdgcn_s_barrier()
; #define PG8_SCHED __builtin_amdgcn_sched_barrier(0)
;     ...
;             PG8_LDB(B0, 1, 0); PG8_LDB(B1, 1, 1); PG8_SCHED; PG8_LDA(At, 1, 0); PG8_STAGE(PG8_SA(0, 1), a2 + hstepA, voffA);
;             PG8_WAIT_V(8); PG8_WAIT_L(0); PG8_BAR; PG8_MMA(0, 0, At, B0); PG8_MMA(0, 1, At, B1); PG8_BAR; PG8_SCHED;
;             if constexpr (!HALFU) PG8_LDA(At, 1, 1); PG8_STAGE(PG8_SB(1, 0), b3, voffB); PG8_STAGE(PG8_SB(1, 1), b3 + hstep, voffB); PG8_STAGE(PG8_SA(1, 0), a3, voffA);
;             PG8_WAIT_V(8); PG8_WAIT_L(0); PG8_BAR; if constexpr (!HALFU) { PG8_MMA(1, 0, At, B0); PG8_MMA(1, 1, At, B1); } PG8_BAR; PG8_SCHED;
	s_mov_b32 m0, s45
	s_nop 0
	global_load_lds_dwordx4 v128, s[40:41]
	s_mov_b32 m0, s46
	s_nop 0
	global_load_lds_dwordx4 v130, s[40:41]
	s_add_i32 s62, 0, 0x18000
	s_add_i32 s63, 0, 0x1c000
	s_nop 0
	v_add_u32_e32 v12, s62, v136
	v_add_u32_e32 v16, s63, v136
	ds_read_b128 v[0:3], v12
	ds_read_b128 v[4:7], v12 offset:1024
	ds_read_b128 v[8:11], v12 offset:2048
	ds_read_b128 v[12:15], v12 offset:3072
	ds_read_b128 v[142:145], v16
	ds_read_b128 v[146:149], v16 offset:1024
	ds_read_b128 v[150:153], v16 offset:2048
	ds_read_b128 v[154:157], v16 offset:3072
	s_add_u32 s28, s40, 0x40000
	s_addc_u32 s29, s41, 0
	s_mov_b32 m0, s47
	ds_read_b128 v[16:19], v139 offset:32768
	ds_read_b128 v[20:23], v139 offset:33792
	ds_read_b128 v[24:27], v139 offset:34816
	ds_read_b128 v[28:31], v139 offset:35840
	ds_read_b128 v[32:35], v139 offset:36864
	ds_read_b128 v[36:39], v139 offset:37888
	ds_read_b128 v[40:43], v139 offset:38912
	ds_read_b128 v[44:47], v139 offset:39936
	global_load_lds_dwordx4 v128, s[28:29]
	s_mov_b32 m0, s48
	s_nop 0
	global_load_lds_dwordx4 v130, s[28:29]
	s_waitcnt vmcnt(8)
	s_waitcnt lgkmcnt(0)
	s_barrier
	s_setprio 1
	s_waitcnt lgkmcnt(0)
	v_mfma_scale_f32_16x16x128_f8f6f4 v[124:127], v[0:7], v[16:23], v[124:127], v140, v140 op_sel_hi:[0,0,0]
	v_mfma_scale_f32_16x16x128_f8f6f4 v[120:123], v[8:15], v[16:23], v[120:123], v140, v140 op_sel_hi:[0,0,0]
	v_mfma_scale_f32_16x16x128_f8f6f4 v[108:111], v[0:7], v[24:31], v[108:111], v140, v140 op_sel_hi:[0,0,0]
	v_mfma_scale_f32_16x16x128_f8f6f4 v[104:107], v[8:15], v[24:31], v[104:107], v140, v140 op_sel_hi:[0,0,0]
	v_mfma_scale_f32_16x16x128_f8f6f4 v[96:99], v[0:7], v[32:39], v[96:99], v140, v140 op_sel_hi:[0,0,0]
	v_mfma_scale_f32_16x16x128_f8f6f4 v[88:91], v[8:15], v[32:39], v[206:209], v140, v140 op_sel_hi:[0,0,0]
	v_mfma_scale_f32_16x16x128_f8f6f4 v[80:83], v[0:7], v[40:47], v[210:213], v140, v140 op_sel_hi:[0,0,0]
	v_mfma_scale_f32_16x16x128_f8f6f4 v[72:75], v[8:15], v[40:47], v[214:217], v140, v140 op_sel_hi:[0,0,0]
	s_setprio 0
	s_setprio 1
	v_mfma_scale_f32_16x16x128_f8f6f4 v[116:119], v[142:149], v[16:23], v[116:119], v140, v140 op_sel_hi:[0,0,0]
	v_mfma_scale_f32_16x16x128_f8f6f4 v[112:115], v[150:157], v[16:23], v[112:115], v140, v140 op_sel_hi:[0,0,0]
	v_mfma_scale_f32_16x16x128_f8f6f4 v[100:103], v[142:149], v[24:31], v[100:103], v140, v140 op_sel_hi:[0,0,0]
	v_mfma_scale_f32_16x16x128_f8f6f4 v[92:95], v[150:157], v[24:31], v[174:177], v140, v140 op_sel_hi:[0,0,0]
	v_mfma_scale_f32_16x16x128_f8f6f4 v[84:87], v[142:149], v[32:39], v[178:181], v140, v140 op_sel_hi:[0,0,0]
	v_mfma_scale_f32_16x16x128_f8f6f4 v[76:79], v[150:157], v[32:39], v[182:185], v140, v140 op_sel_hi:[0,0,0]
	v_mfma_scale_f32_16x16x128_f8f6f4 v[68:71], v[142:149], v[40:47], v[186:189], v140, v140 op_sel_hi:[0,0,0]
	v_mfma_scale_f32_16x16x128_f8f6f4 v[64:67], v[150:157], v[40:47], v[190:193], v140, v140 op_sel_hi:[0,0,0]
	s_setprio 0
	s_barrier
	s_add_u32 s28, s38, 0x80
	s_addc_u32 s29, s39, 0
	s_add_i32 s40, s62, s43
	s_mov_b32 m0, s40
	ds_read_b128 v[158:161], v139 offset:49152
	ds_read_b128 v[162:165], v139 offset:50176
	ds_read_b128 v[166:169], v139 offset:51200
	ds_read_b128 v[170:173], v139 offset:52224
	ds_read_b128 v[174:177], v139 offset:53248
	ds_read_b128 v[178:181], v139 offset:54272
	ds_read_b128 v[182:185], v139 offset:55296
	ds_read_b128 v[186:189], v139 offset:56320
	global_load_lds_dwordx4 v128, s[28:29]
	s_add_i32 m0, s40, 0x2000
	v_lshl_add_u64 v[16:17], s[28:29], 0, v[130:131]
	s_add_u32 s28, s38, 0x40080
	s_addc_u32 s29, s39, 0
	s_add_i32 s38, s63, s43
	global_load_lds_dwordx4 v[16:17], off
	s_mov_b32 m0, s38
	s_nop 0
	global_load_lds_dwordx4 v128, s[28:29]
	s_add_i32 m0, s38, 0x2000
	s_nop 0
	global_load_lds_dwordx4 v130, s[28:29]
	s_waitcnt vmcnt(4)
	s_waitcnt lgkmcnt(0)
	s_barrier
	s_setprio 1
	s_waitcnt lgkmcnt(0)
	v_mfma_scale_f32_16x16x128_f8f6f4 v[60:63], v[0:7], v[158:165], v[60:63], v140, v140 op_sel_hi:[0,0,0]
	v_mfma_scale_f32_16x16x128_f8f6f4 v[56:59], v[8:15], v[158:165], v[56:59], v140, v140 op_sel_hi:[0,0,0]
	v_mfma_scale_f32_16x16x128_f8f6f4 v[48:51], v[0:7], v[166:173], v[48:51], v140, v140 op_sel_hi:[0,0,0]
	v_mfma_scale_f32_16x16x128_f8f6f4 v[40:43], v[8:15], v[166:173], v[194:197], v140, v140 op_sel_hi:[0,0,0]
	v_mfma_scale_f32_16x16x128_f8f6f4 v[32:35], v[0:7], v[174:181], v[198:201], v140, v140 op_sel_hi:[0,0,0]
	v_mfma_scale_f32_16x16x128_f8f6f4 v[24:27], v[8:15], v[174:181], v[202:205], v140, v140 op_sel_hi:[0,0,0]
	v_mfma_scale_f32_16x16x128_f8f6f4 v[16:19], v[0:7], v[182:189], v[218:221], v140, v140 op_sel_hi:[0,0,0]
	v_mfma_scale_f32_16x16x128_f8f6f4 v[8:11], v[8:15], v[182:189], v[222:225], v140, v140 op_sel_hi:[0,0,0]
	s_setprio 0
	s_setprio 1
	v_mfma_scale_f32_16x16x128_f8f6f4 v[52:55], v[142:149], v[158:165], v[52:55], v140, v140 op_sel_hi:[0,0,0]
	v_mfma_scale_f32_16x16x128_f8f6f4 v[44:47], v[150:157], v[158:165], v[226:229], v140, v140 op_sel_hi:[0,0,0]
	v_mfma_scale_f32_16x16x128_f8f6f4 v[36:39], v[142:149], v[166:173], v[230:233], v140, v140 op_sel_hi:[0,0,0]
	v_mfma_scale_f32_16x16x128_f8f6f4 v[28:31], v[150:157], v[166:173], v[234:237], v140, v140 op_sel_hi:[0,0,0]
	v_mfma_scale_f32_16x16x128_f8f6f4 v[20:23], v[142:149], v[174:181], v[238:241], v140, v140 op_sel_hi:[0,0,0]
	v_mfma_scale_f32_16x16x128_f8f6f4 v[12:15], v[150:157], v[174:181], v[242:245], v140, v140 op_sel_hi:[0,0,0]
	v_mfma_scale_f32_16x16x128_f8f6f4 v[4:7], v[142:149], v[182:189], v[246:249], v140, v140 op_sel_hi:[0,0,0]
	v_mfma_scale_f32_16x16x128_f8f6f4 v[0:3], v[150:157], v[182:189], v[250:253], v140, v140 op_sel_hi:[0,0,0]
	s_setprio 0
	s_barrier
	s_add_i32 s61, s61, 2
	s_add_u32 s59, s59, 0x100
	s_addc_u32 s60, s60, 0
	s_cmp_gt_u32 s61, 13
	s_mov_b64 s[28:29], s[30:31]
	s_cbranch_scc0 .LBB0_542
	s_and_b64 vcc, exec, s[6:7]
	s_cbranch_vccz .LBB0_545
	s_barrier

; #define PG8_WAIT_V(n) asm volatile("s_waitcnt vmcnt(" #n ")" ::: "memory")
; #define PG8_WAIT_L(n) asm volatile("s_waitcnt lgkmcnt(" #n ")" ::: "memory")
; #define PG8_BAR __builtin_amdgcn_s_barrier()
; #define PG8_SCHED __builtin_amdgcn_sched_barrier(0)
;     ...
;         const bool has_next = S.next(ui + 1, nxt);
;         const char* nA = has_next ? (const char*)g.A + (size_t)nxt.pm * tstepA : cA; const char* nB = has_next ? (const char*)g.Bt + (size_t)nxt.pn * tstep : cB;
;         for (int t = 0; t < nt; t += 2) {
;             const bool last = (t == nt - 2);
;             const char* a1 = cA + (size_t)(t + 1) * kstep;
;             const char* a2 = last ? nA : cA + (size_t)(t + 2) * kstep; const char* b2 = last ? nB : cB + (size_t)(t + 2) * kstep;
;             const char* a3 = a2 + kstep; const char* b3 = b2 + kstep;
;             if (last && has_next) S.a_ready(nxt);
;             if constexpr (SP2) {
;             PG8_LDB(B0, 0, 0); PG8_LDB(B1, 0, 1); PG8_SCHED; PG8_LDA(At, 0, 0); PG8_STAGE(PG8_SA(1, 1), a1 + hstepA, voffA);
;             PG8_WAIT_V(8); PG8_WAIT_L(0); PG8_BAR; PG8_MMA(0, 0, At, B0); PG8_MMA(0, 1, At, B1); PG8_BAR; PG8_SCHED;
;             if constexpr (!HALFU) PG8_LDA(At, 0, 1); PG8_STAGE(PG8_SB(0, 0), b2, voffB); PG8_STAGE(PG8_SB(0, 1), b2 + hstep, voffB); PG8_STAGE(PG8_SA(0, 0), a2, voffA);
;             PG8_WAIT_V(8); PG8_WAIT_L(0); PG8_BAR; if constexpr (!HALFU) { PG8_MMA(1, 0, At, B0); PG8_MMA(1, 1, At, B1); } PG8_BAR; PG8_SCHED;
.LBB0_670:
	s_add_u32 s98, s18, 0x80
	s_addc_u32 s99, s19, 0
	s_mov_b32 m0, s43
	s_nop 0
	global_load_lds_dwordx4 v134, s[98:99]
	s_mov_b32 m0, s44
	s_nop 0
	global_load_lds_dwordx4 v132, s[98:99]
	ds_read_b128 v[144:147], v141
	ds_read_b128 v[148:151], v141 offset:1024
	ds_read_b128 v[152:155], v141 offset:2048
	ds_read_b128 v[156:159], v141 offset:3072
	ds_read_b128 v[160:163], v142
	ds_read_b128 v[164:167], v142 offset:1024
	ds_read_b128 v[168:171], v142 offset:2048
	ds_read_b128 v[172:175], v142 offset:3072
	s_add_u32 s20, s18, 0x100
	s_addc_u32 s21, s19, 0
	s_cmp_eq_u32 s53, 60
	s_cselect_b32 s26, s49, s20
	s_cselect_b32 s27, s11, s21
	s_cselect_b32 s24, s50, s51
	s_cselect_b32 s25, s9, s52
	s_add_u32 s22, s26, 0x80
	s_addc_u32 s23, s27, 0
	s_add_u32 s18, s18, 0x100080
	s_addc_u32 s19, s19, 0
	s_add_i32 m0, s17, 0xc000
	ds_read_b128 v[176:179], v143
	ds_read_b128 v[180:183], v143 offset:1024
	ds_read_b128 v[184:187], v143 offset:2048
	ds_read_b128 v[188:191], v143 offset:3072
	ds_read_b128 v[192:195], v143 offset:4096
	ds_read_b128 v[196:199], v143 offset:5120
	ds_read_b128 v[200:203], v143 offset:6144
	ds_read_b128 v[204:207], v143 offset:7168
	global_load_lds_dwordx4 v134, s[18:19]
	s_add_i32 m0, s17, 0xe000
	s_nop 0
	global_load_lds_dwordx4 v132, s[18:19]
	s_waitcnt vmcnt(8)
	s_waitcnt lgkmcnt(0)
	s_barrier
	s_setprio 1
	s_waitcnt lgkmcnt(0)
	v_mfma_f32_16x16x32_bf16 v[124:127], v[144:147], v[176:179], v[124:127]
	v_mfma_f32_16x16x32_bf16 v[120:123], v[152:155], v[176:179], v[120:123]
	v_mfma_f32_16x16x32_bf16 v[108:111], v[144:147], v[184:187], v[108:111]
	v_mfma_f32_16x16x32_bf16 v[104:107], v[152:155], v[184:187], v[104:107]
	v_mfma_f32_16x16x32_bf16 v[92:95], v[144:147], v[192:195], v[92:95]
	v_mfma_f32_16x16x32_bf16 v[88:91], v[152:155], v[192:195], v[88:91]
	v_mfma_f32_16x16x32_bf16 v[76:79], v[144:147], v[200:203], v[76:79]
	v_mfma_f32_16x16x32_bf16 v[72:75], v[152:155], v[200:203], v[72:75]
	v_mfma_f32_16x16x32_bf16 v[124:127], v[148:151], v[180:183], v[124:127]
	v_mfma_f32_16x16x32_bf16 v[120:123], v[156:159], v[180:183], v[120:123]
	v_mfma_f32_16x16x32_bf16 v[108:111], v[148:151], v[188:191], v[108:111]
	v_mfma_f32_16x16x32_bf16 v[104:107], v[156:159], v[188:191], v[104:107]
	v_mfma_f32_16x16x32_bf16 v[92:95], v[148:151], v[196:199], v[92:95]
	v_mfma_f32_16x16x32_bf16 v[88:91], v[156:159], v[196:199], v[88:91]
	v_mfma_f32_16x16x32_bf16 v[76:79], v[148:151], v[204:207], v[76:79]
	v_mfma_f32_16x16x32_bf16 v[72:75], v[156:159], v[204:207], v[72:75]
	s_setprio 0
	s_setprio 1
	v_mfma_f32_16x16x32_bf16 v[116:119], v[160:163], v[176:179], v[116:119]
	v_mfma_f32_16x16x32_bf16 v[112:115], v[168:171], v[176:179], v[112:115]
	v_mfma_f32_16x16x32_bf16 v[100:103], v[160:163], v[184:187], v[100:103]
	v_mfma_f32_16x16x32_bf16 v[96:99], v[168:171], v[184:187], v[96:99]
	v_mfma_f32_16x16x32_bf16 v[84:87], v[160:163], v[192:195], v[84:87]
	v_mfma_f32_16x16x32_bf16 v[80:83], v[168:171], v[192:195], v[80:83]
	v_mfma_f32_16x16x32_bf16 v[68:71], v[160:163], v[200:203], v[68:71]
	v_mfma_f32_16x16x32_bf16 v[64:67], v[168:171], v[200:203], v[64:67]
	v_mfma_f32_16x16x32_bf16 v[116:119], v[164:167], v[180:183], v[116:119]
	v_mfma_f32_16x16x32_bf16 v[112:115], v[172:175], v[180:183], v[112:115]
	v_mfma_f32_16x16x32_bf16 v[100:103], v[164:167], v[188:191], v[100:103]
	v_mfma_f32_16x16x32_bf16 v[96:99], v[172:175], v[188:191], v[96:99]
	v_mfma_f32_16x16x32_bf16 v[84:87], v[164:167], v[196:199], v[84:87]
	v_mfma_f32_16x16x32_bf16 v[80:83], v[172:175], v[196:199], v[80:83]
	v_mfma_f32_16x16x32_bf16 v[68:71], v[164:167], v[204:207], v[68:71]
	v_mfma_f32_16x16x32_bf16 v[64:67], v[172:175], v[204:207], v[64:67]
	s_setprio 0
	s_barrier
	s_add_i32 s18, s45, s30
	s_mov_b32 m0, s18
	ds_read_b128 v[176:179], v143 offset:16384
	ds_read_b128 v[180:183], v143 offset:17408
	ds_read_b128 v[184:187], v143 offset:18432
	ds_read_b128 v[188:191], v143 offset:19456
	ds_read_b128 v[192:195], v143 offset:20480
	ds_read_b128 v[196:199], v143 offset:21504
	ds_read_b128 v[200:203], v143 offset:22528
	ds_read_b128 v[204:207], v143 offset:23552
	global_load_lds_dwordx4 v128, s[24:25]
	s_add_i32 m0, s18, 0x2000
	s_add_u32 s18, s24, 0x100000
	s_addc_u32 s19, s25, 0
	s_add_i32 s54, s46, s30
	global_load_lds_dwordx4 v130, s[24:25]
	s_mov_b32 m0, s54
	s_nop 0
	global_load_lds_dwordx4 v128, s[18:19]
	s_add_i32 m0, s54, 0x2000
	s_nop 0
	global_load_lds_dwordx4 v130, s[18:19]
	s_waitcnt vmcnt(4)
	s_waitcnt lgkmcnt(0)
	s_barrier
	s_setprio 1
	s_waitcnt lgkmcnt(0)
	v_mfma_f32_16x16x32_bf16 v[60:63], v[144:147], v[176:179], v[60:63]
	v_mfma_f32_16x16x32_bf16 v[56:59], v[152:155], v[176:179], v[56:59]
	v_mfma_f32_16x16x32_bf16 v[44:47], v[144:147], v[184:187], v[44:47]
	v_mfma_f32_16x16x32_bf16 v[40:43], v[152:155], v[184:187], v[40:43]
	v_mfma_f32_16x16x32_bf16 v[28:31], v[144:147], v[192:195], v[28:31]
	v_mfma_f32_16x16x32_bf16 v[24:27], v[152:155], v[192:195], v[24:27]
	v_mfma_f32_16x16x32_bf16 v[12:15], v[144:147], v[200:203], v[12:15]
	v_mfma_f32_16x16x32_bf16 v[8:11], v[152:155], v[200:203], v[8:11]
	v_mfma_f32_16x16x32_bf16 v[60:63], v[148:151], v[180:183], v[60:63]
	v_mfma_f32_16x16x32_bf16 v[56:59], v[156:159], v[180:183], v[56:59]
	v_mfma_f32_16x16x32_bf16 v[44:47], v[148:151], v[188:191], v[44:47]
	v_mfma_f32_16x16x32_bf16 v[40:43], v[156:159], v[188:191], v[40:43]
	v_mfma_f32_16x16x32_bf16 v[28:31], v[148:151], v[196:199], v[28:31]
	v_mfma_f32_16x16x32_bf16 v[24:27], v[156:159], v[196:199], v[24:27]
	v_mfma_f32_16x16x32_bf16 v[12:15], v[148:151], v[204:207], v[12:15]
	v_mfma_f32_16x16x32_bf16 v[8:11], v[156:159], v[204:207], v[8:11]
	s_setprio 0
	s_setprio 1
	v_mfma_f32_16x16x32_bf16 v[52:55], v[160:163], v[176:179], v[52:55]
	v_mfma_f32_16x16x32_bf16 v[48:51], v[168:171], v[176:179], v[48:51]
	v_mfma_f32_16x16x32_bf16 v[36:39], v[160:163], v[184:187], v[36:39]
	v_mfma_f32_16x16x32_bf16 v[32:35], v[168:171], v[184:187], v[32:35]
	v_mfma_f32_16x16x32_bf16 v[20:23], v[160:163], v[192:195], v[20:23]
	v_mfma_f32_16x16x32_bf16 v[16:19], v[168:171], v[192:195], v[16:19]
	v_mfma_f32_16x16x32_bf16 v[4:7], v[160:163], v[200:203], v[4:7]
	v_mfma_f32_16x16x32_bf16 v[0:3], v[168:171], v[200:203], v[0:3]
	v_mfma_f32_16x16x32_bf16 v[52:55], v[164:167], v[180:183], v[52:55]
	v_mfma_f32_16x16x32_bf16 v[48:51], v[172:175], v[180:183], v[48:51]
	v_mfma_f32_16x16x32_bf16 v[36:39], v[164:167], v[188:191], v[36:39]
	v_mfma_f32_16x16x32_bf16 v[32:35], v[172:175], v[188:191], v[32:35]
	v_mfma_f32_16x16x32_bf16 v[20:23], v[164:167], v[196:199], v[20:23]
	v_mfma_f32_16x16x32_bf16 v[16:19], v[172:175], v[196:199], v[16:19]
	v_mfma_f32_16x16x32_bf16 v[4:7], v[164:167], v[204:207], v[4:7]
	v_mfma_f32_16x16x32_bf16 v[0:3], v[172:175], v[204:207], v[0:3]
	s_setprio 0
	s_barrier
; #define PG8_WAIT_V(n) asm volatile("s_waitcnt vmcnt(" #n ")" ::: "memory")
; #define PG8_WAIT_L(n) asm volatile("s_waitcnt lgkmcnt(" #n ")" ::: "memory")
; #define PG8_BAR __builtin_amdgcn_s_barrier()
; #define PG8_SCHED __builtin_amdgcn_sched_barrier(0)
;     ...
;             PG8_LDB(B0, 1, 0); PG8_LDB(B1, 1, 1); PG8_SCHED; PG8_LDA(At, 1, 0); PG8_STAGE(PG8_SA(0, 1), a2 + hstepA, voffA);
;             PG8_WAIT_V(8); PG8_WAIT_L(0); PG8_BAR; PG8_MMA(0, 0, At, B0); PG8_MMA(0, 1, At, B1); PG8_BAR; PG8_SCHED;
;             if constexpr (!HALFU) PG8_LDA(At, 1, 1); PG8_STAGE(PG8_SB(1, 0), b3, voffB); PG8_STAGE(PG8_SB(1, 1), b3 + hstep, voffB); PG8_STAGE(PG8_SA(1, 0), a3, voffA);
;             PG8_WAIT_V(8); PG8_WAIT_L(0); PG8_BAR; if constexpr (!HALFU) { PG8_MMA(1, 0, At, B0); PG8_MMA(1, 1, At, B1); } PG8_BAR; PG8_SCHED;
	s_mov_b32 m0, s17
	s_nop 0
	global_load_lds_dwordx4 v134, s[26:27]
	s_mov_b32 m0, s36
	s_nop 0
	global_load_lds_dwordx4 v132, s[26:27]
	s_add_i32 s54, 0, 0x18000
	s_add_i32 s55, 0, 0x1c000
	v_add_u32_e32 v156, s54, v140
	v_add_u32_e32 v172, s55, v140
	ds_read_b128 v[144:147], v156
	ds_read_b128 v[148:151], v156 offset:1024
	ds_read_b128 v[152:155], v156 offset:2048
	ds_read_b128 v[156:159], v156 offset:3072
	ds_read_b128 v[160:163], v172
	ds_read_b128 v[164:167], v172 offset:1024
	ds_read_b128 v[168:171], v172 offset:2048
	ds_read_b128 v[172:175], v172 offset:3072
	s_add_u32 s18, s26, 0x100000
	s_addc_u32 s19, s27, 0
	s_mov_b32 m0, s37
	ds_read_b128 v[176:179], v143 offset:32768
	ds_read_b128 v[180:183], v143 offset:33792
	ds_read_b128 v[184:187], v143 offset:34816
	ds_read_b128 v[188:191], v143 offset:35840
	ds_read_b128 v[192:195], v143 offset:36864
	ds_read_b128 v[196:199], v143 offset:37888
	ds_read_b128 v[200:203], v143 offset:38912
	ds_read_b128 v[204:207], v143 offset:39936
	global_load_lds_dwordx4 v134, s[18:19]
	s_mov_b32 m0, s38
	s_nop 0
	global_load_lds_dwordx4 v132, s[18:19]
	s_waitcnt vmcnt(8)
	s_waitcnt lgkmcnt(0)
	s_barrier
	s_setprio 1
	s_waitcnt lgkmcnt(0)
	v_mfma_f32_16x16x32_bf16 v[124:127], v[144:147], v[176:179], v[124:127]
	v_mfma_f32_16x16x32_bf16 v[120:123], v[152:155], v[176:179], v[120:123]
	v_mfma_f32_16x16x32_bf16 v[108:111], v[144:147], v[184:187], v[108:111]
	v_mfma_f32_16x16x32_bf16 v[104:107], v[152:155], v[184:187], v[104:107]
	v_mfma_f32_16x16x32_bf16 v[92:95], v[144:147], v[192:195], v[92:95]
	v_mfma_f32_16x16x32_bf16 v[88:91], v[152:155], v[192:195], v[88:91]
	v_mfma_f32_16x16x32_bf16 v[76:79], v[144:147], v[200:203], v[76:79]
	v_mfma_f32_16x16x32_bf16 v[72:75], v[152:155], v[200:203], v[72:75]
	v_mfma_f32_16x16x32_bf16 v[124:127], v[148:151], v[180:183], v[124:127]
	v_mfma_f32_16x16x32_bf16 v[120:123], v[156:159], v[180:183], v[120:123]
	v_mfma_f32_16x16x32_bf16 v[108:111], v[148:151], v[188:191], v[108:111]
	v_mfma_f32_16x16x32_bf16 v[104:107], v[156:159], v[188:191], v[104:107]
	v_mfma_f32_16x16x32_bf16 v[92:95], v[148:151], v[196:199], v[92:95]
	v_mfma_f32_16x16x32_bf16 v[88:91], v[156:159], v[196:199], v[88:91]
	v_mfma_f32_16x16x32_bf16 v[76:79], v[148:151], v[204:207], v[76:79]
	v_mfma_f32_16x16x32_bf16 v[72:75], v[156:159], v[204:207], v[72:75]
	s_setprio 0
	s_setprio 1
	v_mfma_f32_16x16x32_bf16 v[116:119], v[160:163], v[176:179], v[116:119]
	v_mfma_f32_16x16x32_bf16 v[112:115], v[168:171], v[176:179], v[112:115]
	v_mfma_f32_16x16x32_bf16 v[100:103], v[160:163], v[184:187], v[100:103]
	v_mfma_f32_16x16x32_bf16 v[96:99], v[168:171], v[184:187], v[96:99]
	v_mfma_f32_16x16x32_bf16 v[84:87], v[160:163], v[192:195], v[84:87]
	v_mfma_f32_16x16x32_bf16 v[80:83], v[168:171], v[192:195], v[80:83]
	v_mfma_f32_16x16x32_bf16 v[68:71], v[160:163], v[200:203], v[68:71]
	v_mfma_f32_16x16x32_bf16 v[64:67], v[168:171], v[200:203], v[64:67]
	v_mfma_f32_16x16x32_bf16 v[116:119], v[164:167], v[180:183], v[116:119]
	v_mfma_f32_16x16x32_bf16 v[112:115], v[172:175], v[180:183], v[112:115]
	v_mfma_f32_16x16x32_bf16 v[100:103], v[164:167], v[188:191], v[100:103]
	v_mfma_f32_16x16x32_bf16 v[96:99], v[172:175], v[188:191], v[96:99]
	v_mfma_f32_16x16x32_bf16 v[84:87], v[164:167], v[196:199], v[84:87]
	v_mfma_f32_16x16x32_bf16 v[80:83], v[172:175], v[196:199], v[80:83]
	v_mfma_f32_16x16x32_bf16 v[68:71], v[164:167], v[204:207], v[68:71]
	v_mfma_f32_16x16x32_bf16 v[64:67], v[172:175], v[204:207], v[64:67]
	s_setprio 0
	s_barrier
	s_add_u32 s18, s24, 0x80
	s_addc_u32 s19, s25, 0
	s_add_i32 s26, s54, s30
	s_mov_b32 m0, s26
	ds_read_b128 v[176:179], v143 offset:49152
	ds_read_b128 v[180:183], v143 offset:50176
	ds_read_b128 v[184:187], v143 offset:51200
	ds_read_b128 v[188:191], v143 offset:52224
	ds_read_b128 v[192:195], v143 offset:53248
	ds_read_b128 v[196:199], v143 offset:54272
	ds_read_b128 v[200:203], v143 offset:55296
	ds_read_b128 v[204:207], v143 offset:56320
	global_load_lds_dwordx4 v128, s[18:19]
	s_add_i32 m0, s26, 0x2000
	v_lshl_add_u64 v[208:209], s[18:19], 0, v[130:131]
	s_add_u32 s18, s24, 0x100080
	s_addc_u32 s19, s25, 0
	s_add_i32 s24, s55, s30
	global_load_lds_dwordx4 v[208:209], off
	s_mov_b32 m0, s24
	s_nop 0
	global_load_lds_dwordx4 v128, s[18:19]
	s_add_i32 m0, s24, 0x2000
	s_nop 0
	global_load_lds_dwordx4 v130, s[18:19]
	s_waitcnt vmcnt(4)
	s_waitcnt lgkmcnt(0)
	s_barrier
	s_setprio 1
	s_waitcnt lgkmcnt(0)
	v_mfma_f32_16x16x32_bf16 v[60:63], v[144:147], v[176:179], v[60:63]
	v_mfma_f32_16x16x32_bf16 v[56:59], v[152:155], v[176:179], v[56:59]
	v_mfma_f32_16x16x32_bf16 v[44:47], v[144:147], v[184:187], v[44:47]
	v_mfma_f32_16x16x32_bf16 v[40:43], v[152:155], v[184:187], v[40:43]
	v_mfma_f32_16x16x32_bf16 v[28:31], v[144:147], v[192:195], v[28:31]
	v_mfma_f32_16x16x32_bf16 v[24:27], v[152:155], v[192:195], v[24:27]
	v_mfma_f32_16x16x32_bf16 v[12:15], v[144:147], v[200:203], v[12:15]
	v_mfma_f32_16x16x32_bf16 v[8:11], v[152:155], v[200:203], v[8:11]
	v_mfma_f32_16x16x32_bf16 v[60:63], v[148:151], v[180:183], v[60:63]
	v_mfma_f32_16x16x32_bf16 v[56:59], v[156:159], v[180:183], v[56:59]
	v_mfma_f32_16x16x32_bf16 v[44:47], v[148:151], v[188:191], v[44:47]
	v_mfma_f32_16x16x32_bf16 v[40:43], v[156:159], v[188:191], v[40:43]
	v_mfma_f32_16x16x32_bf16 v[28:31], v[148:151], v[196:199], v[28:31]
	v_mfma_f32_16x16x32_bf16 v[24:27], v[156:159], v[196:199], v[24:27]
	v_mfma_f32_16x16x32_bf16 v[12:15], v[148:151], v[204:207], v[12:15]
	v_mfma_f32_16x16x32_bf16 v[8:11], v[156:159], v[204:207], v[8:11]
	s_setprio 0
	s_setprio 1
	v_mfma_f32_16x16x32_bf16 v[52:55], v[160:163], v[176:179], v[52:55]
	v_mfma_f32_16x16x32_bf16 v[48:51], v[168:171], v[176:179], v[48:51]
	v_mfma_f32_16x16x32_bf16 v[36:39], v[160:163], v[184:187], v[36:39]
	v_mfma_f32_16x16x32_bf16 v[32:35], v[168:171], v[184:187], v[32:35]
	v_mfma_f32_16x16x32_bf16 v[20:23], v[160:163], v[192:195], v[20:23]
	v_mfma_f32_16x16x32_bf16 v[16:19], v[168:171], v[192:195], v[16:19]
	v_mfma_f32_16x16x32_bf16 v[4:7], v[160:163], v[200:203], v[4:7]
	v_mfma_f32_16x16x32_bf16 v[0:3], v[168:171], v[200:203], v[0:3]
	v_mfma_f32_16x16x32_bf16 v[52:55], v[164:167], v[180:183], v[52:55]
	v_mfma_f32_16x16x32_bf16 v[48:51], v[172:175], v[180:183], v[48:51]
	v_mfma_f32_16x16x32_bf16 v[36:39], v[164:167], v[188:191], v[36:39]
	v_mfma_f32_16x16x32_bf16 v[32:35], v[172:175], v[188:191], v[32:35]
	v_mfma_f32_16x16x32_bf16 v[20:23], v[164:167], v[196:199], v[20:23]
	v_mfma_f32_16x16x32_bf16 v[16:19], v[172:175], v[196:199], v[16:19]
	v_mfma_f32_16x16x32_bf16 v[4:7], v[164:167], v[204:207], v[4:7]
	v_mfma_f32_16x16x32_bf16 v[0:3], v[172:175], v[204:207], v[0:3]
	s_setprio 0
	s_barrier
	s_add_i32 s53, s53, 2
	s_add_u32 s51, s51, 0x100
	s_addc_u32 s52, s52, 0
	s_cmp_gt_u32 s53, 61
	s_mov_b64 s[18:19], s[20:21]
	s_cbranch_scc0 .LBB0_670
	s_and_b64 vcc, exec, s[6:7]
	s_cbranch_vccz .LBB0_673
	s_barrier

; #define PG8_WAIT_V(n) asm volatile("s_waitcnt vmcnt(" #n ")" ::: "memory")
; #define PG8_WAIT_L(n) asm volatile("s_waitcnt lgkmcnt(" #n ")" ::: "memory")
; #define PG8_BAR __builtin_amdgcn_s_barrier()
; #define PG8_SCHED __builtin_amdgcn_sched_barrier(0)
;     ...
;         const bool has_next = S.next(ui + 1, nxt);
;         const char* nA = has_next ? (const char*)g.A + (size_t)nxt.pm * tstepA : cA; const char* nB = has_next ? (const char*)g.Bt + (size_t)nxt.pn * tstep : cB;
;         for (int t = 0; t < nt; t += 2) {
;             const bool last = (t == nt - 2);
;             const char* a1 = cA + (size_t)(t + 1) * kstep;
;             const char* a2 = last ? nA : cA + (size_t)(t + 2) * kstep; const char* b2 = last ? nB : cB + (size_t)(t + 2) * kstep;
;             const char* a3 = a2 + kstep; const char* b3 = b2 + kstep;
;             if (last && has_next) S.a_ready(nxt);
;             if constexpr (SP2) {
;             PG8_LDB(B0, 0, 0); PG8_LDB(B1, 0, 1); PG8_SCHED; PG8_LDA(At, 0, 0); PG8_STAGE(PG8_SA(1, 1), a1 + hstepA, voffA);
;             PG8_WAIT_V(8); PG8_WAIT_L(0); PG8_BAR; PG8_MMA(0, 0, At, B0); PG8_MMA(0, 1, At, B1); PG8_BAR; PG8_SCHED;
;             if constexpr (!HALFU) PG8_LDA(At, 0, 1); PG8_STAGE(PG8_SB(0, 0), b2, voffB); PG8_STAGE(PG8_SB(0, 1), b2 + hstep, voffB); PG8_STAGE(PG8_SA(0, 0), a2, voffA);
;             PG8_WAIT_V(8); PG8_WAIT_L(0); PG8_BAR; if constexpr (!HALFU) { PG8_MMA(1, 0, At, B0); PG8_MMA(1, 1, At, B1); } PG8_BAR; PG8_SCHED;
.LBB0_793:
	s_add_u32 s98, s10, 0x80
	s_addc_u32 s99, s11, 0
	s_mov_b32 m0, s43
	s_nop 0
	global_load_lds_dwordx4 v128, s[98:99]
	s_mov_b32 m0, s44
	s_nop 0
	global_load_lds_dwordx4 v130, s[98:99]
	ds_read_b128 v[140:143], v137
	ds_read_b128 v[144:147], v137 offset:1024
	ds_read_b128 v[148:151], v137 offset:2048
	ds_read_b128 v[152:155], v137 offset:3072
	ds_read_b128 v[156:159], v138
	ds_read_b128 v[160:163], v138 offset:1024
	ds_read_b128 v[164:167], v138 offset:2048
	ds_read_b128 v[168:171], v138 offset:3072
	s_add_u32 s22, s10, 0x100
	s_addc_u32 s23, s11, 0
	s_cmpk_eq_i32 s54, 0xa8
	s_cselect_b32 s28, s6, s22
	s_cselect_b32 s29, s7, s23
	s_cselect_b32 s26, s20, s52
	s_cselect_b32 s27, s21, s53
	s_add_u32 s24, s28, 0x80
	s_addc_u32 s25, s29, 0
	s_add_u32 s10, s10, 0x2b0080
	s_addc_u32 s11, s11, 0
	s_add_i32 m0, s36, 0xc000
	ds_read_b128 v[172:175], v139
	ds_read_b128 v[176:179], v139 offset:1024
	ds_read_b128 v[180:183], v139 offset:2048
	ds_read_b128 v[184:187], v139 offset:3072
	ds_read_b128 v[188:191], v139 offset:4096
	ds_read_b128 v[192:195], v139 offset:5120
	ds_read_b128 v[196:199], v139 offset:6144
	ds_read_b128 v[200:203], v139 offset:7168
	global_load_lds_dwordx4 v128, s[10:11]
	s_add_i32 m0, s36, 0xe000
	s_nop 0
	global_load_lds_dwordx4 v130, s[10:11]
	s_waitcnt vmcnt(8)
	s_waitcnt lgkmcnt(0)
	s_barrier
	s_setprio 1
	s_waitcnt lgkmcnt(0)
	v_mfma_f32_16x16x32_bf16 v[124:127], v[140:143], v[172:175], v[124:127]
	v_mfma_f32_16x16x32_bf16 v[120:123], v[148:151], v[172:175], v[120:123]
	v_mfma_f32_16x16x32_bf16 v[112:115], v[140:143], v[180:183], v[112:115]
	v_mfma_f32_16x16x32_bf16 v[104:107], v[148:151], v[180:183], v[104:107]
	v_mfma_f32_16x16x32_bf16 v[96:99], v[140:143], v[188:191], v[96:99]
	v_mfma_f32_16x16x32_bf16 v[88:91], v[148:151], v[188:191], v[88:91]
	v_mfma_f32_16x16x32_bf16 v[80:83], v[140:143], v[196:199], v[80:83]
	v_mfma_f32_16x16x32_bf16 v[72:75], v[148:151], v[196:199], v[72:75]
	v_mfma_f32_16x16x32_bf16 v[124:127], v[144:147], v[176:179], v[124:127]
	v_mfma_f32_16x16x32_bf16 v[120:123], v[152:155], v[176:179], v[120:123]
	v_mfma_f32_16x16x32_bf16 v[112:115], v[144:147], v[184:187], v[112:115]
	v_mfma_f32_16x16x32_bf16 v[104:107], v[152:155], v[184:187], v[104:107]
	v_mfma_f32_16x16x32_bf16 v[96:99], v[144:147], v[192:195], v[96:99]
	v_mfma_f32_16x16x32_bf16 v[88:91], v[152:155], v[192:195], v[88:91]
	v_mfma_f32_16x16x32_bf16 v[80:83], v[144:147], v[200:203], v[80:83]
	v_mfma_f32_16x16x32_bf16 v[72:75], v[152:155], v[200:203], v[72:75]
	s_setprio 0
	s_setprio 1
	v_mfma_f32_16x16x32_bf16 v[116:119], v[156:159], v[172:175], v[116:119]
	v_mfma_f32_16x16x32_bf16 v[108:111], v[164:167], v[172:175], v[108:111]
	v_mfma_f32_16x16x32_bf16 v[100:103], v[156:159], v[180:183], v[100:103]
	v_mfma_f32_16x16x32_bf16 v[92:95], v[164:167], v[180:183], v[92:95]
	v_mfma_f32_16x16x32_bf16 v[84:87], v[156:159], v[188:191], v[84:87]
	v_mfma_f32_16x16x32_bf16 v[76:79], v[164:167], v[188:191], v[76:79]
	v_mfma_f32_16x16x32_bf16 v[68:71], v[156:159], v[196:199], v[68:71]
	v_mfma_f32_16x16x32_bf16 v[64:67], v[164:167], v[196:199], v[64:67]
	v_mfma_f32_16x16x32_bf16 v[116:119], v[160:163], v[176:179], v[116:119]
	v_mfma_f32_16x16x32_bf16 v[108:111], v[168:171], v[176:179], v[108:111]
	v_mfma_f32_16x16x32_bf16 v[100:103], v[160:163], v[184:187], v[100:103]
	v_mfma_f32_16x16x32_bf16 v[92:95], v[168:171], v[184:187], v[92:95]
	v_mfma_f32_16x16x32_bf16 v[84:87], v[160:163], v[192:195], v[84:87]
	v_mfma_f32_16x16x32_bf16 v[76:79], v[168:171], v[192:195], v[76:79]
	v_mfma_f32_16x16x32_bf16 v[68:71], v[160:163], v[200:203], v[68:71]
	v_mfma_f32_16x16x32_bf16 v[64:67], v[168:171], v[200:203], v[64:67]
	s_setprio 0
	s_barrier
	s_add_i32 s10, s46, s31
	s_mov_b32 m0, s10
	ds_read_b128 v[172:175], v139 offset:16384
	ds_read_b128 v[176:179], v139 offset:17408
	ds_read_b128 v[180:183], v139 offset:18432
	ds_read_b128 v[184:187], v139 offset:19456
	ds_read_b128 v[188:191], v139 offset:20480
	ds_read_b128 v[192:195], v139 offset:21504
	ds_read_b128 v[196:199], v139 offset:22528
	ds_read_b128 v[200:203], v139 offset:23552
	global_load_lds_dwordx4 v128, s[26:27]
	s_add_i32 m0, s10, 0x2000
	s_add_u32 s10, s26, 0x2b0000
	s_addc_u32 s11, s27, 0
	s_add_i32 s55, s47, s31
	global_load_lds_dwordx4 v130, s[26:27]
	s_mov_b32 m0, s55
	s_nop 0
	global_load_lds_dwordx4 v128, s[10:11]
	s_add_i32 m0, s55, 0x2000
	s_nop 0
	global_load_lds_dwordx4 v130, s[10:11]
	s_waitcnt vmcnt(4)
	s_waitcnt lgkmcnt(0)
	s_barrier
	s_setprio 1
	s_waitcnt lgkmcnt(0)
	v_mfma_f32_16x16x32_bf16 v[60:63], v[140:143], v[172:175], v[60:63]
	v_mfma_f32_16x16x32_bf16 v[56:59], v[148:151], v[172:175], v[56:59]
	v_mfma_f32_16x16x32_bf16 v[48:51], v[140:143], v[180:183], v[48:51]
	v_mfma_f32_16x16x32_bf16 v[40:43], v[148:151], v[180:183], v[40:43]
	v_mfma_f32_16x16x32_bf16 v[32:35], v[140:143], v[188:191], v[32:35]
	v_mfma_f32_16x16x32_bf16 v[24:27], v[148:151], v[188:191], v[24:27]
	v_mfma_f32_16x16x32_bf16 v[16:19], v[140:143], v[196:199], v[16:19]
	v_mfma_f32_16x16x32_bf16 v[8:11], v[148:151], v[196:199], v[8:11]
	v_mfma_f32_16x16x32_bf16 v[60:63], v[144:147], v[176:179], v[60:63]
	v_mfma_f32_16x16x32_bf16 v[56:59], v[152:155], v[176:179], v[56:59]
	v_mfma_f32_16x16x32_bf16 v[48:51], v[144:147], v[184:187], v[48:51]
	v_mfma_f32_16x16x32_bf16 v[40:43], v[152:155], v[184:187], v[40:43]
	v_mfma_f32_16x16x32_bf16 v[32:35], v[144:147], v[192:195], v[32:35]
	v_mfma_f32_16x16x32_bf16 v[24:27], v[152:155], v[192:195], v[24:27]
	v_mfma_f32_16x16x32_bf16 v[16:19], v[144:147], v[200:203], v[16:19]
	v_mfma_f32_16x16x32_bf16 v[8:11], v[152:155], v[200:203], v[8:11]
	s_setprio 0
	s_setprio 1
	v_mfma_f32_16x16x32_bf16 v[52:55], v[156:159], v[172:175], v[52:55]
	v_mfma_f32_16x16x32_bf16 v[44:47], v[164:167], v[172:175], v[44:47]
	v_mfma_f32_16x16x32_bf16 v[36:39], v[156:159], v[180:183], v[36:39]
	v_mfma_f32_16x16x32_bf16 v[28:31], v[164:167], v[180:183], v[28:31]
	v_mfma_f32_16x16x32_bf16 v[20:23], v[156:159], v[188:191], v[20:23]
	v_mfma_f32_16x16x32_bf16 v[12:15], v[164:167], v[188:191], v[12:15]
	v_mfma_f32_16x16x32_bf16 v[4:7], v[156:159], v[196:199], v[4:7]
	v_mfma_f32_16x16x32_bf16 v[0:3], v[164:167], v[196:199], v[0:3]
	v_mfma_f32_16x16x32_bf16 v[52:55], v[160:163], v[176:179], v[52:55]
	v_mfma_f32_16x16x32_bf16 v[44:47], v[168:171], v[176:179], v[44:47]
	v_mfma_f32_16x16x32_bf16 v[36:39], v[160:163], v[184:187], v[36:39]
	v_mfma_f32_16x16x32_bf16 v[28:31], v[168:171], v[184:187], v[28:31]
	v_mfma_f32_16x16x32_bf16 v[20:23], v[160:163], v[192:195], v[20:23]
	v_mfma_f32_16x16x32_bf16 v[12:15], v[168:171], v[192:195], v[12:15]
	v_mfma_f32_16x16x32_bf16 v[4:7], v[160:163], v[200:203], v[4:7]
	v_mfma_f32_16x16x32_bf16 v[0:3], v[168:171], v[200:203], v[0:3]
	s_setprio 0
	s_barrier
; #define PG8_WAIT_V(n) asm volatile("s_waitcnt vmcnt(" #n ")" ::: "memory")
; #define PG8_WAIT_L(n) asm volatile("s_waitcnt lgkmcnt(" #n ")" ::: "memory")
; #define PG8_BAR __builtin_amdgcn_s_barrier()
; #define PG8_SCHED __builtin_amdgcn_sched_barrier(0)
;     ...
;             PG8_LDB(B0, 1, 0); PG8_LDB(B1, 1, 1); PG8_SCHED; PG8_LDA(At, 1, 0); PG8_STAGE(PG8_SA(0, 1), a2 + hstepA, voffA);
;             PG8_WAIT_V(8); PG8_WAIT_L(0); PG8_BAR; PG8_MMA(0, 0, At, B0); PG8_MMA(0, 1, At, B1); PG8_BAR; PG8_SCHED;
;             if constexpr (!HALFU) PG8_LDA(At, 1, 1); PG8_STAGE(PG8_SB(1, 0), b3, voffB); PG8_STAGE(PG8_SB(1, 1), b3 + hstep, voffB); PG8_STAGE(PG8_SA(1, 0), a3, voffA);
;             PG8_WAIT_V(8); PG8_WAIT_L(0); PG8_BAR; if constexpr (!HALFU) { PG8_MMA(1, 0, At, B0); PG8_MMA(1, 1, At, B1); } PG8_BAR; PG8_SCHED;
	s_mov_b32 m0, s36
	s_nop 0
	global_load_lds_dwordx4 v128, s[28:29]
	s_mov_b32 m0, s37
	s_nop 0
	global_load_lds_dwordx4 v130, s[28:29]
	s_add_i32 s55, 0, 0x18000
	s_add_i32 s56, 0, 0x1c000
	v_add_u32_e32 v152, s55, v136
	v_add_u32_e32 v168, s56, v136
	ds_read_b128 v[140:143], v152
	ds_read_b128 v[144:147], v152 offset:1024
	ds_read_b128 v[148:151], v152 offset:2048
	ds_read_b128 v[152:155], v152 offset:3072
	ds_read_b128 v[156:159], v168
	ds_read_b128 v[160:163], v168 offset:1024
	ds_read_b128 v[164:167], v168 offset:2048
	ds_read_b128 v[168:171], v168 offset:3072
	s_add_u32 s10, s28, 0x2b0000
	s_addc_u32 s11, s29, 0
	s_mov_b32 m0, s38
	ds_read_b128 v[172:175], v139 offset:32768
	ds_read_b128 v[176:179], v139 offset:33792
	ds_read_b128 v[180:183], v139 offset:34816
	ds_read_b128 v[184:187], v139 offset:35840
	ds_read_b128 v[188:191], v139 offset:36864
	ds_read_b128 v[192:195], v139 offset:37888
	ds_read_b128 v[196:199], v139 offset:38912
	ds_read_b128 v[200:203], v139 offset:39936
	global_load_lds_dwordx4 v128, s[10:11]
	s_mov_b32 m0, s39
	s_nop 0
	global_load_lds_dwordx4 v130, s[10:11]
	s_waitcnt vmcnt(8)
	s_waitcnt lgkmcnt(0)
	s_barrier
	s_setprio 1
	s_waitcnt lgkmcnt(0)
	v_mfma_f32_16x16x32_bf16 v[124:127], v[140:143], v[172:175], v[124:127]
	v_mfma_f32_16x16x32_bf16 v[120:123], v[148:151], v[172:175], v[120:123]
	v_mfma_f32_16x16x32_bf16 v[112:115], v[140:143], v[180:183], v[112:115]
	v_mfma_f32_16x16x32_bf16 v[104:107], v[148:151], v[180:183], v[104:107]
	v_mfma_f32_16x16x32_bf16 v[96:99], v[140:143], v[188:191], v[96:99]
	v_mfma_f32_16x16x32_bf16 v[88:91], v[148:151], v[188:191], v[88:91]
	v_mfma_f32_16x16x32_bf16 v[80:83], v[140:143], v[196:199], v[80:83]
	v_mfma_f32_16x16x32_bf16 v[72:75], v[148:151], v[196:199], v[72:75]
	v_mfma_f32_16x16x32_bf16 v[124:127], v[144:147], v[176:179], v[124:127]
	v_mfma_f32_16x16x32_bf16 v[120:123], v[152:155], v[176:179], v[120:123]
	v_mfma_f32_16x16x32_bf16 v[112:115], v[144:147], v[184:187], v[112:115]
	v_mfma_f32_16x16x32_bf16 v[104:107], v[152:155], v[184:187], v[104:107]
	v_mfma_f32_16x16x32_bf16 v[96:99], v[144:147], v[192:195], v[96:99]
	v_mfma_f32_16x16x32_bf16 v[88:91], v[152:155], v[192:195], v[88:91]
	v_mfma_f32_16x16x32_bf16 v[80:83], v[144:147], v[200:203], v[80:83]
	v_mfma_f32_16x16x32_bf16 v[72:75], v[152:155], v[200:203], v[72:75]
	s_setprio 0
	s_setprio 1
	v_mfma_f32_16x16x32_bf16 v[116:119], v[156:159], v[172:175], v[116:119]
	v_mfma_f32_16x16x32_bf16 v[108:111], v[164:167], v[172:175], v[108:111]
	v_mfma_f32_16x16x32_bf16 v[100:103], v[156:159], v[180:183], v[100:103]
	v_mfma_f32_16x16x32_bf16 v[92:95], v[164:167], v[180:183], v[92:95]
	v_mfma_f32_16x16x32_bf16 v[84:87], v[156:159], v[188:191], v[84:87]
	v_mfma_f32_16x16x32_bf16 v[76:79], v[164:167], v[188:191], v[76:79]
	v_mfma_f32_16x16x32_bf16 v[68:71], v[156:159], v[196:199], v[68:71]
	v_mfma_f32_16x16x32_bf16 v[64:67], v[164:167], v[196:199], v[64:67]
	v_mfma_f32_16x16x32_bf16 v[116:119], v[160:163], v[176:179], v[116:119]
	v_mfma_f32_16x16x32_bf16 v[108:111], v[168:171], v[176:179], v[108:111]
	v_mfma_f32_16x16x32_bf16 v[100:103], v[160:163], v[184:187], v[100:103]
	v_mfma_f32_16x16x32_bf16 v[92:95], v[168:171], v[184:187], v[92:95]
	v_mfma_f32_16x16x32_bf16 v[84:87], v[160:163], v[192:195], v[84:87]
	v_mfma_f32_16x16x32_bf16 v[76:79], v[168:171], v[192:195], v[76:79]
	v_mfma_f32_16x16x32_bf16 v[68:71], v[160:163], v[200:203], v[68:71]
	v_mfma_f32_16x16x32_bf16 v[64:67], v[168:171], v[200:203], v[64:67]
	s_setprio 0
	s_barrier
	s_add_u32 s10, s26, 0x80
	s_addc_u32 s11, s27, 0
	s_add_i32 s28, s55, s31
	s_mov_b32 m0, s28
	ds_read_b128 v[172:175], v139 offset:49152
	ds_read_b128 v[176:179], v139 offset:50176
	ds_read_b128 v[180:183], v139 offset:51200
	ds_read_b128 v[184:187], v139 offset:52224
	ds_read_b128 v[188:191], v139 offset:53248
	ds_read_b128 v[192:195], v139 offset:54272
	ds_read_b128 v[196:199], v139 offset:55296
	ds_read_b128 v[200:203], v139 offset:56320
	global_load_lds_dwordx4 v128, s[10:11]
	s_add_i32 m0, s28, 0x2000
	v_lshl_add_u64 v[204:205], s[10:11], 0, v[130:131]
	s_add_u32 s10, s26, 0x2b0080
	s_addc_u32 s11, s27, 0
	s_add_i32 s26, s56, s31
	global_load_lds_dwordx4 v[204:205], off
	s_mov_b32 m0, s26
	s_nop 0
	global_load_lds_dwordx4 v128, s[10:11]
	s_add_i32 m0, s26, 0x2000
	s_nop 0
	global_load_lds_dwordx4 v130, s[10:11]
	s_waitcnt vmcnt(4)
	s_waitcnt lgkmcnt(0)
	s_barrier
	s_setprio 1
	s_waitcnt lgkmcnt(0)
	v_mfma_f32_16x16x32_bf16 v[60:63], v[140:143], v[172:175], v[60:63]
	v_mfma_f32_16x16x32_bf16 v[56:59], v[148:151], v[172:175], v[56:59]
	v_mfma_f32_16x16x32_bf16 v[48:51], v[140:143], v[180:183], v[48:51]
	v_mfma_f32_16x16x32_bf16 v[40:43], v[148:151], v[180:183], v[40:43]
	v_mfma_f32_16x16x32_bf16 v[32:35], v[140:143], v[188:191], v[32:35]
	v_mfma_f32_16x16x32_bf16 v[24:27], v[148:151], v[188:191], v[24:27]
	v_mfma_f32_16x16x32_bf16 v[16:19], v[140:143], v[196:199], v[16:19]
	v_mfma_f32_16x16x32_bf16 v[8:11], v[148:151], v[196:199], v[8:11]
	v_mfma_f32_16x16x32_bf16 v[60:63], v[144:147], v[176:179], v[60:63]
	v_mfma_f32_16x16x32_bf16 v[56:59], v[152:155], v[176:179], v[56:59]
	v_mfma_f32_16x16x32_bf16 v[48:51], v[144:147], v[184:187], v[48:51]
	v_mfma_f32_16x16x32_bf16 v[40:43], v[152:155], v[184:187], v[40:43]
	v_mfma_f32_16x16x32_bf16 v[32:35], v[144:147], v[192:195], v[32:35]
	v_mfma_f32_16x16x32_bf16 v[24:27], v[152:155], v[192:195], v[24:27]
	v_mfma_f32_16x16x32_bf16 v[16:19], v[144:147], v[200:203], v[16:19]
	v_mfma_f32_16x16x32_bf16 v[8:11], v[152:155], v[200:203], v[8:11]
	s_setprio 0
	s_setprio 1
	v_mfma_f32_16x16x32_bf16 v[52:55], v[156:159], v[172:175], v[52:55]
	v_mfma_f32_16x16x32_bf16 v[44:47], v[164:167], v[172:175], v[44:47]
	v_mfma_f32_16x16x32_bf16 v[36:39], v[156:159], v[180:183], v[36:39]
	v_mfma_f32_16x16x32_bf16 v[28:31], v[164:167], v[180:183], v[28:31]
	v_mfma_f32_16x16x32_bf16 v[20:23], v[156:159], v[188:191], v[20:23]
	v_mfma_f32_16x16x32_bf16 v[12:15], v[164:167], v[188:191], v[12:15]
	v_mfma_f32_16x16x32_bf16 v[4:7], v[156:159], v[196:199], v[4:7]
	v_mfma_f32_16x16x32_bf16 v[0:3], v[164:167], v[196:199], v[0:3]
	v_mfma_f32_16x16x32_bf16 v[52:55], v[160:163], v[176:179], v[52:55]
	v_mfma_f32_16x16x32_bf16 v[44:47], v[168:171], v[176:179], v[44:47]
	v_mfma_f32_16x16x32_bf16 v[36:39], v[160:163], v[184:187], v[36:39]
	v_mfma_f32_16x16x32_bf16 v[28:31], v[168:171], v[184:187], v[28:31]
	v_mfma_f32_16x16x32_bf16 v[20:23], v[160:163], v[192:195], v[20:23]
	v_mfma_f32_16x16x32_bf16 v[12:15], v[168:171], v[192:195], v[12:15]
	v_mfma_f32_16x16x32_bf16 v[4:7], v[160:163], v[200:203], v[4:7]
	v_mfma_f32_16x16x32_bf16 v[0:3], v[168:171], v[200:203], v[0:3]
	s_setprio 0
	s_barrier
	s_add_i32 s54, s54, 2
	s_add_u32 s52, s52, 0x100
	s_addc_u32 s53, s53, 0
	s_cmpk_gt_u32 s54, 0xa9
	s_mov_b64 s[10:11], s[22:23]
	s_cbranch_scc0 .LBB0_793
	s_and_b64 vcc, exec, s[12:13]
	s_cbranch_vccz .LBB0_796
	s_barrier

; #define PG8_WAIT_V(n) asm volatile("s_waitcnt vmcnt(" #n ")" ::: "memory")
; #define PG8_WAIT_L(n) asm volatile("s_waitcnt lgkmcnt(" #n ")" ::: "memory")
; #define PG8_BAR __builtin_amdgcn_s_barrier()
; #define PG8_SCHED __builtin_amdgcn_sched_barrier(0)
;     ...
;         const bool has_next = S.next(ui + 1, nxt);
;         const char* nA = has_next ? (const char*)g.A + (size_t)nxt.pm * tstepA : cA; const char* nB = has_next ? (const char*)g.Bt + (size_t)nxt.pn * tstep : cB;
;         for (int t = 0; t < nt; t += 2) {
;             const bool last = (t == nt - 2);
;             const char* a1 = cA + (size_t)(t + 1) * kstep;
;             const char* a2 = last ? nA : cA + (size_t)(t + 2) * kstep; const char* b2 = last ? nB : cB + (size_t)(t + 2) * kstep;
;             const char* a3 = a2 + kstep; const char* b3 = b2 + kstep;
;             if (last && has_next) S.a_ready(nxt);
;             if constexpr (SP2) {
;             PG8_LDB(B0, 0, 0); PG8_LDB(B1, 0, 1); PG8_SCHED; PG8_LDA(At, 0, 0); PG8_STAGE(PG8_SA(1, 1), a1 + hstepA, voffA);
;             PG8_WAIT_V(8); PG8_WAIT_L(0); PG8_BAR; PG8_MMA(0, 0, At, B0); PG8_MMA(0, 1, At, B1); PG8_BAR; PG8_SCHED;
;             if constexpr (!HALFU) PG8_LDA(At, 0, 1); PG8_STAGE(PG8_SB(0, 0), b2, voffB); PG8_STAGE(PG8_SB(0, 1), b2 + hstep, voffB); PG8_STAGE(PG8_SA(0, 0), a2, voffA);
;             PG8_WAIT_V(8); PG8_WAIT_L(0); PG8_BAR; if constexpr (!HALFU) { PG8_MMA(1, 0, At, B0); PG8_MMA(1, 1, At, B1); } PG8_BAR; PG8_SCHED;
.LBB0_1200:
	s_add_u32 s98, s10, 0x80
	s_addc_u32 s99, s11, 0
	s_mov_b32 m0, s68
	s_nop 0
	global_load_lds_dwordx4 v136, s[98:99]
	s_mov_b32 m0, s69
	s_nop 0
	global_load_lds_dwordx4 v140, s[98:99]
	ds_read_b128 v[128:131], v149
	ds_read_b128 v[132:135], v149 offset:1024
	ds_read_b128 v[154:157], v149 offset:2048
	ds_read_b128 v[158:161], v149 offset:3072
	ds_read_b128 v[162:165], v150
	ds_read_b128 v[166:169], v150 offset:1024
	ds_read_b128 v[170:173], v150 offset:2048
	ds_read_b128 v[174:177], v150 offset:3072
	s_add_u32 s26, s10, 0x100
	s_addc_u32 s27, s11, 0
	s_cmp_eq_u32 s76, 28
	s_cselect_b32 s50, s9, s26
	s_cselect_b32 s51, s7, s27
	s_cselect_b32 s48, s43, s74
	s_cselect_b32 s49, s41, s75
	s_add_u32 s30, s50, 0x80
	s_addc_u32 s31, s51, 0
	s_add_u32 s10, s10, 0x80080
	s_addc_u32 s11, s11, 0
	s_add_i32 m0, s57, 0xc000
	ds_read_b128 v[178:181], v151
	ds_read_b128 v[182:185], v151 offset:1024
	ds_read_b128 v[186:189], v151 offset:2048
	ds_read_b128 v[190:193], v151 offset:3072
	ds_read_b128 v[194:197], v151 offset:4096
	ds_read_b128 v[198:201], v151 offset:5120
	ds_read_b128 v[202:205], v151 offset:6144
	ds_read_b128 v[206:209], v151 offset:7168
	global_load_lds_dwordx4 v136, s[10:11]
	s_add_i32 m0, s57, 0xe000
	s_nop 0
	global_load_lds_dwordx4 v140, s[10:11]
	s_waitcnt vmcnt(8)
	s_waitcnt lgkmcnt(0)
	s_barrier
	s_setprio 1
	s_waitcnt lgkmcnt(0)
	v_mfma_scale_f32_16x16x128_f8f6f4 v[124:127], v[128:135], v[178:185], v[124:127], v152, v152 op_sel_hi:[0,0,0]
	v_mfma_scale_f32_16x16x128_f8f6f4 v[120:123], v[154:161], v[178:185], v[120:123], v152, v152 op_sel_hi:[0,0,0]
	v_mfma_scale_f32_16x16x128_f8f6f4 v[108:111], v[128:135], v[186:193], v[108:111], v152, v152 op_sel_hi:[0,0,0]
	v_mfma_scale_f32_16x16x128_f8f6f4 v[104:107], v[154:161], v[186:193], v[104:107], v152, v152 op_sel_hi:[0,0,0]
	v_mfma_scale_f32_16x16x128_f8f6f4 v[210:213], v[128:135], v[194:201], v[92:95], v152, v152 op_sel_hi:[0,0,0]
	v_mfma_scale_f32_16x16x128_f8f6f4 v[214:217], v[154:161], v[194:201], v[88:91], v152, v152 op_sel_hi:[0,0,0]
	v_mfma_scale_f32_16x16x128_f8f6f4 v[218:221], v[128:135], v[202:209], v[76:79], v152, v152 op_sel_hi:[0,0,0]
	v_mfma_scale_f32_16x16x128_f8f6f4 v[222:225], v[154:161], v[202:209], v[72:75], v152, v152 op_sel_hi:[0,0,0]
	s_setprio 0
	s_setprio 1
	v_mfma_scale_f32_16x16x128_f8f6f4 v[116:119], v[162:169], v[178:185], v[116:119], v152, v152 op_sel_hi:[0,0,0]
	v_mfma_scale_f32_16x16x128_f8f6f4 v[112:115], v[170:177], v[178:185], v[112:115], v152, v152 op_sel_hi:[0,0,0]
	v_mfma_scale_f32_16x16x128_f8f6f4 v[100:103], v[162:169], v[186:193], v[100:103], v152, v152 op_sel_hi:[0,0,0]
	v_mfma_scale_f32_16x16x128_f8f6f4 v[96:99], v[170:177], v[186:193], v[96:99], v152, v152 op_sel_hi:[0,0,0]
	v_mfma_scale_f32_16x16x128_f8f6f4 v[178:181], v[162:169], v[194:201], v[84:87], v152, v152 op_sel_hi:[0,0,0]
	v_mfma_scale_f32_16x16x128_f8f6f4 v[182:185], v[170:177], v[194:201], v[80:83], v152, v152 op_sel_hi:[0,0,0]
	v_mfma_scale_f32_16x16x128_f8f6f4 v[186:189], v[162:169], v[202:209], v[68:71], v152, v152 op_sel_hi:[0,0,0]
	v_mfma_scale_f32_16x16x128_f8f6f4 v[190:193], v[170:177], v[202:209], v[64:67], v152, v152 op_sel_hi:[0,0,0]
	s_setprio 0
	s_barrier
	s_add_i32 s10, s71, s56
	s_mov_b32 m0, s10
	s_nop 1
	ds_read_b128 v[64:67], v151 offset:16384
	ds_read_b128 v[68:71], v151 offset:17408
	ds_read_b128 v[72:75], v151 offset:18432
	ds_read_b128 v[76:79], v151 offset:19456
	ds_read_b128 v[80:83], v151 offset:20480
	ds_read_b128 v[84:87], v151 offset:21504
	ds_read_b128 v[88:91], v151 offset:22528
	ds_read_b128 v[92:95], v151 offset:23552
	global_load_lds_dwordx4 v138, s[48:49]
	s_add_i32 m0, s10, 0x2000
	s_add_u32 s10, s48, 0x80000
	s_addc_u32 s11, s49, 0
	s_add_i32 s77, s72, s56
	global_load_lds_dwordx4 v142, s[48:49]
	s_mov_b32 m0, s77
	s_nop 0
	global_load_lds_dwordx4 v138, s[10:11]
	s_add_i32 m0, s77, 0x2000
	s_nop 0
	global_load_lds_dwordx4 v142, s[10:11]
	s_waitcnt vmcnt(4)
	s_waitcnt lgkmcnt(0)
	s_barrier
	s_setprio 1
	s_waitcnt lgkmcnt(0)
	v_mfma_scale_f32_16x16x128_f8f6f4 v[60:63], v[128:135], v[64:71], v[60:63], v152, v152 op_sel_hi:[0,0,0]
	v_mfma_scale_f32_16x16x128_f8f6f4 v[56:59], v[154:161], v[64:71], v[56:59], v152, v152 op_sel_hi:[0,0,0]
	v_mfma_scale_f32_16x16x128_f8f6f4 v[194:197], v[128:135], v[72:79], v[44:47], v152, v152 op_sel_hi:[0,0,0]
	v_mfma_scale_f32_16x16x128_f8f6f4 v[198:201], v[154:161], v[72:79], v[40:43], v152, v152 op_sel_hi:[0,0,0]
	v_mfma_scale_f32_16x16x128_f8f6f4 v[202:205], v[128:135], v[80:87], v[28:31], v152, v152 op_sel_hi:[0,0,0]
	v_mfma_scale_f32_16x16x128_f8f6f4 v[206:209], v[154:161], v[80:87], v[24:27], v152, v152 op_sel_hi:[0,0,0]
	v_mfma_scale_f32_16x16x128_f8f6f4 v[226:229], v[128:135], v[88:95], v[12:15], v152, v152 op_sel_hi:[0,0,0]
	v_mfma_scale_f32_16x16x128_f8f6f4 v[230:233], v[154:161], v[88:95], v[8:11], v152, v152 op_sel_hi:[0,0,0]
	s_setprio 0
	s_setprio 1
	v_mfma_scale_f32_16x16x128_f8f6f4 v[52:55], v[162:169], v[64:71], v[52:55], v152, v152 op_sel_hi:[0,0,0]
	v_mfma_scale_f32_16x16x128_f8f6f4 v[48:51], v[170:177], v[64:71], v[48:51], v152, v152 op_sel_hi:[0,0,0]
	v_mfma_scale_f32_16x16x128_f8f6f4 v[234:237], v[162:169], v[72:79], v[36:39], v152, v152 op_sel_hi:[0,0,0]
	v_mfma_scale_f32_16x16x128_f8f6f4 v[238:241], v[170:177], v[72:79], v[32:35], v152, v152 op_sel_hi:[0,0,0]
	v_mfma_scale_f32_16x16x128_f8f6f4 v[242:245], v[162:169], v[80:87], v[20:23], v152, v152 op_sel_hi:[0,0,0]
	v_mfma_scale_f32_16x16x128_f8f6f4 v[246:249], v[170:177], v[80:87], v[16:19], v152, v152 op_sel_hi:[0,0,0]
	v_mfma_scale_f32_16x16x128_f8f6f4 v[250:253], v[162:169], v[88:95], v[4:7], v152, v152 op_sel_hi:[0,0,0]
	v_mfma_scale_f32_16x16x128_f8f6f4 v[144:147], v[170:177], v[88:95], v[0:3], v152, v152 op_sel_hi:[0,0,0]
	s_setprio 0
	s_barrier
; #define PG8_WAIT_V(n) asm volatile("s_waitcnt vmcnt(" #n ")" ::: "memory")
; #define PG8_WAIT_L(n) asm volatile("s_waitcnt lgkmcnt(" #n ")" ::: "memory")
; #define PG8_BAR __builtin_amdgcn_s_barrier()
; #define PG8_SCHED __builtin_amdgcn_sched_barrier(0)
;     ...
;             PG8_LDB(B0, 1, 0); PG8_LDB(B1, 1, 1); PG8_SCHED; PG8_LDA(At, 1, 0); PG8_STAGE(PG8_SA(0, 1), a2 + hstepA, voffA);
;             PG8_WAIT_V(8); PG8_WAIT_L(0); PG8_BAR; PG8_MMA(0, 0, At, B0); PG8_MMA(0, 1, At, B1); PG8_BAR; PG8_SCHED;
;             if constexpr (!HALFU) PG8_LDA(At, 1, 1); PG8_STAGE(PG8_SB(1, 0), b3, voffB); PG8_STAGE(PG8_SB(1, 1), b3 + hstep, voffB); PG8_STAGE(PG8_SA(1, 0), a3, voffA);
;             PG8_WAIT_V(8); PG8_WAIT_L(0); PG8_BAR; if constexpr (!HALFU) { PG8_MMA(1, 0, At, B0); PG8_MMA(1, 1, At, B1); } PG8_BAR; PG8_SCHED;
	s_mov_b32 m0, s57
	s_nop 0
	global_load_lds_dwordx4 v136, s[50:51]
	s_mov_b32 m0, s62
	s_nop 0
	global_load_lds_dwordx4 v140, s[50:51]
	s_add_i32 s77, 0, 0x18000
	v_add_u32_e32 v8, s77, v148
	s_add_i32 s78, 0, 0x1c000
	s_nop 1
	ds_read_b128 v[0:3], v8
	ds_read_b128 v[4:7], v8 offset:1024
	ds_read_b128 v[16:19], v8 offset:2048
	ds_read_b128 v[20:23], v8 offset:3072
	v_add_u32_e32 v8, s78, v148
	ds_read_b128 v[128:131], v8
	ds_read_b128 v[132:135], v8 offset:1024
	ds_read_b128 v[154:157], v8 offset:2048
	ds_read_b128 v[158:161], v8 offset:3072
	s_add_u32 s10, s50, 0x80000
	s_addc_u32 s11, s51, 0
	s_mov_b32 m0, s63
	ds_read_b128 v[8:11], v151 offset:32768
	ds_read_b128 v[12:15], v151 offset:33792
	ds_read_b128 v[24:27], v151 offset:34816
	ds_read_b128 v[28:31], v151 offset:35840
	ds_read_b128 v[32:35], v151 offset:36864
	ds_read_b128 v[36:39], v151 offset:37888
	ds_read_b128 v[40:43], v151 offset:38912
	ds_read_b128 v[44:47], v151 offset:39936
	global_load_lds_dwordx4 v136, s[10:11]
	s_mov_b32 m0, s64
	s_nop 0
	global_load_lds_dwordx4 v140, s[10:11]
	s_waitcnt vmcnt(8)
	s_waitcnt lgkmcnt(0)
	s_barrier
	s_setprio 1
	s_waitcnt lgkmcnt(0)
	v_mfma_scale_f32_16x16x128_f8f6f4 v[124:127], v[0:7], v[8:15], v[124:127], v152, v152 op_sel_hi:[0,0,0]
	v_mfma_scale_f32_16x16x128_f8f6f4 v[120:123], v[16:23], v[8:15], v[120:123], v152, v152 op_sel_hi:[0,0,0]
	v_mfma_scale_f32_16x16x128_f8f6f4 v[108:111], v[0:7], v[24:31], v[108:111], v152, v152 op_sel_hi:[0,0,0]
	v_mfma_scale_f32_16x16x128_f8f6f4 v[104:107], v[16:23], v[24:31], v[104:107], v152, v152 op_sel_hi:[0,0,0]
	v_mfma_scale_f32_16x16x128_f8f6f4 v[92:95], v[0:7], v[32:39], v[210:213], v152, v152 op_sel_hi:[0,0,0]
	v_mfma_scale_f32_16x16x128_f8f6f4 v[88:91], v[16:23], v[32:39], v[214:217], v152, v152 op_sel_hi:[0,0,0]
	v_mfma_scale_f32_16x16x128_f8f6f4 v[76:79], v[0:7], v[40:47], v[218:221], v152, v152 op_sel_hi:[0,0,0]
	v_mfma_scale_f32_16x16x128_f8f6f4 v[72:75], v[16:23], v[40:47], v[222:225], v152, v152 op_sel_hi:[0,0,0]
	s_setprio 0
	s_setprio 1
	v_mfma_scale_f32_16x16x128_f8f6f4 v[116:119], v[128:135], v[8:15], v[116:119], v152, v152 op_sel_hi:[0,0,0]
	v_mfma_scale_f32_16x16x128_f8f6f4 v[112:115], v[154:161], v[8:15], v[112:115], v152, v152 op_sel_hi:[0,0,0]
	v_mfma_scale_f32_16x16x128_f8f6f4 v[100:103], v[128:135], v[24:31], v[100:103], v152, v152 op_sel_hi:[0,0,0]
	v_mfma_scale_f32_16x16x128_f8f6f4 v[96:99], v[154:161], v[24:31], v[96:99], v152, v152 op_sel_hi:[0,0,0]
	v_mfma_scale_f32_16x16x128_f8f6f4 v[84:87], v[128:135], v[32:39], v[178:181], v152, v152 op_sel_hi:[0,0,0]
	v_mfma_scale_f32_16x16x128_f8f6f4 v[80:83], v[154:161], v[32:39], v[182:185], v152, v152 op_sel_hi:[0,0,0]
	v_mfma_scale_f32_16x16x128_f8f6f4 v[68:71], v[128:135], v[40:47], v[186:189], v152, v152 op_sel_hi:[0,0,0]
	v_mfma_scale_f32_16x16x128_f8f6f4 v[64:67], v[154:161], v[40:47], v[190:193], v152, v152 op_sel_hi:[0,0,0]
	s_setprio 0
	s_barrier
	s_add_u32 s10, s48, 0x80
	s_addc_u32 s11, s49, 0
	s_add_i32 s50, s77, s56
	s_mov_b32 m0, s50
	ds_read_b128 v[32:35], v151 offset:49152
	ds_read_b128 v[36:39], v151 offset:50176
	ds_read_b128 v[162:165], v151 offset:51200
	ds_read_b128 v[166:169], v151 offset:52224
	ds_read_b128 v[170:173], v151 offset:53248
	ds_read_b128 v[174:177], v151 offset:54272
	ds_read_b128 v[178:181], v151 offset:55296
	ds_read_b128 v[182:185], v151 offset:56320
	global_load_lds_dwordx4 v138, s[10:11]
	s_add_i32 m0, s50, 0x2000
	v_lshl_add_u64 v[8:9], s[10:11], 0, v[142:143]
	s_add_u32 s10, s48, 0x80080
	s_addc_u32 s11, s49, 0
	s_add_i32 s48, s78, s56
	global_load_lds_dwordx4 v[8:9], off
	s_mov_b32 m0, s48
	s_nop 0
	global_load_lds_dwordx4 v138, s[10:11]
	s_add_i32 m0, s48, 0x2000
	s_nop 0
	global_load_lds_dwordx4 v142, s[10:11]
	s_waitcnt vmcnt(4)
	s_waitcnt lgkmcnt(0)
	s_barrier
	s_setprio 1
	s_waitcnt lgkmcnt(0)
	v_mfma_scale_f32_16x16x128_f8f6f4 v[60:63], v[0:7], v[32:39], v[60:63], v152, v152 op_sel_hi:[0,0,0]
	v_mfma_scale_f32_16x16x128_f8f6f4 v[56:59], v[16:23], v[32:39], v[56:59], v152, v152 op_sel_hi:[0,0,0]
	v_mfma_scale_f32_16x16x128_f8f6f4 v[44:47], v[0:7], v[162:169], v[194:197], v152, v152 op_sel_hi:[0,0,0]
	v_mfma_scale_f32_16x16x128_f8f6f4 v[40:43], v[16:23], v[162:169], v[198:201], v152, v152 op_sel_hi:[0,0,0]
	v_mfma_scale_f32_16x16x128_f8f6f4 v[28:31], v[0:7], v[170:177], v[202:205], v152, v152 op_sel_hi:[0,0,0]
	v_mfma_scale_f32_16x16x128_f8f6f4 v[24:27], v[16:23], v[170:177], v[206:209], v152, v152 op_sel_hi:[0,0,0]
	v_mfma_scale_f32_16x16x128_f8f6f4 v[12:15], v[0:7], v[178:185], v[226:229], v152, v152 op_sel_hi:[0,0,0]
	v_mfma_scale_f32_16x16x128_f8f6f4 v[8:11], v[16:23], v[178:185], v[230:233], v152, v152 op_sel_hi:[0,0,0]
	s_setprio 0
	s_setprio 1
	v_mfma_scale_f32_16x16x128_f8f6f4 v[52:55], v[128:135], v[32:39], v[52:55], v152, v152 op_sel_hi:[0,0,0]
	v_mfma_scale_f32_16x16x128_f8f6f4 v[48:51], v[154:161], v[32:39], v[48:51], v152, v152 op_sel_hi:[0,0,0]
	v_mfma_scale_f32_16x16x128_f8f6f4 v[36:39], v[128:135], v[162:169], v[234:237], v152, v152 op_sel_hi:[0,0,0]
	v_mfma_scale_f32_16x16x128_f8f6f4 v[32:35], v[154:161], v[162:169], v[238:241], v152, v152 op_sel_hi:[0,0,0]
	v_mfma_scale_f32_16x16x128_f8f6f4 v[20:23], v[128:135], v[170:177], v[242:245], v152, v152 op_sel_hi:[0,0,0]
	v_mfma_scale_f32_16x16x128_f8f6f4 v[16:19], v[154:161], v[170:177], v[246:249], v152, v152 op_sel_hi:[0,0,0]
	v_mfma_scale_f32_16x16x128_f8f6f4 v[4:7], v[128:135], v[178:185], v[250:253], v152, v152 op_sel_hi:[0,0,0]
	v_mfma_scale_f32_16x16x128_f8f6f4 v[0:3], v[154:161], v[178:185], v[144:147], v152, v152 op_sel_hi:[0,0,0]
	s_setprio 0
	s_barrier
	s_add_i32 s76, s76, 2
	s_add_u32 s74, s74, 0x100
	s_addc_u32 s75, s75, 0
	s_cmp_gt_u32 s76, 29
	s_mov_b64 s[10:11], s[26:27]
	s_cbranch_scc0 .LBB0_1200
	s_and_b64 vcc, exec, s[36:37]
	s_cbranch_vccz .LBB0_1203
	s_barrier

; #define PG8_WAIT_V(n) asm volatile("s_waitcnt vmcnt(" #n ")" ::: "memory")
; #define PG8_WAIT_L(n) asm volatile("s_waitcnt lgkmcnt(" #n ")" ::: "memory")
; #define PG8_BAR __builtin_amdgcn_s_barrier()
; #define PG8_SCHED __builtin_amdgcn_sched_barrier(0)
;     ...
;         const bool has_next = S.next(ui + 1, nxt);
;         const char* nA = has_next ? (const char*)g.A + (size_t)nxt.pm * tstepA : cA; const char* nB = has_next ? (const char*)g.Bt + (size_t)nxt.pn * tstep : cB;
;         for (int t = 0; t < nt; t += 2) {
;             const bool last = (t == nt - 2);
;             const char* a1 = cA + (size_t)(t + 1) * kstep;
;             const char* a2 = last ? nA : cA + (size_t)(t + 2) * kstep; const char* b2 = last ? nB : cB + (size_t)(t + 2) * kstep;
;             const char* a3 = a2 + kstep; const char* b3 = b2 + kstep;
;             if (last && has_next) S.a_ready(nxt);
;             if constexpr (SP2) {
;             PG8_LDB(B0, 0, 0); PG8_LDB(B1, 0, 1); PG8_SCHED; PG8_LDA(At, 0, 0); PG8_STAGE(PG8_SA(1, 1), a1 + hstepA, voffA);
;             PG8_WAIT_V(8); PG8_WAIT_L(0); PG8_BAR; PG8_MMA(0, 0, At, B0); PG8_MMA(0, 1, At, B1); PG8_BAR; PG8_SCHED;
;             if constexpr (!HALFU) PG8_LDA(At, 0, 1); PG8_STAGE(PG8_SB(0, 0), b2, voffB); PG8_STAGE(PG8_SB(0, 1), b2 + hstep, voffB); PG8_STAGE(PG8_SA(0, 0), a2, voffA);
;             PG8_WAIT_V(8); PG8_WAIT_L(0); PG8_BAR; if constexpr (!HALFU) { PG8_MMA(1, 0, At, B0); PG8_MMA(1, 1, At, B1); } PG8_BAR; PG8_SCHED;
.LBB0_1370:
	s_add_u32 s98, s10, 0x80
	s_addc_u32 s99, s11, 0
	s_mov_b32 m0, s67
	s_nop 0
	global_load_lds_dwordx4 v136, s[98:99]
	s_mov_b32 m0, s68
	s_nop 0
	global_load_lds_dwordx4 v140, s[98:99]
	ds_read_b128 v[128:131], v163
	ds_read_b128 v[132:135], v163 offset:1024
	ds_read_b128 v[150:153], v163 offset:2048
	ds_read_b128 v[154:157], v163 offset:3072
	ds_read_b128 v[158:161], v164
	ds_read_b128 v[166:169], v164 offset:1024
	ds_read_b128 v[170:173], v164 offset:2048
	ds_read_b128 v[174:177], v164 offset:3072
	s_add_u32 s12, s10, 0x100
	s_addc_u32 s13, s11, 0
	s_cmp_eq_u32 s53, 60
	s_cselect_b32 s50, s7, s12
	s_cselect_b32 s51, s0, s13
	s_cselect_b32 s48, s39, s41
	s_cselect_b32 s49, s9, s52
	s_add_u32 s46, s50, 0x80
	s_addc_u32 s47, s51, 0
	s_add_u32 s10, s10, 0x100080
	s_addc_u32 s11, s11, 0
	s_add_i32 m0, s37, 0xc000
	ds_read_b128 v[178:181], v165
	ds_read_b128 v[182:185], v165 offset:1024
	ds_read_b128 v[186:189], v165 offset:2048
	ds_read_b128 v[190:193], v165 offset:3072
	ds_read_b128 v[194:197], v165 offset:4096
	ds_read_b128 v[198:201], v165 offset:5120
	ds_read_b128 v[202:205], v165 offset:6144
	ds_read_b128 v[206:209], v165 offset:7168
	global_load_lds_dwordx4 v136, s[10:11]
	s_add_i32 m0, s37, 0xe000
	s_nop 0
	global_load_lds_dwordx4 v140, s[10:11]
	s_waitcnt vmcnt(8)
	s_waitcnt lgkmcnt(0)
	s_barrier
	s_setprio 1
	s_waitcnt lgkmcnt(0)
	v_mfma_f32_16x16x32_bf16 v[124:127], v[128:131], v[178:181], v[124:127]
	v_mfma_f32_16x16x32_bf16 v[120:123], v[150:153], v[178:181], v[120:123]
	v_mfma_f32_16x16x32_bf16 v[108:111], v[128:131], v[186:189], v[108:111]
	v_mfma_f32_16x16x32_bf16 v[104:107], v[150:153], v[186:189], v[104:107]
	v_mfma_f32_16x16x32_bf16 v[92:95], v[128:131], v[194:197], v[92:95]
	v_mfma_f32_16x16x32_bf16 v[88:91], v[150:153], v[194:197], v[88:91]
	v_mfma_f32_16x16x32_bf16 v[76:79], v[128:131], v[202:205], v[76:79]
	v_mfma_f32_16x16x32_bf16 v[72:75], v[150:153], v[202:205], v[72:75]
	v_mfma_f32_16x16x32_bf16 v[124:127], v[132:135], v[182:185], v[124:127]
	v_mfma_f32_16x16x32_bf16 v[120:123], v[154:157], v[182:185], v[120:123]
	v_mfma_f32_16x16x32_bf16 v[108:111], v[132:135], v[190:193], v[108:111]
	v_mfma_f32_16x16x32_bf16 v[104:107], v[154:157], v[190:193], v[104:107]
	v_mfma_f32_16x16x32_bf16 v[92:95], v[132:135], v[198:201], v[92:95]
	v_mfma_f32_16x16x32_bf16 v[88:91], v[154:157], v[198:201], v[88:91]
	v_mfma_f32_16x16x32_bf16 v[76:79], v[132:135], v[206:209], v[76:79]
	v_mfma_f32_16x16x32_bf16 v[72:75], v[154:157], v[206:209], v[72:75]
	s_setprio 0
	s_setprio 1
	v_mfma_f32_16x16x32_bf16 v[116:119], v[158:161], v[178:181], v[116:119]
	v_mfma_f32_16x16x32_bf16 v[112:115], v[170:173], v[178:181], v[112:115]
	v_mfma_f32_16x16x32_bf16 v[100:103], v[158:161], v[186:189], v[100:103]
	v_mfma_f32_16x16x32_bf16 v[96:99], v[170:173], v[186:189], v[96:99]
	v_mfma_f32_16x16x32_bf16 v[84:87], v[158:161], v[194:197], v[84:87]
	v_mfma_f32_16x16x32_bf16 v[80:83], v[170:173], v[194:197], v[80:83]
	v_mfma_f32_16x16x32_bf16 v[68:71], v[158:161], v[202:205], v[68:71]
	v_mfma_f32_16x16x32_bf16 v[64:67], v[170:173], v[202:205], v[64:67]
	v_mfma_f32_16x16x32_bf16 v[116:119], v[166:169], v[182:185], v[116:119]
	v_mfma_f32_16x16x32_bf16 v[112:115], v[174:177], v[182:185], v[112:115]
	v_mfma_f32_16x16x32_bf16 v[100:103], v[166:169], v[190:193], v[100:103]
	v_mfma_f32_16x16x32_bf16 v[96:99], v[174:177], v[190:193], v[96:99]
	v_mfma_f32_16x16x32_bf16 v[84:87], v[166:169], v[198:201], v[84:87]
	v_mfma_f32_16x16x32_bf16 v[80:83], v[174:177], v[198:201], v[80:83]
	v_mfma_f32_16x16x32_bf16 v[68:71], v[166:169], v[206:209], v[68:71]
	v_mfma_f32_16x16x32_bf16 v[64:67], v[174:177], v[206:209], v[64:67]
	s_setprio 0
	s_barrier
	s_add_i32 s10, s71, s21
	s_mov_b32 m0, s10
	ds_read_b128 v[178:181], v165 offset:16384
	ds_read_b128 v[182:185], v165 offset:17408
	ds_read_b128 v[186:189], v165 offset:18432
	ds_read_b128 v[190:193], v165 offset:19456
	ds_read_b128 v[194:197], v165 offset:20480
	ds_read_b128 v[198:201], v165 offset:21504
	ds_read_b128 v[202:205], v165 offset:22528
	ds_read_b128 v[206:209], v165 offset:23552
	global_load_lds_dwordx4 v138, s[48:49]
	s_add_i32 m0, s10, 0x2000
	s_add_u32 s10, s48, 0x100000
	s_addc_u32 s11, s49, 0
	s_add_i32 s54, s72, s21
	global_load_lds_dwordx4 v142, s[48:49]
	s_mov_b32 m0, s54
	s_nop 0
	global_load_lds_dwordx4 v138, s[10:11]
	s_add_i32 m0, s54, 0x2000
	s_nop 0
	global_load_lds_dwordx4 v142, s[10:11]
	s_waitcnt vmcnt(4)
	s_waitcnt lgkmcnt(0)
	s_barrier
	s_setprio 1
	s_waitcnt lgkmcnt(0)
	v_mfma_f32_16x16x32_bf16 v[60:63], v[128:131], v[178:181], v[60:63]
	v_mfma_f32_16x16x32_bf16 v[56:59], v[150:153], v[178:181], v[56:59]
	v_mfma_f32_16x16x32_bf16 v[44:47], v[128:131], v[186:189], v[44:47]
	v_mfma_f32_16x16x32_bf16 v[40:43], v[150:153], v[186:189], v[40:43]
	v_mfma_f32_16x16x32_bf16 v[28:31], v[128:131], v[194:197], v[28:31]
	v_mfma_f32_16x16x32_bf16 v[24:27], v[150:153], v[194:197], v[24:27]
	v_mfma_f32_16x16x32_bf16 v[12:15], v[128:131], v[202:205], v[12:15]
	v_mfma_f32_16x16x32_bf16 v[8:11], v[150:153], v[202:205], v[8:11]
	v_mfma_f32_16x16x32_bf16 v[60:63], v[132:135], v[182:185], v[60:63]
	v_mfma_f32_16x16x32_bf16 v[56:59], v[154:157], v[182:185], v[56:59]
	v_mfma_f32_16x16x32_bf16 v[44:47], v[132:135], v[190:193], v[44:47]
	v_mfma_f32_16x16x32_bf16 v[40:43], v[154:157], v[190:193], v[40:43]
	v_mfma_f32_16x16x32_bf16 v[28:31], v[132:135], v[198:201], v[28:31]
	v_mfma_f32_16x16x32_bf16 v[24:27], v[154:157], v[198:201], v[24:27]
	v_mfma_f32_16x16x32_bf16 v[12:15], v[132:135], v[206:209], v[12:15]
	v_mfma_f32_16x16x32_bf16 v[8:11], v[154:157], v[206:209], v[8:11]
	s_setprio 0
	s_setprio 1
	v_mfma_f32_16x16x32_bf16 v[52:55], v[158:161], v[178:181], v[52:55]
	v_mfma_f32_16x16x32_bf16 v[48:51], v[170:173], v[178:181], v[48:51]
	v_mfma_f32_16x16x32_bf16 v[36:39], v[158:161], v[186:189], v[36:39]
	v_mfma_f32_16x16x32_bf16 v[32:35], v[170:173], v[186:189], v[32:35]
	v_mfma_f32_16x16x32_bf16 v[20:23], v[158:161], v[194:197], v[20:23]
	v_mfma_f32_16x16x32_bf16 v[16:19], v[170:173], v[194:197], v[16:19]
	v_mfma_f32_16x16x32_bf16 v[4:7], v[158:161], v[202:205], v[4:7]
	v_mfma_f32_16x16x32_bf16 v[0:3], v[170:173], v[202:205], v[0:3]
	v_mfma_f32_16x16x32_bf16 v[52:55], v[166:169], v[182:185], v[52:55]
	v_mfma_f32_16x16x32_bf16 v[48:51], v[174:177], v[182:185], v[48:51]
	v_mfma_f32_16x16x32_bf16 v[36:39], v[166:169], v[190:193], v[36:39]
	v_mfma_f32_16x16x32_bf16 v[32:35], v[174:177], v[190:193], v[32:35]
	v_mfma_f32_16x16x32_bf16 v[20:23], v[166:169], v[198:201], v[20:23]
	v_mfma_f32_16x16x32_bf16 v[16:19], v[174:177], v[198:201], v[16:19]
	v_mfma_f32_16x16x32_bf16 v[4:7], v[166:169], v[206:209], v[4:7]
	v_mfma_f32_16x16x32_bf16 v[0:3], v[174:177], v[206:209], v[0:3]
	s_setprio 0
	s_barrier
; #define PG8_WAIT_V(n) asm volatile("s_waitcnt vmcnt(" #n ")" ::: "memory")
; #define PG8_WAIT_L(n) asm volatile("s_waitcnt lgkmcnt(" #n ")" ::: "memory")
; #define PG8_BAR __builtin_amdgcn_s_barrier()
; #define PG8_SCHED __builtin_amdgcn_sched_barrier(0)
;     ...
;             PG8_LDB(B0, 1, 0); PG8_LDB(B1, 1, 1); PG8_SCHED; PG8_LDA(At, 1, 0); PG8_STAGE(PG8_SA(0, 1), a2 + hstepA, voffA);
;             PG8_WAIT_V(8); PG8_WAIT_L(0); PG8_BAR; PG8_MMA(0, 0, At, B0); PG8_MMA(0, 1, At, B1); PG8_BAR; PG8_SCHED;
;             if constexpr (!HALFU) PG8_LDA(At, 1, 1); PG8_STAGE(PG8_SB(1, 0), b3, voffB); PG8_STAGE(PG8_SB(1, 1), b3 + hstep, voffB); PG8_STAGE(PG8_SA(1, 0), a3, voffA);
;             PG8_WAIT_V(8); PG8_WAIT_L(0); PG8_BAR; if constexpr (!HALFU) { PG8_MMA(1, 0, At, B0); PG8_MMA(1, 1, At, B1); } PG8_BAR; PG8_SCHED;
	s_mov_b32 m0, s37
	s_nop 0
	global_load_lds_dwordx4 v136, s[50:51]
	s_mov_b32 m0, s62
	s_nop 0
	global_load_lds_dwordx4 v140, s[50:51]
	s_add_i32 s54, 0, 0x18000
	v_add_u32_e32 v144, s54, v162
	s_add_i32 s55, 0, 0x1c000
	ds_read_b128 v[128:131], v144
	ds_read_b128 v[132:135], v144 offset:1024
	ds_read_b128 v[150:153], v144 offset:2048
	ds_read_b128 v[154:157], v144 offset:3072
	v_add_u32_e32 v144, s55, v162
	ds_read_b128 v[158:161], v144
	ds_read_b128 v[166:169], v144 offset:1024
	ds_read_b128 v[170:173], v144 offset:2048
	ds_read_b128 v[174:177], v144 offset:3072
	s_add_u32 s10, s50, 0x100000
	s_addc_u32 s11, s51, 0
	s_mov_b32 m0, s63
	ds_read_b128 v[178:181], v165 offset:32768
	ds_read_b128 v[182:185], v165 offset:33792
	ds_read_b128 v[186:189], v165 offset:34816
	ds_read_b128 v[190:193], v165 offset:35840
	ds_read_b128 v[194:197], v165 offset:36864
	ds_read_b128 v[198:201], v165 offset:37888
	ds_read_b128 v[202:205], v165 offset:38912
	ds_read_b128 v[206:209], v165 offset:39936
	global_load_lds_dwordx4 v136, s[10:11]
	s_mov_b32 m0, s64
	s_nop 0
	global_load_lds_dwordx4 v140, s[10:11]
	s_waitcnt vmcnt(8)
	s_waitcnt lgkmcnt(0)
	s_barrier
	s_setprio 1
	s_waitcnt lgkmcnt(0)
	v_mfma_f32_16x16x32_bf16 v[124:127], v[128:131], v[178:181], v[124:127]
	v_mfma_f32_16x16x32_bf16 v[120:123], v[150:153], v[178:181], v[120:123]
	v_mfma_f32_16x16x32_bf16 v[108:111], v[128:131], v[186:189], v[108:111]
	v_mfma_f32_16x16x32_bf16 v[104:107], v[150:153], v[186:189], v[104:107]
	v_mfma_f32_16x16x32_bf16 v[92:95], v[128:131], v[194:197], v[92:95]
	v_mfma_f32_16x16x32_bf16 v[88:91], v[150:153], v[194:197], v[88:91]
	v_mfma_f32_16x16x32_bf16 v[76:79], v[128:131], v[202:205], v[76:79]
	v_mfma_f32_16x16x32_bf16 v[72:75], v[150:153], v[202:205], v[72:75]
	v_mfma_f32_16x16x32_bf16 v[124:127], v[132:135], v[182:185], v[124:127]
	v_mfma_f32_16x16x32_bf16 v[120:123], v[154:157], v[182:185], v[120:123]
	v_mfma_f32_16x16x32_bf16 v[108:111], v[132:135], v[190:193], v[108:111]
	v_mfma_f32_16x16x32_bf16 v[104:107], v[154:157], v[190:193], v[104:107]
	v_mfma_f32_16x16x32_bf16 v[92:95], v[132:135], v[198:201], v[92:95]
	v_mfma_f32_16x16x32_bf16 v[88:91], v[154:157], v[198:201], v[88:91]
	v_mfma_f32_16x16x32_bf16 v[76:79], v[132:135], v[206:209], v[76:79]
	v_mfma_f32_16x16x32_bf16 v[72:75], v[154:157], v[206:209], v[72:75]
	s_setprio 0
	s_setprio 1
	v_mfma_f32_16x16x32_bf16 v[116:119], v[158:161], v[178:181], v[116:119]
	v_mfma_f32_16x16x32_bf16 v[112:115], v[170:173], v[178:181], v[112:115]
	v_mfma_f32_16x16x32_bf16 v[100:103], v[158:161], v[186:189], v[100:103]
	v_mfma_f32_16x16x32_bf16 v[96:99], v[170:173], v[186:189], v[96:99]
	v_mfma_f32_16x16x32_bf16 v[84:87], v[158:161], v[194:197], v[84:87]
	v_mfma_f32_16x16x32_bf16 v[80:83], v[170:173], v[194:197], v[80:83]
	v_mfma_f32_16x16x32_bf16 v[68:71], v[158:161], v[202:205], v[68:71]
	v_mfma_f32_16x16x32_bf16 v[64:67], v[170:173], v[202:205], v[64:67]
	v_mfma_f32_16x16x32_bf16 v[116:119], v[166:169], v[182:185], v[116:119]
	v_mfma_f32_16x16x32_bf16 v[112:115], v[174:177], v[182:185], v[112:115]
	v_mfma_f32_16x16x32_bf16 v[100:103], v[166:169], v[190:193], v[100:103]
	v_mfma_f32_16x16x32_bf16 v[96:99], v[174:177], v[190:193], v[96:99]
	v_mfma_f32_16x16x32_bf16 v[84:87], v[166:169], v[198:201], v[84:87]
	v_mfma_f32_16x16x32_bf16 v[80:83], v[174:177], v[198:201], v[80:83]
	v_mfma_f32_16x16x32_bf16 v[68:71], v[166:169], v[206:209], v[68:71]
	v_mfma_f32_16x16x32_bf16 v[64:67], v[174:177], v[206:209], v[64:67]
	s_setprio 0
	s_barrier
	s_add_u32 s10, s48, 0x80
	s_addc_u32 s11, s49, 0
	s_add_i32 s50, s54, s21
	s_mov_b32 m0, s50
	ds_read_b128 v[178:181], v165 offset:49152
	ds_read_b128 v[182:185], v165 offset:50176
	ds_read_b128 v[186:189], v165 offset:51200
	ds_read_b128 v[190:193], v165 offset:52224
	ds_read_b128 v[194:197], v165 offset:53248
	ds_read_b128 v[198:201], v165 offset:54272
	ds_read_b128 v[202:205], v165 offset:55296
	ds_read_b128 v[206:209], v165 offset:56320
	global_load_lds_dwordx4 v138, s[10:11]
	s_add_i32 m0, s50, 0x2000
	v_lshl_add_u64 v[210:211], s[10:11], 0, v[142:143]
	s_add_u32 s10, s48, 0x100080
	s_addc_u32 s11, s49, 0
	s_add_i32 s48, s55, s21
	global_load_lds_dwordx4 v[210:211], off
	s_mov_b32 m0, s48
	s_nop 0
	global_load_lds_dwordx4 v138, s[10:11]
	s_add_i32 m0, s48, 0x2000
	s_nop 0
	global_load_lds_dwordx4 v142, s[10:11]
	s_waitcnt vmcnt(4)
	s_waitcnt lgkmcnt(0)
	s_barrier
	s_setprio 1
	s_waitcnt lgkmcnt(0)
	v_mfma_f32_16x16x32_bf16 v[60:63], v[128:131], v[178:181], v[60:63]
	v_mfma_f32_16x16x32_bf16 v[56:59], v[150:153], v[178:181], v[56:59]
	v_mfma_f32_16x16x32_bf16 v[44:47], v[128:131], v[186:189], v[44:47]
	v_mfma_f32_16x16x32_bf16 v[40:43], v[150:153], v[186:189], v[40:43]
	v_mfma_f32_16x16x32_bf16 v[28:31], v[128:131], v[194:197], v[28:31]
	v_mfma_f32_16x16x32_bf16 v[24:27], v[150:153], v[194:197], v[24:27]
	v_mfma_f32_16x16x32_bf16 v[12:15], v[128:131], v[202:205], v[12:15]
	v_mfma_f32_16x16x32_bf16 v[8:11], v[150:153], v[202:205], v[8:11]
	v_mfma_f32_16x16x32_bf16 v[60:63], v[132:135], v[182:185], v[60:63]
	v_mfma_f32_16x16x32_bf16 v[56:59], v[154:157], v[182:185], v[56:59]
	v_mfma_f32_16x16x32_bf16 v[44:47], v[132:135], v[190:193], v[44:47]
	v_mfma_f32_16x16x32_bf16 v[40:43], v[154:157], v[190:193], v[40:43]
	v_mfma_f32_16x16x32_bf16 v[28:31], v[132:135], v[198:201], v[28:31]
	v_mfma_f32_16x16x32_bf16 v[24:27], v[154:157], v[198:201], v[24:27]
	v_mfma_f32_16x16x32_bf16 v[12:15], v[132:135], v[206:209], v[12:15]
	v_mfma_f32_16x16x32_bf16 v[8:11], v[154:157], v[206:209], v[8:11]
	s_setprio 0
	s_setprio 1
	v_mfma_f32_16x16x32_bf16 v[52:55], v[158:161], v[178:181], v[52:55]
	v_mfma_f32_16x16x32_bf16 v[48:51], v[170:173], v[178:181], v[48:51]
	v_mfma_f32_16x16x32_bf16 v[36:39], v[158:161], v[186:189], v[36:39]
	v_mfma_f32_16x16x32_bf16 v[32:35], v[170:173], v[186:189], v[32:35]
	v_mfma_f32_16x16x32_bf16 v[20:23], v[158:161], v[194:197], v[20:23]
	v_mfma_f32_16x16x32_bf16 v[16:19], v[170:173], v[194:197], v[16:19]
	v_mfma_f32_16x16x32_bf16 v[4:7], v[158:161], v[202:205], v[4:7]
	v_mfma_f32_16x16x32_bf16 v[0:3], v[170:173], v[202:205], v[0:3]
	v_mfma_f32_16x16x32_bf16 v[52:55], v[166:169], v[182:185], v[52:55]
	v_mfma_f32_16x16x32_bf16 v[48:51], v[174:177], v[182:185], v[48:51]
	v_mfma_f32_16x16x32_bf16 v[36:39], v[166:169], v[190:193], v[36:39]
	v_mfma_f32_16x16x32_bf16 v[32:35], v[174:177], v[190:193], v[32:35]
	v_mfma_f32_16x16x32_bf16 v[20:23], v[166:169], v[198:201], v[20:23]
	v_mfma_f32_16x16x32_bf16 v[16:19], v[174:177], v[198:201], v[16:19]
	v_mfma_f32_16x16x32_bf16 v[4:7], v[166:169], v[206:209], v[4:7]
	v_mfma_f32_16x16x32_bf16 v[0:3], v[174:177], v[206:209], v[0:3]
	s_setprio 0
	s_barrier
	s_add_i32 s53, s53, 2
	s_add_u32 s41, s41, 0x100
	s_addc_u32 s52, s52, 0
	s_cmp_gt_u32 s53, 61
	s_mov_b64 s[10:11], s[12:13]
	s_cbranch_scc0 .LBB0_1370
	s_and_b64 vcc, exec, s[28:29]
	s_cbranch_vccz .LBB0_1373
	s_barrier

; #define PG8_WAIT_V(n) asm volatile("s_waitcnt vmcnt(" #n ")" ::: "memory")
; #define PG8_WAIT_L(n) asm volatile("s_waitcnt lgkmcnt(" #n ")" ::: "memory")
; #define PG8_BAR __builtin_amdgcn_s_barrier()
; #define PG8_SCHED __builtin_amdgcn_sched_barrier(0)
;     ...
;         const bool has_next = S.next(ui + 1, nxt);
;         const char* nA = has_next ? (const char*)g.A + (size_t)nxt.pm * tstepA : cA; const char* nB = has_next ? (const char*)g.Bt + (size_t)nxt.pn * tstep : cB;
;         for (int t = 0; t < nt; t += 2) {
;             const bool last = (t == nt - 2);
;             const char* a1 = cA + (size_t)(t + 1) * kstep;
;             const char* a2 = last ? nA : cA + (size_t)(t + 2) * kstep; const char* b2 = last ? nB : cB + (size_t)(t + 2) * kstep;
;             const char* a3 = a2 + kstep; const char* b3 = b2 + kstep;
;             if (last && has_next) S.a_ready(nxt);
;             if constexpr (SP2) {
;             PG8_LDB(B0, 0, 0); PG8_LDB(B1, 0, 1); PG8_SCHED; PG8_LDA(At, 0, 0); PG8_STAGE(PG8_SA(1, 1), a1 + hstepA, voffA);
;             PG8_WAIT_V(8); PG8_WAIT_L(0); PG8_BAR; PG8_MMA(0, 0, At, B0); PG8_MMA(0, 1, At, B1); PG8_BAR; PG8_SCHED;
;             if constexpr (!HALFU) PG8_LDA(At, 0, 1); PG8_STAGE(PG8_SB(0, 0), b2, voffB); PG8_STAGE(PG8_SB(0, 1), b2 + hstep, voffB); PG8_STAGE(PG8_SA(0, 0), a2, voffA);
;             PG8_WAIT_V(8); PG8_WAIT_L(0); PG8_BAR; if constexpr (!HALFU) { PG8_MMA(1, 0, At, B0); PG8_MMA(1, 1, At, B1); } PG8_BAR; PG8_SCHED;
.LBB0_3426:
	s_sub_u32 s98, s28, 0x80000
	s_subb_u32 s99, s29, 0
	s_mov_b32 m0, s50
	s_nop 0
	global_load_lds_dwordx4 v128, s[98:99]
	s_mov_b32 m0, s51
	s_nop 0
	global_load_lds_dwordx4 v130, s[98:99]
	ds_read_b128 v[142:145], v137
	ds_read_b128 v[146:149], v137 offset:1024
	ds_read_b128 v[150:153], v137 offset:2048
	ds_read_b128 v[154:157], v137 offset:3072
	ds_read_b128 v[158:161], v138
	ds_read_b128 v[162:165], v138 offset:1024
	ds_read_b128 v[166:169], v138 offset:2048
	ds_read_b128 v[170:173], v138 offset:3072
	s_cmp_eq_u32 s62, 28
	s_cselect_b32 s38, s55, s57
	s_cselect_b32 s39, s23, s59
	s_cselect_b32 s36, s56, s60
	s_cselect_b32 s37, s21, s61
	s_add_u32 s30, s38, 0x80
	s_addc_u32 s31, s39, 0
	s_add_i32 m0, s43, 0xc000
	ds_read_b128 v[174:177], v139
	ds_read_b128 v[178:181], v139 offset:1024
	ds_read_b128 v[182:185], v139 offset:2048
	ds_read_b128 v[186:189], v139 offset:3072
	ds_read_b128 v[190:193], v139 offset:4096
	ds_read_b128 v[194:197], v139 offset:5120
	ds_read_b128 v[198:201], v139 offset:6144
	ds_read_b128 v[202:205], v139 offset:7168
	global_load_lds_dwordx4 v128, s[28:29]
	s_add_i32 m0, s43, 0xe000
	s_nop 0
	global_load_lds_dwordx4 v130, s[28:29]
	s_waitcnt vmcnt(8)
	s_waitcnt lgkmcnt(0)
	s_barrier
	s_setprio 1
	s_waitcnt lgkmcnt(0)
	v_mfma_scale_f32_16x16x128_f8f6f4 v[124:127], v[142:149], v[174:181], v[124:127], v140, v140 op_sel_hi:[0,0,0]
	v_mfma_scale_f32_16x16x128_f8f6f4 v[120:123], v[150:157], v[174:181], v[120:123], v140, v140 op_sel_hi:[0,0,0]
	v_mfma_scale_f32_16x16x128_f8f6f4 v[112:115], v[142:149], v[182:189], v[112:115], v140, v140 op_sel_hi:[0,0,0]
	v_mfma_scale_f32_16x16x128_f8f6f4 v[104:107], v[150:157], v[182:189], v[104:107], v140, v140 op_sel_hi:[0,0,0]
	v_mfma_scale_f32_16x16x128_f8f6f4 v[96:99], v[142:149], v[190:197], v[96:99], v140, v140 op_sel_hi:[0,0,0]
	v_mfma_scale_f32_16x16x128_f8f6f4 v[206:209], v[150:157], v[190:197], v[88:91], v140, v140 op_sel_hi:[0,0,0]
	v_mfma_scale_f32_16x16x128_f8f6f4 v[210:213], v[142:149], v[198:205], v[80:83], v140, v140 op_sel_hi:[0,0,0]
	v_mfma_scale_f32_16x16x128_f8f6f4 v[214:217], v[150:157], v[198:205], v[72:75], v140, v140 op_sel_hi:[0,0,0]
	s_setprio 0
	s_setprio 1
	v_mfma_scale_f32_16x16x128_f8f6f4 v[116:119], v[158:165], v[174:181], v[116:119], v140, v140 op_sel_hi:[0,0,0]
	v_mfma_scale_f32_16x16x128_f8f6f4 v[108:111], v[166:173], v[174:181], v[108:111], v140, v140 op_sel_hi:[0,0,0]
	v_mfma_scale_f32_16x16x128_f8f6f4 v[100:103], v[158:165], v[182:189], v[100:103], v140, v140 op_sel_hi:[0,0,0]
	v_mfma_scale_f32_16x16x128_f8f6f4 v[174:177], v[166:173], v[182:189], v[92:95], v140, v140 op_sel_hi:[0,0,0]
	v_mfma_scale_f32_16x16x128_f8f6f4 v[178:181], v[158:165], v[190:197], v[84:87], v140, v140 op_sel_hi:[0,0,0]
	v_mfma_scale_f32_16x16x128_f8f6f4 v[182:185], v[166:173], v[190:197], v[76:79], v140, v140 op_sel_hi:[0,0,0]
	v_mfma_scale_f32_16x16x128_f8f6f4 v[186:189], v[158:165], v[198:205], v[68:71], v140, v140 op_sel_hi:[0,0,0]
	v_mfma_scale_f32_16x16x128_f8f6f4 v[190:193], v[166:173], v[198:205], v[64:67], v140, v140 op_sel_hi:[0,0,0]
	s_setprio 0
	s_barrier
	s_add_i32 s63, s53, s41
	s_mov_b32 m0, s63
	s_nop 1
	ds_read_b128 v[64:67], v139 offset:16384
	ds_read_b128 v[68:71], v139 offset:17408
	ds_read_b128 v[72:75], v139 offset:18432
	ds_read_b128 v[76:79], v139 offset:19456
	ds_read_b128 v[80:83], v139 offset:20480
	ds_read_b128 v[84:87], v139 offset:21504
	ds_read_b128 v[88:91], v139 offset:22528
	ds_read_b128 v[92:95], v139 offset:23552
	global_load_lds_dwordx4 v128, s[36:37]
	s_add_i32 m0, s63, 0x2000
	s_add_u32 s64, s36, 0x80000
	s_addc_u32 s65, s37, 0
	s_add_i32 s63, s54, s41
	global_load_lds_dwordx4 v130, s[36:37]
	s_mov_b32 m0, s63
	s_nop 0
	global_load_lds_dwordx4 v128, s[64:65]
	s_add_i32 m0, s63, 0x2000
	s_nop 0
	global_load_lds_dwordx4 v130, s[64:65]
	s_waitcnt vmcnt(4)
	s_waitcnt lgkmcnt(0)
	s_barrier
	s_setprio 1
	s_waitcnt lgkmcnt(0)
	v_mfma_scale_f32_16x16x128_f8f6f4 v[60:63], v[142:149], v[64:71], v[60:63], v140, v140 op_sel_hi:[0,0,0]
	v_mfma_scale_f32_16x16x128_f8f6f4 v[56:59], v[150:157], v[64:71], v[56:59], v140, v140 op_sel_hi:[0,0,0]
	v_mfma_scale_f32_16x16x128_f8f6f4 v[48:51], v[142:149], v[72:79], v[48:51], v140, v140 op_sel_hi:[0,0,0]
	v_mfma_scale_f32_16x16x128_f8f6f4 v[194:197], v[150:157], v[72:79], v[40:43], v140, v140 op_sel_hi:[0,0,0]
	v_mfma_scale_f32_16x16x128_f8f6f4 v[198:201], v[142:149], v[80:87], v[32:35], v140, v140 op_sel_hi:[0,0,0]
	v_mfma_scale_f32_16x16x128_f8f6f4 v[202:205], v[150:157], v[80:87], v[24:27], v140, v140 op_sel_hi:[0,0,0]
	v_mfma_scale_f32_16x16x128_f8f6f4 v[218:221], v[142:149], v[88:95], v[16:19], v140, v140 op_sel_hi:[0,0,0]
	v_mfma_scale_f32_16x16x128_f8f6f4 v[222:225], v[150:157], v[88:95], v[8:11], v140, v140 op_sel_hi:[0,0,0]
	s_setprio 0
	s_setprio 1
	v_mfma_scale_f32_16x16x128_f8f6f4 v[52:55], v[158:165], v[64:71], v[52:55], v140, v140 op_sel_hi:[0,0,0]
	v_mfma_scale_f32_16x16x128_f8f6f4 v[226:229], v[166:173], v[64:71], v[44:47], v140, v140 op_sel_hi:[0,0,0]
	v_mfma_scale_f32_16x16x128_f8f6f4 v[230:233], v[158:165], v[72:79], v[36:39], v140, v140 op_sel_hi:[0,0,0]
	v_mfma_scale_f32_16x16x128_f8f6f4 v[234:237], v[166:173], v[72:79], v[28:31], v140, v140 op_sel_hi:[0,0,0]
	v_mfma_scale_f32_16x16x128_f8f6f4 v[238:241], v[158:165], v[80:87], v[20:23], v140, v140 op_sel_hi:[0,0,0]
	v_mfma_scale_f32_16x16x128_f8f6f4 v[242:245], v[166:173], v[80:87], v[12:15], v140, v140 op_sel_hi:[0,0,0]
	v_mfma_scale_f32_16x16x128_f8f6f4 v[246:249], v[158:165], v[88:95], v[4:7], v140, v140 op_sel_hi:[0,0,0]
	v_mfma_scale_f32_16x16x128_f8f6f4 v[250:253], v[166:173], v[88:95], v[0:3], v140, v140 op_sel_hi:[0,0,0]
	s_setprio 0
	s_barrier
; #define PG8_WAIT_V(n) asm volatile("s_waitcnt vmcnt(" #n ")" ::: "memory")
; #define PG8_WAIT_L(n) asm volatile("s_waitcnt lgkmcnt(" #n ")" ::: "memory")
; #define PG8_BAR __builtin_amdgcn_s_barrier()
; #define PG8_SCHED __builtin_amdgcn_sched_barrier(0)
;     ...
;             PG8_LDB(B0, 1, 0); PG8_LDB(B1, 1, 1); PG8_SCHED; PG8_LDA(At, 1, 0); PG8_STAGE(PG8_SA(0, 1), a2 + hstepA, voffA);
;             PG8_WAIT_V(8); PG8_WAIT_L(0); PG8_BAR; PG8_MMA(0, 0, At, B0); PG8_MMA(0, 1, At, B1); PG8_BAR; PG8_SCHED;
;             if constexpr (!HALFU) PG8_LDA(At, 1, 1); PG8_STAGE(PG8_SB(1, 0), b3, voffB); PG8_STAGE(PG8_SB(1, 1), b3 + hstep, voffB); PG8_STAGE(PG8_SA(1, 0), a3, voffA);
;             PG8_WAIT_V(8); PG8_WAIT_L(0); PG8_BAR; if constexpr (!HALFU) { PG8_MMA(1, 0, At, B0); PG8_MMA(1, 1, At, B1); } PG8_BAR; PG8_SCHED;
	s_mov_b32 m0, s43
	s_nop 0
	global_load_lds_dwordx4 v128, s[38:39]
	s_mov_b32 m0, s44
	s_nop 0
	global_load_lds_dwordx4 v130, s[38:39]
	s_add_i32 s63, 0, 0x18000
	s_add_i32 s64, 0, 0x1c000
	s_nop 0
	v_add_u32_e32 v12, s63, v136
	v_add_u32_e32 v16, s64, v136
	ds_read_b128 v[0:3], v12
	ds_read_b128 v[4:7], v12 offset:1024
	ds_read_b128 v[8:11], v12 offset:2048
	ds_read_b128 v[12:15], v12 offset:3072
	ds_read_b128 v[142:145], v16
	ds_read_b128 v[146:149], v16 offset:1024
	ds_read_b128 v[150:153], v16 offset:2048
	ds_read_b128 v[154:157], v16 offset:3072
	s_add_u32 s38, s38, 0x80000
	s_addc_u32 s39, s39, 0
	s_mov_b32 m0, s45
	ds_read_b128 v[16:19], v139 offset:32768
	ds_read_b128 v[20:23], v139 offset:33792
	ds_read_b128 v[24:27], v139 offset:34816
	ds_read_b128 v[28:31], v139 offset:35840
	ds_read_b128 v[32:35], v139 offset:36864
	ds_read_b128 v[36:39], v139 offset:37888
	ds_read_b128 v[40:43], v139 offset:38912
	ds_read_b128 v[44:47], v139 offset:39936
	global_load_lds_dwordx4 v128, s[38:39]
	s_mov_b32 m0, s46
	s_nop 0
	global_load_lds_dwordx4 v130, s[38:39]
	s_waitcnt vmcnt(8)
	s_waitcnt lgkmcnt(0)
	s_barrier
	s_setprio 1
	s_waitcnt lgkmcnt(0)
	v_mfma_scale_f32_16x16x128_f8f6f4 v[124:127], v[0:7], v[16:23], v[124:127], v140, v140 op_sel_hi:[0,0,0]
	v_mfma_scale_f32_16x16x128_f8f6f4 v[120:123], v[8:15], v[16:23], v[120:123], v140, v140 op_sel_hi:[0,0,0]
	v_mfma_scale_f32_16x16x128_f8f6f4 v[112:115], v[0:7], v[24:31], v[112:115], v140, v140 op_sel_hi:[0,0,0]
	v_mfma_scale_f32_16x16x128_f8f6f4 v[104:107], v[8:15], v[24:31], v[104:107], v140, v140 op_sel_hi:[0,0,0]
	v_mfma_scale_f32_16x16x128_f8f6f4 v[96:99], v[0:7], v[32:39], v[96:99], v140, v140 op_sel_hi:[0,0,0]
	v_mfma_scale_f32_16x16x128_f8f6f4 v[88:91], v[8:15], v[32:39], v[206:209], v140, v140 op_sel_hi:[0,0,0]
	v_mfma_scale_f32_16x16x128_f8f6f4 v[80:83], v[0:7], v[40:47], v[210:213], v140, v140 op_sel_hi:[0,0,0]
	v_mfma_scale_f32_16x16x128_f8f6f4 v[72:75], v[8:15], v[40:47], v[214:217], v140, v140 op_sel_hi:[0,0,0]
	s_setprio 0
	s_setprio 1
	v_mfma_scale_f32_16x16x128_f8f6f4 v[116:119], v[142:149], v[16:23], v[116:119], v140, v140 op_sel_hi:[0,0,0]
	v_mfma_scale_f32_16x16x128_f8f6f4 v[108:111], v[150:157], v[16:23], v[108:111], v140, v140 op_sel_hi:[0,0,0]
	v_mfma_scale_f32_16x16x128_f8f6f4 v[100:103], v[142:149], v[24:31], v[100:103], v140, v140 op_sel_hi:[0,0,0]
	v_mfma_scale_f32_16x16x128_f8f6f4 v[92:95], v[150:157], v[24:31], v[174:177], v140, v140 op_sel_hi:[0,0,0]
	v_mfma_scale_f32_16x16x128_f8f6f4 v[84:87], v[142:149], v[32:39], v[178:181], v140, v140 op_sel_hi:[0,0,0]
	v_mfma_scale_f32_16x16x128_f8f6f4 v[76:79], v[150:157], v[32:39], v[182:185], v140, v140 op_sel_hi:[0,0,0]
	v_mfma_scale_f32_16x16x128_f8f6f4 v[68:71], v[142:149], v[40:47], v[186:189], v140, v140 op_sel_hi:[0,0,0]
	v_mfma_scale_f32_16x16x128_f8f6f4 v[64:67], v[150:157], v[40:47], v[190:193], v140, v140 op_sel_hi:[0,0,0]
	s_setprio 0
	s_barrier
	s_add_u32 s38, s36, 0x80
	s_addc_u32 s39, s37, 0
	s_add_i32 s63, s63, s41
	s_mov_b32 m0, s63
	ds_read_b128 v[158:161], v139 offset:49152
	ds_read_b128 v[162:165], v139 offset:50176
	ds_read_b128 v[166:169], v139 offset:51200
	ds_read_b128 v[170:173], v139 offset:52224
	ds_read_b128 v[174:177], v139 offset:53248
	ds_read_b128 v[178:181], v139 offset:54272
	ds_read_b128 v[182:185], v139 offset:55296
	ds_read_b128 v[186:189], v139 offset:56320
	global_load_lds_dwordx4 v128, s[38:39]
	s_add_i32 m0, s63, 0x2000
	s_add_u32 s36, s36, 0x80080
	v_lshl_add_u64 v[16:17], s[38:39], 0, v[130:131]
	s_addc_u32 s37, s37, 0
	s_add_i32 s38, s64, s41
	global_load_lds_dwordx4 v[16:17], off
	s_mov_b32 m0, s38
	s_nop 0
	global_load_lds_dwordx4 v128, s[36:37]
	s_add_i32 m0, s38, 0x2000
	s_nop 0
	global_load_lds_dwordx4 v130, s[36:37]
	s_waitcnt vmcnt(4)
	s_waitcnt lgkmcnt(0)
	s_barrier
	s_setprio 1
	s_waitcnt lgkmcnt(0)
	v_mfma_scale_f32_16x16x128_f8f6f4 v[60:63], v[0:7], v[158:165], v[60:63], v140, v140 op_sel_hi:[0,0,0]
	v_mfma_scale_f32_16x16x128_f8f6f4 v[56:59], v[8:15], v[158:165], v[56:59], v140, v140 op_sel_hi:[0,0,0]
	v_mfma_scale_f32_16x16x128_f8f6f4 v[48:51], v[0:7], v[166:173], v[48:51], v140, v140 op_sel_hi:[0,0,0]
	v_mfma_scale_f32_16x16x128_f8f6f4 v[40:43], v[8:15], v[166:173], v[194:197], v140, v140 op_sel_hi:[0,0,0]
	v_mfma_scale_f32_16x16x128_f8f6f4 v[32:35], v[0:7], v[174:181], v[198:201], v140, v140 op_sel_hi:[0,0,0]
	v_mfma_scale_f32_16x16x128_f8f6f4 v[24:27], v[8:15], v[174:181], v[202:205], v140, v140 op_sel_hi:[0,0,0]
	v_mfma_scale_f32_16x16x128_f8f6f4 v[16:19], v[0:7], v[182:189], v[218:221], v140, v140 op_sel_hi:[0,0,0]
	v_mfma_scale_f32_16x16x128_f8f6f4 v[8:11], v[8:15], v[182:189], v[222:225], v140, v140 op_sel_hi:[0,0,0]
	s_setprio 0
	s_setprio 1
	v_mfma_scale_f32_16x16x128_f8f6f4 v[52:55], v[142:149], v[158:165], v[52:55], v140, v140 op_sel_hi:[0,0,0]
	v_mfma_scale_f32_16x16x128_f8f6f4 v[44:47], v[150:157], v[158:165], v[226:229], v140, v140 op_sel_hi:[0,0,0]
	v_mfma_scale_f32_16x16x128_f8f6f4 v[36:39], v[142:149], v[166:173], v[230:233], v140, v140 op_sel_hi:[0,0,0]
	v_mfma_scale_f32_16x16x128_f8f6f4 v[28:31], v[150:157], v[166:173], v[234:237], v140, v140 op_sel_hi:[0,0,0]
	v_mfma_scale_f32_16x16x128_f8f6f4 v[20:23], v[142:149], v[174:181], v[238:241], v140, v140 op_sel_hi:[0,0,0]
	v_mfma_scale_f32_16x16x128_f8f6f4 v[12:15], v[150:157], v[174:181], v[242:245], v140, v140 op_sel_hi:[0,0,0]
	v_mfma_scale_f32_16x16x128_f8f6f4 v[4:7], v[142:149], v[182:189], v[246:249], v140, v140 op_sel_hi:[0,0,0]
	v_mfma_scale_f32_16x16x128_f8f6f4 v[0:3], v[150:157], v[182:189], v[250:253], v140, v140 op_sel_hi:[0,0,0]
	s_setprio 0
	s_barrier
	s_add_i32 s62, s62, 2
	s_add_u32 s57, s57, 0x100
	s_addc_u32 s59, s59, 0
	s_add_u32 s60, s60, 0x100
	s_addc_u32 s61, s61, 0
	s_add_u32 s28, s28, 0x100
	s_addc_u32 s29, s29, 0
	s_cmp_gt_u32 s62, 29
	s_cbranch_scc0 .LBB0_3426
	s_and_b64 vcc, exec, s[6:7]
	s_cbranch_vccz .LBB0_3429
	s_barrier

; #define PG8_WAIT_V(n) asm volatile("s_waitcnt vmcnt(" #n ")" ::: "memory")
; #define PG8_WAIT_L(n) asm volatile("s_waitcnt lgkmcnt(" #n ")" ::: "memory")
; #define PG8_BAR __builtin_amdgcn_s_barrier()
; #define PG8_SCHED __builtin_amdgcn_sched_barrier(0)
;     ...
;         const bool has_next = S.next(ui + 1, nxt);
;         const char* nA = has_next ? (const char*)g.A + (size_t)nxt.pm * tstepA : cA; const char* nB = has_next ? (const char*)g.Bt + (size_t)nxt.pn * tstep : cB;
;         for (int t = 0; t < nt; t += 2) {
;             const bool last = (t == nt - 2);
;             const char* a1 = cA + (size_t)(t + 1) * kstep;
;             const char* a2 = last ? nA : cA + (size_t)(t + 2) * kstep; const char* b2 = last ? nB : cB + (size_t)(t + 2) * kstep;
;             const char* a3 = a2 + kstep; const char* b3 = b2 + kstep;
;             if (last && has_next) S.a_ready(nxt);
;             if constexpr (SP2) {
;             PG8_LDB(B0, 0, 0); PG8_LDB(B1, 0, 1); PG8_SCHED; PG8_LDA(At, 0, 0); PG8_STAGE(PG8_SA(1, 1), a1 + hstepA, voffA);
;             PG8_WAIT_V(8); PG8_WAIT_L(0); PG8_BAR; PG8_MMA(0, 0, At, B0); PG8_MMA(0, 1, At, B1); PG8_BAR; PG8_SCHED;
;             if constexpr (!HALFU) PG8_LDA(At, 0, 1); PG8_STAGE(PG8_SB(0, 0), b2, voffB); PG8_STAGE(PG8_SB(0, 1), b2 + hstep, voffB); PG8_STAGE(PG8_SA(0, 0), a2, voffA);
;             PG8_WAIT_V(8); PG8_WAIT_L(0); PG8_BAR; if constexpr (!HALFU) { PG8_MMA(1, 0, At, B0); PG8_MMA(1, 1, At, B1); } PG8_BAR; PG8_SCHED;
.LBB0_3554:
	s_add_u32 s98, s24, 0x80
	s_addc_u32 s99, s25, 0
	s_mov_b32 m0, s49
	s_nop 0
	global_load_lds_dwordx4 v134, s[98:99]
	s_mov_b32 m0, s50
	s_nop 0
	global_load_lds_dwordx4 v132, s[98:99]
	ds_read_b128 v[144:147], v141
	ds_read_b128 v[148:151], v141 offset:1024
	ds_read_b128 v[152:155], v141 offset:2048
	ds_read_b128 v[156:159], v141 offset:3072
	ds_read_b128 v[160:163], v142
	ds_read_b128 v[164:167], v142 offset:1024
	ds_read_b128 v[168:171], v142 offset:2048
	ds_read_b128 v[172:175], v142 offset:3072
	s_add_u32 s26, s24, 0x100
	s_addc_u32 s27, s25, 0
	s_cmp_eq_u32 s59, 60
	s_cselect_b32 s36, s54, s26
	s_cselect_b32 s37, s15, s27
	s_cselect_b32 s30, s55, s56
	s_cselect_b32 s31, s13, s57
	s_add_u32 s28, s36, 0x80
	s_addc_u32 s29, s37, 0
	s_add_u32 s24, s24, 0x100080
	s_addc_u32 s25, s25, 0
	s_add_i32 m0, s23, 0xc000
	ds_read_b128 v[176:179], v143
	ds_read_b128 v[180:183], v143 offset:1024
	ds_read_b128 v[184:187], v143 offset:2048
	ds_read_b128 v[188:191], v143 offset:3072
	ds_read_b128 v[192:195], v143 offset:4096
	ds_read_b128 v[196:199], v143 offset:5120
	ds_read_b128 v[200:203], v143 offset:6144
	ds_read_b128 v[204:207], v143 offset:7168
	global_load_lds_dwordx4 v134, s[24:25]
	s_add_i32 m0, s23, 0xe000
	s_nop 0
	global_load_lds_dwordx4 v132, s[24:25]
	s_waitcnt vmcnt(8)
	s_waitcnt lgkmcnt(0)
	s_barrier
	s_setprio 1
	s_waitcnt lgkmcnt(0)
	v_mfma_f32_16x16x32_bf16 v[124:127], v[144:147], v[176:179], v[124:127]
	v_mfma_f32_16x16x32_bf16 v[120:123], v[152:155], v[176:179], v[120:123]
	v_mfma_f32_16x16x32_bf16 v[108:111], v[144:147], v[184:187], v[108:111]
	v_mfma_f32_16x16x32_bf16 v[104:107], v[152:155], v[184:187], v[104:107]
	v_mfma_f32_16x16x32_bf16 v[92:95], v[144:147], v[192:195], v[92:95]
	v_mfma_f32_16x16x32_bf16 v[88:91], v[152:155], v[192:195], v[88:91]
	v_mfma_f32_16x16x32_bf16 v[76:79], v[144:147], v[200:203], v[76:79]
	v_mfma_f32_16x16x32_bf16 v[72:75], v[152:155], v[200:203], v[72:75]
	v_mfma_f32_16x16x32_bf16 v[124:127], v[148:151], v[180:183], v[124:127]
	v_mfma_f32_16x16x32_bf16 v[120:123], v[156:159], v[180:183], v[120:123]
	v_mfma_f32_16x16x32_bf16 v[108:111], v[148:151], v[188:191], v[108:111]
	v_mfma_f32_16x16x32_bf16 v[104:107], v[156:159], v[188:191], v[104:107]
	v_mfma_f32_16x16x32_bf16 v[92:95], v[148:151], v[196:199], v[92:95]
	v_mfma_f32_16x16x32_bf16 v[88:91], v[156:159], v[196:199], v[88:91]
	v_mfma_f32_16x16x32_bf16 v[76:79], v[148:151], v[204:207], v[76:79]
	v_mfma_f32_16x16x32_bf16 v[72:75], v[156:159], v[204:207], v[72:75]
	s_setprio 0
	s_setprio 1
	v_mfma_f32_16x16x32_bf16 v[116:119], v[160:163], v[176:179], v[116:119]
	v_mfma_f32_16x16x32_bf16 v[112:115], v[168:171], v[176:179], v[112:115]
	v_mfma_f32_16x16x32_bf16 v[100:103], v[160:163], v[184:187], v[100:103]
	v_mfma_f32_16x16x32_bf16 v[96:99], v[168:171], v[184:187], v[96:99]
	v_mfma_f32_16x16x32_bf16 v[84:87], v[160:163], v[192:195], v[84:87]
	v_mfma_f32_16x16x32_bf16 v[80:83], v[168:171], v[192:195], v[80:83]
	v_mfma_f32_16x16x32_bf16 v[68:71], v[160:163], v[200:203], v[68:71]
	v_mfma_f32_16x16x32_bf16 v[64:67], v[168:171], v[200:203], v[64:67]
	v_mfma_f32_16x16x32_bf16 v[116:119], v[164:167], v[180:183], v[116:119]
	v_mfma_f32_16x16x32_bf16 v[112:115], v[172:175], v[180:183], v[112:115]
	v_mfma_f32_16x16x32_bf16 v[100:103], v[164:167], v[188:191], v[100:103]
	v_mfma_f32_16x16x32_bf16 v[96:99], v[172:175], v[188:191], v[96:99]
	v_mfma_f32_16x16x32_bf16 v[84:87], v[164:167], v[196:199], v[84:87]
	v_mfma_f32_16x16x32_bf16 v[80:83], v[172:175], v[196:199], v[80:83]
	v_mfma_f32_16x16x32_bf16 v[68:71], v[164:167], v[204:207], v[68:71]
	v_mfma_f32_16x16x32_bf16 v[64:67], v[172:175], v[204:207], v[64:67]
	s_setprio 0
	s_barrier
	s_add_i32 s24, s6, s40
	s_mov_b32 m0, s24
	ds_read_b128 v[176:179], v143 offset:16384
	ds_read_b128 v[180:183], v143 offset:17408
	ds_read_b128 v[184:187], v143 offset:18432
	ds_read_b128 v[188:191], v143 offset:19456
	ds_read_b128 v[192:195], v143 offset:20480
	ds_read_b128 v[196:199], v143 offset:21504
	ds_read_b128 v[200:203], v143 offset:22528
	ds_read_b128 v[204:207], v143 offset:23552
	global_load_lds_dwordx4 v128, s[30:31]
	s_add_i32 m0, s24, 0x2000
	s_add_u32 s24, s30, 0x100000
	s_addc_u32 s25, s31, 0
	s_add_i32 s60, s51, s40
	global_load_lds_dwordx4 v130, s[30:31]
	s_mov_b32 m0, s60
	s_nop 0
	global_load_lds_dwordx4 v128, s[24:25]
	s_add_i32 m0, s60, 0x2000
	s_nop 0
	global_load_lds_dwordx4 v130, s[24:25]
	s_waitcnt vmcnt(4)
	s_waitcnt lgkmcnt(0)
	s_barrier
	s_setprio 1
	s_waitcnt lgkmcnt(0)
	v_mfma_f32_16x16x32_bf16 v[60:63], v[144:147], v[176:179], v[60:63]
	v_mfma_f32_16x16x32_bf16 v[56:59], v[152:155], v[176:179], v[56:59]
	v_mfma_f32_16x16x32_bf16 v[44:47], v[144:147], v[184:187], v[44:47]
	v_mfma_f32_16x16x32_bf16 v[40:43], v[152:155], v[184:187], v[40:43]
	v_mfma_f32_16x16x32_bf16 v[28:31], v[144:147], v[192:195], v[28:31]
	v_mfma_f32_16x16x32_bf16 v[24:27], v[152:155], v[192:195], v[24:27]
	v_mfma_f32_16x16x32_bf16 v[12:15], v[144:147], v[200:203], v[12:15]
	v_mfma_f32_16x16x32_bf16 v[8:11], v[152:155], v[200:203], v[8:11]
	v_mfma_f32_16x16x32_bf16 v[60:63], v[148:151], v[180:183], v[60:63]
	v_mfma_f32_16x16x32_bf16 v[56:59], v[156:159], v[180:183], v[56:59]
	v_mfma_f32_16x16x32_bf16 v[44:47], v[148:151], v[188:191], v[44:47]
	v_mfma_f32_16x16x32_bf16 v[40:43], v[156:159], v[188:191], v[40:43]
	v_mfma_f32_16x16x32_bf16 v[28:31], v[148:151], v[196:199], v[28:31]
	v_mfma_f32_16x16x32_bf16 v[24:27], v[156:159], v[196:199], v[24:27]
	v_mfma_f32_16x16x32_bf16 v[12:15], v[148:151], v[204:207], v[12:15]
	v_mfma_f32_16x16x32_bf16 v[8:11], v[156:159], v[204:207], v[8:11]
	s_setprio 0
	s_setprio 1
	v_mfma_f32_16x16x32_bf16 v[52:55], v[160:163], v[176:179], v[52:55]
	v_mfma_f32_16x16x32_bf16 v[48:51], v[168:171], v[176:179], v[48:51]
	v_mfma_f32_16x16x32_bf16 v[36:39], v[160:163], v[184:187], v[36:39]
	v_mfma_f32_16x16x32_bf16 v[32:35], v[168:171], v[184:187], v[32:35]
	v_mfma_f32_16x16x32_bf16 v[20:23], v[160:163], v[192:195], v[20:23]
	v_mfma_f32_16x16x32_bf16 v[16:19], v[168:171], v[192:195], v[16:19]
	v_mfma_f32_16x16x32_bf16 v[4:7], v[160:163], v[200:203], v[4:7]
	v_mfma_f32_16x16x32_bf16 v[0:3], v[168:171], v[200:203], v[0:3]
	v_mfma_f32_16x16x32_bf16 v[52:55], v[164:167], v[180:183], v[52:55]
	v_mfma_f32_16x16x32_bf16 v[48:51], v[172:175], v[180:183], v[48:51]
	v_mfma_f32_16x16x32_bf16 v[36:39], v[164:167], v[188:191], v[36:39]
	v_mfma_f32_16x16x32_bf16 v[32:35], v[172:175], v[188:191], v[32:35]
	v_mfma_f32_16x16x32_bf16 v[20:23], v[164:167], v[196:199], v[20:23]
	v_mfma_f32_16x16x32_bf16 v[16:19], v[172:175], v[196:199], v[16:19]
	v_mfma_f32_16x16x32_bf16 v[4:7], v[164:167], v[204:207], v[4:7]
	v_mfma_f32_16x16x32_bf16 v[0:3], v[172:175], v[204:207], v[0:3]
	s_setprio 0
	s_barrier
; #define PG8_WAIT_V(n) asm volatile("s_waitcnt vmcnt(" #n ")" ::: "memory")
; #define PG8_WAIT_L(n) asm volatile("s_waitcnt lgkmcnt(" #n ")" ::: "memory")
; #define PG8_BAR __builtin_amdgcn_s_barrier()
; #define PG8_SCHED __builtin_amdgcn_sched_barrier(0)
;     ...
;             PG8_LDB(B0, 1, 0); PG8_LDB(B1, 1, 1); PG8_SCHED; PG8_LDA(At, 1, 0); PG8_STAGE(PG8_SA(0, 1), a2 + hstepA, voffA);
;             PG8_WAIT_V(8); PG8_WAIT_L(0); PG8_BAR; PG8_MMA(0, 0, At, B0); PG8_MMA(0, 1, At, B1); PG8_BAR; PG8_SCHED;
;             if constexpr (!HALFU) PG8_LDA(At, 1, 1); PG8_STAGE(PG8_SB(1, 0), b3, voffB); PG8_STAGE(PG8_SB(1, 1), b3 + hstep, voffB); PG8_STAGE(PG8_SA(1, 0), a3, voffA);
;             PG8_WAIT_V(8); PG8_WAIT_L(0); PG8_BAR; if constexpr (!HALFU) { PG8_MMA(1, 0, At, B0); PG8_MMA(1, 1, At, B1); } PG8_BAR; PG8_SCHED;
	s_mov_b32 m0, s23
	s_nop 0
	global_load_lds_dwordx4 v134, s[36:37]
	s_mov_b32 m0, s43
	s_nop 0
	global_load_lds_dwordx4 v132, s[36:37]
	s_add_i32 s60, 0, 0x18000
	v_add_u32_e32 v138, s60, v140
	s_add_i32 s61, 0, 0x1c000
	ds_read_b128 v[144:147], v138
	ds_read_b128 v[148:151], v138 offset:1024
	ds_read_b128 v[152:155], v138 offset:2048
	ds_read_b128 v[156:159], v138 offset:3072
	v_add_u32_e32 v138, s61, v140
	ds_read_b128 v[160:163], v138
	ds_read_b128 v[164:167], v138 offset:1024
	ds_read_b128 v[168:171], v138 offset:2048
	ds_read_b128 v[172:175], v138 offset:3072
	s_add_u32 s24, s36, 0x100000
	s_addc_u32 s25, s37, 0
	s_mov_b32 m0, s44
	ds_read_b128 v[176:179], v143 offset:32768
	ds_read_b128 v[180:183], v143 offset:33792
	ds_read_b128 v[184:187], v143 offset:34816
	ds_read_b128 v[188:191], v143 offset:35840
	ds_read_b128 v[192:195], v143 offset:36864
	ds_read_b128 v[196:199], v143 offset:37888
	ds_read_b128 v[200:203], v143 offset:38912
	ds_read_b128 v[204:207], v143 offset:39936
	global_load_lds_dwordx4 v134, s[24:25]
	s_mov_b32 m0, s45
	s_nop 0
	global_load_lds_dwordx4 v132, s[24:25]
	s_waitcnt vmcnt(8)
	s_waitcnt lgkmcnt(0)
	s_barrier
	s_setprio 1
	s_waitcnt lgkmcnt(0)
	v_mfma_f32_16x16x32_bf16 v[124:127], v[144:147], v[176:179], v[124:127]
	v_mfma_f32_16x16x32_bf16 v[120:123], v[152:155], v[176:179], v[120:123]
	v_mfma_f32_16x16x32_bf16 v[108:111], v[144:147], v[184:187], v[108:111]
	v_mfma_f32_16x16x32_bf16 v[104:107], v[152:155], v[184:187], v[104:107]
	v_mfma_f32_16x16x32_bf16 v[92:95], v[144:147], v[192:195], v[92:95]
	v_mfma_f32_16x16x32_bf16 v[88:91], v[152:155], v[192:195], v[88:91]
	v_mfma_f32_16x16x32_bf16 v[76:79], v[144:147], v[200:203], v[76:79]
	v_mfma_f32_16x16x32_bf16 v[72:75], v[152:155], v[200:203], v[72:75]
	v_mfma_f32_16x16x32_bf16 v[124:127], v[148:151], v[180:183], v[124:127]
	v_mfma_f32_16x16x32_bf16 v[120:123], v[156:159], v[180:183], v[120:123]
	v_mfma_f32_16x16x32_bf16 v[108:111], v[148:151], v[188:191], v[108:111]
	v_mfma_f32_16x16x32_bf16 v[104:107], v[156:159], v[188:191], v[104:107]
	v_mfma_f32_16x16x32_bf16 v[92:95], v[148:151], v[196:199], v[92:95]
	v_mfma_f32_16x16x32_bf16 v[88:91], v[156:159], v[196:199], v[88:91]
	v_mfma_f32_16x16x32_bf16 v[76:79], v[148:151], v[204:207], v[76:79]
	v_mfma_f32_16x16x32_bf16 v[72:75], v[156:159], v[204:207], v[72:75]
	s_setprio 0
	s_setprio 1
	v_mfma_f32_16x16x32_bf16 v[116:119], v[160:163], v[176:179], v[116:119]
	v_mfma_f32_16x16x32_bf16 v[112:115], v[168:171], v[176:179], v[112:115]
	v_mfma_f32_16x16x32_bf16 v[100:103], v[160:163], v[184:187], v[100:103]
	v_mfma_f32_16x16x32_bf16 v[96:99], v[168:171], v[184:187], v[96:99]
	v_mfma_f32_16x16x32_bf16 v[84:87], v[160:163], v[192:195], v[84:87]
	v_mfma_f32_16x16x32_bf16 v[80:83], v[168:171], v[192:195], v[80:83]
	v_mfma_f32_16x16x32_bf16 v[68:71], v[160:163], v[200:203], v[68:71]
	v_mfma_f32_16x16x32_bf16 v[64:67], v[168:171], v[200:203], v[64:67]
	v_mfma_f32_16x16x32_bf16 v[116:119], v[164:167], v[180:183], v[116:119]
	v_mfma_f32_16x16x32_bf16 v[112:115], v[172:175], v[180:183], v[112:115]
	v_mfma_f32_16x16x32_bf16 v[100:103], v[164:167], v[188:191], v[100:103]
	v_mfma_f32_16x16x32_bf16 v[96:99], v[172:175], v[188:191], v[96:99]
	v_mfma_f32_16x16x32_bf16 v[84:87], v[164:167], v[196:199], v[84:87]
	v_mfma_f32_16x16x32_bf16 v[80:83], v[172:175], v[196:199], v[80:83]
	v_mfma_f32_16x16x32_bf16 v[68:71], v[164:167], v[204:207], v[68:71]
	v_mfma_f32_16x16x32_bf16 v[64:67], v[172:175], v[204:207], v[64:67]
	s_setprio 0
	s_barrier
	s_add_u32 s24, s30, 0x80
	s_addc_u32 s25, s31, 0
	s_add_i32 s36, s60, s40
	s_mov_b32 m0, s36
	ds_read_b128 v[176:179], v143 offset:49152
	ds_read_b128 v[180:183], v143 offset:50176
	ds_read_b128 v[184:187], v143 offset:51200
	ds_read_b128 v[188:191], v143 offset:52224
	ds_read_b128 v[192:195], v143 offset:53248
	ds_read_b128 v[196:199], v143 offset:54272
	ds_read_b128 v[200:203], v143 offset:55296
	ds_read_b128 v[204:207], v143 offset:56320
	global_load_lds_dwordx4 v128, s[24:25]
	s_add_i32 m0, s36, 0x2000
	v_lshl_add_u64 v[138:139], s[24:25], 0, v[130:131]
	s_add_u32 s24, s30, 0x100080
	s_addc_u32 s25, s31, 0
	s_add_i32 s30, s61, s40
	global_load_lds_dwordx4 v[138:139], off
	s_mov_b32 m0, s30
	s_nop 0
	global_load_lds_dwordx4 v128, s[24:25]
	s_add_i32 m0, s30, 0x2000
	s_nop 0
	global_load_lds_dwordx4 v130, s[24:25]
	s_waitcnt vmcnt(4)
	s_waitcnt lgkmcnt(0)
	s_barrier
	s_setprio 1
	s_waitcnt lgkmcnt(0)
	v_mfma_f32_16x16x32_bf16 v[60:63], v[144:147], v[176:179], v[60:63]
	v_mfma_f32_16x16x32_bf16 v[56:59], v[152:155], v[176:179], v[56:59]
	v_mfma_f32_16x16x32_bf16 v[44:47], v[144:147], v[184:187], v[44:47]
	v_mfma_f32_16x16x32_bf16 v[40:43], v[152:155], v[184:187], v[40:43]
	v_mfma_f32_16x16x32_bf16 v[28:31], v[144:147], v[192:195], v[28:31]
	v_mfma_f32_16x16x32_bf16 v[24:27], v[152:155], v[192:195], v[24:27]
	v_mfma_f32_16x16x32_bf16 v[12:15], v[144:147], v[200:203], v[12:15]
	v_mfma_f32_16x16x32_bf16 v[8:11], v[152:155], v[200:203], v[8:11]
	v_mfma_f32_16x16x32_bf16 v[60:63], v[148:151], v[180:183], v[60:63]
	v_mfma_f32_16x16x32_bf16 v[56:59], v[156:159], v[180:183], v[56:59]
	v_mfma_f32_16x16x32_bf16 v[44:47], v[148:151], v[188:191], v[44:47]
	v_mfma_f32_16x16x32_bf16 v[40:43], v[156:159], v[188:191], v[40:43]
	v_mfma_f32_16x16x32_bf16 v[28:31], v[148:151], v[196:199], v[28:31]
	v_mfma_f32_16x16x32_bf16 v[24:27], v[156:159], v[196:199], v[24:27]
	v_mfma_f32_16x16x32_bf16 v[12:15], v[148:151], v[204:207], v[12:15]
	v_mfma_f32_16x16x32_bf16 v[8:11], v[156:159], v[204:207], v[8:11]
	s_setprio 0
	s_setprio 1
	v_mfma_f32_16x16x32_bf16 v[52:55], v[160:163], v[176:179], v[52:55]
	v_mfma_f32_16x16x32_bf16 v[48:51], v[168:171], v[176:179], v[48:51]
	v_mfma_f32_16x16x32_bf16 v[36:39], v[160:163], v[184:187], v[36:39]
	v_mfma_f32_16x16x32_bf16 v[32:35], v[168:171], v[184:187], v[32:35]
	v_mfma_f32_16x16x32_bf16 v[20:23], v[160:163], v[192:195], v[20:23]
	v_mfma_f32_16x16x32_bf16 v[16:19], v[168:171], v[192:195], v[16:19]
	v_mfma_f32_16x16x32_bf16 v[4:7], v[160:163], v[200:203], v[4:7]
	v_mfma_f32_16x16x32_bf16 v[0:3], v[168:171], v[200:203], v[0:3]
	v_mfma_f32_16x16x32_bf16 v[52:55], v[164:167], v[180:183], v[52:55]
	v_mfma_f32_16x16x32_bf16 v[48:51], v[172:175], v[180:183], v[48:51]
	v_mfma_f32_16x16x32_bf16 v[36:39], v[164:167], v[188:191], v[36:39]
	v_mfma_f32_16x16x32_bf16 v[32:35], v[172:175], v[188:191], v[32:35]
	v_mfma_f32_16x16x32_bf16 v[20:23], v[164:167], v[196:199], v[20:23]
	v_mfma_f32_16x16x32_bf16 v[16:19], v[172:175], v[196:199], v[16:19]
	v_mfma_f32_16x16x32_bf16 v[4:7], v[164:167], v[204:207], v[4:7]
	v_mfma_f32_16x16x32_bf16 v[0:3], v[172:175], v[204:207], v[0:3]
	s_setprio 0
	s_barrier
	s_add_i32 s59, s59, 2
	s_add_u32 s56, s56, 0x100
	s_addc_u32 s57, s57, 0
	s_cmp_gt_u32 s59, 61
	s_mov_b64 s[24:25], s[26:27]
	s_cbranch_scc0 .LBB0_3554
	s_and_b64 vcc, exec, s[10:11]
	s_cbranch_vccz .LBB0_3557
	s_barrier

; #define PG8_WAIT_V(n) asm volatile("s_waitcnt vmcnt(" #n ")" ::: "memory")
; #define PG8_WAIT_L(n) asm volatile("s_waitcnt lgkmcnt(" #n ")" ::: "memory")
; #define PG8_BAR __builtin_amdgcn_s_barrier()
; #define PG8_SCHED __builtin_amdgcn_sched_barrier(0)
;     ...
;         const bool has_next = S.next(ui + 1, nxt);
;         const char* nA = has_next ? (const char*)g.A + (size_t)nxt.pm * tstepA : cA; const char* nB = has_next ? (const char*)g.Bt + (size_t)nxt.pn * tstep : cB;
;         for (int t = 0; t < nt; t += 2) {
;             const bool last = (t == nt - 2);
;             const char* a1 = cA + (size_t)(t + 1) * kstep;
;             const char* a2 = last ? nA : cA + (size_t)(t + 2) * kstep; const char* b2 = last ? nB : cB + (size_t)(t + 2) * kstep;
;             const char* a3 = a2 + kstep; const char* b3 = b2 + kstep;
;             if (last && has_next) S.a_ready(nxt);
;             if constexpr (SP2) {
;             PG8_LDB(B0, 0, 0); PG8_LDB(B1, 0, 1); PG8_SCHED; PG8_LDA(At, 0, 0); PG8_STAGE(PG8_SA(1, 1), a1 + hstepA, voffA);
;             PG8_WAIT_V(8); PG8_WAIT_L(0); PG8_BAR; PG8_MMA(0, 0, At, B0); PG8_MMA(0, 1, At, B1); PG8_BAR; PG8_SCHED;
;             if constexpr (!HALFU) PG8_LDA(At, 0, 1); PG8_STAGE(PG8_SB(0, 0), b2, voffB); PG8_STAGE(PG8_SB(0, 1), b2 + hstep, voffB); PG8_STAGE(PG8_SA(0, 0), a2, voffA);
;             PG8_WAIT_V(8); PG8_WAIT_L(0); PG8_BAR; if constexpr (!HALFU) { PG8_MMA(1, 0, At, B0); PG8_MMA(1, 1, At, B1); } PG8_BAR; PG8_SCHED;
.LBB0_3640:
	s_sub_u32 s98, s10, 0x158000
	s_subb_u32 s99, s11, 0
	s_mov_b32 m0, s42
	s_nop 0
	global_load_lds_dwordx4 v128, s[98:99]
	s_mov_b32 m0, s43
	s_nop 0
	global_load_lds_dwordx4 v130, s[98:99]
	ds_read_b128 v[142:145], v137
	ds_read_b128 v[146:149], v137 offset:1024
	ds_read_b128 v[150:153], v137 offset:2048
	ds_read_b128 v[154:157], v137 offset:3072
	ds_read_b128 v[158:161], v138
	ds_read_b128 v[162:165], v138 offset:1024
	ds_read_b128 v[166:169], v138 offset:2048
	ds_read_b128 v[170:173], v138 offset:3072
	s_cmpk_eq_i32 s55, 0x52
	s_cselect_b32 s28, s6, s51
	s_cselect_b32 s29, s7, s52
	s_cselect_b32 s26, s22, s53
	s_cselect_b32 s27, s23, s54
	s_add_u32 s24, s28, 0x80
	s_addc_u32 s25, s29, 0
	s_add_i32 m0, s33, 0xc000
	ds_read_b128 v[174:177], v139
	ds_read_b128 v[178:181], v139 offset:1024
	ds_read_b128 v[182:185], v139 offset:2048
	ds_read_b128 v[186:189], v139 offset:3072
	ds_read_b128 v[190:193], v139 offset:4096
	ds_read_b128 v[194:197], v139 offset:5120
	ds_read_b128 v[198:201], v139 offset:6144
	ds_read_b128 v[202:205], v139 offset:7168
	global_load_lds_dwordx4 v128, s[10:11]
	s_add_i32 m0, s33, 0xe000
	s_nop 0
	global_load_lds_dwordx4 v130, s[10:11]
	s_waitcnt vmcnt(8)
	s_waitcnt lgkmcnt(0)
	s_barrier
	s_setprio 1
	s_waitcnt lgkmcnt(0)
	v_mfma_scale_f32_16x16x128_f8f6f4 v[124:127], v[142:149], v[174:181], v[124:127], v140, v140 op_sel_hi:[0,0,0]
	v_mfma_scale_f32_16x16x128_f8f6f4 v[120:123], v[150:157], v[174:181], v[120:123], v140, v140 op_sel_hi:[0,0,0]
	v_mfma_scale_f32_16x16x128_f8f6f4 v[112:115], v[142:149], v[182:189], v[112:115], v140, v140 op_sel_hi:[0,0,0]
	v_mfma_scale_f32_16x16x128_f8f6f4 v[104:107], v[150:157], v[182:189], v[104:107], v140, v140 op_sel_hi:[0,0,0]
	v_mfma_scale_f32_16x16x128_f8f6f4 v[96:99], v[142:149], v[190:197], v[96:99], v140, v140 op_sel_hi:[0,0,0]
	v_mfma_scale_f32_16x16x128_f8f6f4 v[206:209], v[150:157], v[190:197], v[88:91], v140, v140 op_sel_hi:[0,0,0]
	v_mfma_scale_f32_16x16x128_f8f6f4 v[210:213], v[142:149], v[198:205], v[80:83], v140, v140 op_sel_hi:[0,0,0]
	v_mfma_scale_f32_16x16x128_f8f6f4 v[214:217], v[150:157], v[198:205], v[72:75], v140, v140 op_sel_hi:[0,0,0]
	s_setprio 0
	s_setprio 1
	v_mfma_scale_f32_16x16x128_f8f6f4 v[116:119], v[158:165], v[174:181], v[116:119], v140, v140 op_sel_hi:[0,0,0]
	v_mfma_scale_f32_16x16x128_f8f6f4 v[108:111], v[166:173], v[174:181], v[108:111], v140, v140 op_sel_hi:[0,0,0]
	v_mfma_scale_f32_16x16x128_f8f6f4 v[100:103], v[158:165], v[182:189], v[100:103], v140, v140 op_sel_hi:[0,0,0]
	v_mfma_scale_f32_16x16x128_f8f6f4 v[174:177], v[166:173], v[182:189], v[92:95], v140, v140 op_sel_hi:[0,0,0]
	v_mfma_scale_f32_16x16x128_f8f6f4 v[178:181], v[158:165], v[190:197], v[84:87], v140, v140 op_sel_hi:[0,0,0]
	v_mfma_scale_f32_16x16x128_f8f6f4 v[182:185], v[166:173], v[190:197], v[76:79], v140, v140 op_sel_hi:[0,0,0]
	v_mfma_scale_f32_16x16x128_f8f6f4 v[186:189], v[158:165], v[198:205], v[68:71], v140, v140 op_sel_hi:[0,0,0]
	v_mfma_scale_f32_16x16x128_f8f6f4 v[190:193], v[166:173], v[198:205], v[64:67], v140, v140 op_sel_hi:[0,0,0]
	s_setprio 0
	s_barrier
	s_add_i32 s56, s45, s30
	s_mov_b32 m0, s56
	s_nop 1
	ds_read_b128 v[64:67], v139 offset:16384
	ds_read_b128 v[68:71], v139 offset:17408
	ds_read_b128 v[72:75], v139 offset:18432
	ds_read_b128 v[76:79], v139 offset:19456
	ds_read_b128 v[80:83], v139 offset:20480
	ds_read_b128 v[84:87], v139 offset:21504
	ds_read_b128 v[88:91], v139 offset:22528
	ds_read_b128 v[92:95], v139 offset:23552
	global_load_lds_dwordx4 v128, s[26:27]
	s_add_i32 m0, s56, 0x2000
	s_add_u32 s56, s26, 0x158000
	s_addc_u32 s57, s27, 0
	s_add_i32 s58, s46, s30
	global_load_lds_dwordx4 v130, s[26:27]
	s_mov_b32 m0, s58
	s_nop 0
	global_load_lds_dwordx4 v128, s[56:57]
	s_add_i32 m0, s58, 0x2000
	s_nop 0
	global_load_lds_dwordx4 v130, s[56:57]
	s_waitcnt vmcnt(4)
	s_waitcnt lgkmcnt(0)
	s_barrier
	s_setprio 1
	s_waitcnt lgkmcnt(0)
	v_mfma_scale_f32_16x16x128_f8f6f4 v[60:63], v[142:149], v[64:71], v[60:63], v140, v140 op_sel_hi:[0,0,0]
	v_mfma_scale_f32_16x16x128_f8f6f4 v[56:59], v[150:157], v[64:71], v[56:59], v140, v140 op_sel_hi:[0,0,0]
	v_mfma_scale_f32_16x16x128_f8f6f4 v[48:51], v[142:149], v[72:79], v[48:51], v140, v140 op_sel_hi:[0,0,0]
	v_mfma_scale_f32_16x16x128_f8f6f4 v[194:197], v[150:157], v[72:79], v[40:43], v140, v140 op_sel_hi:[0,0,0]
	v_mfma_scale_f32_16x16x128_f8f6f4 v[198:201], v[142:149], v[80:87], v[32:35], v140, v140 op_sel_hi:[0,0,0]
	v_mfma_scale_f32_16x16x128_f8f6f4 v[202:205], v[150:157], v[80:87], v[24:27], v140, v140 op_sel_hi:[0,0,0]
	v_mfma_scale_f32_16x16x128_f8f6f4 v[218:221], v[142:149], v[88:95], v[16:19], v140, v140 op_sel_hi:[0,0,0]
	v_mfma_scale_f32_16x16x128_f8f6f4 v[222:225], v[150:157], v[88:95], v[8:11], v140, v140 op_sel_hi:[0,0,0]
	s_setprio 0
	s_setprio 1
	v_mfma_scale_f32_16x16x128_f8f6f4 v[52:55], v[158:165], v[64:71], v[52:55], v140, v140 op_sel_hi:[0,0,0]
	v_mfma_scale_f32_16x16x128_f8f6f4 v[226:229], v[166:173], v[64:71], v[44:47], v140, v140 op_sel_hi:[0,0,0]
	v_mfma_scale_f32_16x16x128_f8f6f4 v[230:233], v[158:165], v[72:79], v[36:39], v140, v140 op_sel_hi:[0,0,0]
	v_mfma_scale_f32_16x16x128_f8f6f4 v[234:237], v[166:173], v[72:79], v[28:31], v140, v140 op_sel_hi:[0,0,0]
	v_mfma_scale_f32_16x16x128_f8f6f4 v[238:241], v[158:165], v[80:87], v[20:23], v140, v140 op_sel_hi:[0,0,0]
	v_mfma_scale_f32_16x16x128_f8f6f4 v[242:245], v[166:173], v[80:87], v[12:15], v140, v140 op_sel_hi:[0,0,0]
	v_mfma_scale_f32_16x16x128_f8f6f4 v[246:249], v[158:165], v[88:95], v[4:7], v140, v140 op_sel_hi:[0,0,0]
	v_mfma_scale_f32_16x16x128_f8f6f4 v[250:253], v[166:173], v[88:95], v[0:3], v140, v140 op_sel_hi:[0,0,0]
	s_setprio 0
	s_barrier
; #define PG8_WAIT_V(n) asm volatile("s_waitcnt vmcnt(" #n ")" ::: "memory")
; #define PG8_WAIT_L(n) asm volatile("s_waitcnt lgkmcnt(" #n ")" ::: "memory")
; #define PG8_BAR __builtin_amdgcn_s_barrier()
; #define PG8_SCHED __builtin_amdgcn_sched_barrier(0)
;     ...
;             PG8_LDB(B0, 1, 0); PG8_LDB(B1, 1, 1); PG8_SCHED; PG8_LDA(At, 1, 0); PG8_STAGE(PG8_SA(0, 1), a2 + hstepA, voffA);
;             PG8_WAIT_V(8); PG8_WAIT_L(0); PG8_BAR; PG8_MMA(0, 0, At, B0); PG8_MMA(0, 1, At, B1); PG8_BAR; PG8_SCHED;
;             if constexpr (!HALFU) PG8_LDA(At, 1, 1); PG8_STAGE(PG8_SB(1, 0), b3, voffB); PG8_STAGE(PG8_SB(1, 1), b3 + hstep, voffB); PG8_STAGE(PG8_SA(1, 0), a3, voffA);
;             PG8_WAIT_V(8); PG8_WAIT_L(0); PG8_BAR; if constexpr (!HALFU) { PG8_MMA(1, 0, At, B0); PG8_MMA(1, 1, At, B1); } PG8_BAR; PG8_SCHED;
	s_mov_b32 m0, s33
	s_nop 0
	global_load_lds_dwordx4 v128, s[28:29]
	s_mov_b32 m0, s36
	s_nop 0
	global_load_lds_dwordx4 v130, s[28:29]
	s_add_i32 s56, 0, 0x18000
	s_add_i32 s57, 0, 0x1c000
	s_nop 0
	v_add_u32_e32 v12, s56, v136
	v_add_u32_e32 v16, s57, v136
	ds_read_b128 v[0:3], v12
	ds_read_b128 v[4:7], v12 offset:1024
	ds_read_b128 v[8:11], v12 offset:2048
	ds_read_b128 v[12:15], v12 offset:3072
	ds_read_b128 v[142:145], v16
	ds_read_b128 v[146:149], v16 offset:1024
	ds_read_b128 v[150:153], v16 offset:2048
	ds_read_b128 v[154:157], v16 offset:3072
	s_add_u32 s28, s28, 0x158000
	s_addc_u32 s29, s29, 0
	s_mov_b32 m0, s37
	ds_read_b128 v[16:19], v139 offset:32768
	ds_read_b128 v[20:23], v139 offset:33792
	ds_read_b128 v[24:27], v139 offset:34816
	ds_read_b128 v[28:31], v139 offset:35840
	ds_read_b128 v[32:35], v139 offset:36864
	ds_read_b128 v[36:39], v139 offset:37888
	ds_read_b128 v[40:43], v139 offset:38912
	ds_read_b128 v[44:47], v139 offset:39936
	global_load_lds_dwordx4 v128, s[28:29]
	s_mov_b32 m0, s38
	s_nop 0
	global_load_lds_dwordx4 v130, s[28:29]
	s_waitcnt vmcnt(8)
	s_waitcnt lgkmcnt(0)
	s_barrier
	s_setprio 1
	s_waitcnt lgkmcnt(0)
	v_mfma_scale_f32_16x16x128_f8f6f4 v[124:127], v[0:7], v[16:23], v[124:127], v140, v140 op_sel_hi:[0,0,0]
	v_mfma_scale_f32_16x16x128_f8f6f4 v[120:123], v[8:15], v[16:23], v[120:123], v140, v140 op_sel_hi:[0,0,0]
	v_mfma_scale_f32_16x16x128_f8f6f4 v[112:115], v[0:7], v[24:31], v[112:115], v140, v140 op_sel_hi:[0,0,0]
	v_mfma_scale_f32_16x16x128_f8f6f4 v[104:107], v[8:15], v[24:31], v[104:107], v140, v140 op_sel_hi:[0,0,0]
	v_mfma_scale_f32_16x16x128_f8f6f4 v[96:99], v[0:7], v[32:39], v[96:99], v140, v140 op_sel_hi:[0,0,0]
	v_mfma_scale_f32_16x16x128_f8f6f4 v[88:91], v[8:15], v[32:39], v[206:209], v140, v140 op_sel_hi:[0,0,0]
	v_mfma_scale_f32_16x16x128_f8f6f4 v[80:83], v[0:7], v[40:47], v[210:213], v140, v140 op_sel_hi:[0,0,0]
	v_mfma_scale_f32_16x16x128_f8f6f4 v[72:75], v[8:15], v[40:47], v[214:217], v140, v140 op_sel_hi:[0,0,0]
	s_setprio 0
	s_setprio 1
	v_mfma_scale_f32_16x16x128_f8f6f4 v[116:119], v[142:149], v[16:23], v[116:119], v140, v140 op_sel_hi:[0,0,0]
	v_mfma_scale_f32_16x16x128_f8f6f4 v[108:111], v[150:157], v[16:23], v[108:111], v140, v140 op_sel_hi:[0,0,0]
	v_mfma_scale_f32_16x16x128_f8f6f4 v[100:103], v[142:149], v[24:31], v[100:103], v140, v140 op_sel_hi:[0,0,0]
	v_mfma_scale_f32_16x16x128_f8f6f4 v[92:95], v[150:157], v[24:31], v[174:177], v140, v140 op_sel_hi:[0,0,0]
	v_mfma_scale_f32_16x16x128_f8f6f4 v[84:87], v[142:149], v[32:39], v[178:181], v140, v140 op_sel_hi:[0,0,0]
	v_mfma_scale_f32_16x16x128_f8f6f4 v[76:79], v[150:157], v[32:39], v[182:185], v140, v140 op_sel_hi:[0,0,0]
	v_mfma_scale_f32_16x16x128_f8f6f4 v[68:71], v[142:149], v[40:47], v[186:189], v140, v140 op_sel_hi:[0,0,0]
	v_mfma_scale_f32_16x16x128_f8f6f4 v[64:67], v[150:157], v[40:47], v[190:193], v140, v140 op_sel_hi:[0,0,0]
	s_setprio 0
	s_barrier
	s_add_u32 s28, s26, 0x80
	s_addc_u32 s29, s27, 0
	s_add_i32 s56, s56, s30
	s_mov_b32 m0, s56
	ds_read_b128 v[158:161], v139 offset:49152
	ds_read_b128 v[162:165], v139 offset:50176
	ds_read_b128 v[166:169], v139 offset:51200
	ds_read_b128 v[170:173], v139 offset:52224
	ds_read_b128 v[174:177], v139 offset:53248
	ds_read_b128 v[178:181], v139 offset:54272
	ds_read_b128 v[182:185], v139 offset:55296
	ds_read_b128 v[186:189], v139 offset:56320
	global_load_lds_dwordx4 v128, s[28:29]
	s_add_i32 m0, s56, 0x2000
	s_add_u32 s26, s26, 0x158080
	v_lshl_add_u64 v[16:17], s[28:29], 0, v[130:131]
	s_addc_u32 s27, s27, 0
	s_add_i32 s28, s57, s30
	global_load_lds_dwordx4 v[16:17], off
	s_mov_b32 m0, s28
	s_nop 0
	global_load_lds_dwordx4 v128, s[26:27]
	s_add_i32 m0, s28, 0x2000
	s_nop 0
	global_load_lds_dwordx4 v130, s[26:27]
	s_waitcnt vmcnt(4)
	s_waitcnt lgkmcnt(0)
	s_barrier
	s_setprio 1
	s_waitcnt lgkmcnt(0)
	v_mfma_scale_f32_16x16x128_f8f6f4 v[60:63], v[0:7], v[158:165], v[60:63], v140, v140 op_sel_hi:[0,0,0]
	v_mfma_scale_f32_16x16x128_f8f6f4 v[56:59], v[8:15], v[158:165], v[56:59], v140, v140 op_sel_hi:[0,0,0]
	v_mfma_scale_f32_16x16x128_f8f6f4 v[48:51], v[0:7], v[166:173], v[48:51], v140, v140 op_sel_hi:[0,0,0]
	v_mfma_scale_f32_16x16x128_f8f6f4 v[40:43], v[8:15], v[166:173], v[194:197], v140, v140 op_sel_hi:[0,0,0]
	v_mfma_scale_f32_16x16x128_f8f6f4 v[32:35], v[0:7], v[174:181], v[198:201], v140, v140 op_sel_hi:[0,0,0]
	v_mfma_scale_f32_16x16x128_f8f6f4 v[24:27], v[8:15], v[174:181], v[202:205], v140, v140 op_sel_hi:[0,0,0]
	v_mfma_scale_f32_16x16x128_f8f6f4 v[16:19], v[0:7], v[182:189], v[218:221], v140, v140 op_sel_hi:[0,0,0]
	v_mfma_scale_f32_16x16x128_f8f6f4 v[8:11], v[8:15], v[182:189], v[222:225], v140, v140 op_sel_hi:[0,0,0]
	s_setprio 0
	s_setprio 1
	v_mfma_scale_f32_16x16x128_f8f6f4 v[52:55], v[142:149], v[158:165], v[52:55], v140, v140 op_sel_hi:[0,0,0]
	v_mfma_scale_f32_16x16x128_f8f6f4 v[44:47], v[150:157], v[158:165], v[226:229], v140, v140 op_sel_hi:[0,0,0]
	v_mfma_scale_f32_16x16x128_f8f6f4 v[36:39], v[142:149], v[166:173], v[230:233], v140, v140 op_sel_hi:[0,0,0]
	v_mfma_scale_f32_16x16x128_f8f6f4 v[28:31], v[150:157], v[166:173], v[234:237], v140, v140 op_sel_hi:[0,0,0]
	v_mfma_scale_f32_16x16x128_f8f6f4 v[20:23], v[142:149], v[174:181], v[238:241], v140, v140 op_sel_hi:[0,0,0]
	v_mfma_scale_f32_16x16x128_f8f6f4 v[12:15], v[150:157], v[174:181], v[242:245], v140, v140 op_sel_hi:[0,0,0]
	v_mfma_scale_f32_16x16x128_f8f6f4 v[4:7], v[142:149], v[182:189], v[246:249], v140, v140 op_sel_hi:[0,0,0]
	v_mfma_scale_f32_16x16x128_f8f6f4 v[0:3], v[150:157], v[182:189], v[250:253], v140, v140 op_sel_hi:[0,0,0]
	s_setprio 0
	s_barrier
	s_add_i32 s55, s55, 2
	s_add_u32 s51, s51, 0x100
	s_addc_u32 s52, s52, 0
	s_add_u32 s53, s53, 0x100
	s_addc_u32 s54, s54, 0
	s_add_u32 s10, s10, 0x100
	s_addc_u32 s11, s11, 0
	s_cmpk_gt_u32 s55, 0x53
	s_cbranch_scc0 .LBB0_3640
	s_and_b64 vcc, exec, s[12:13]
	s_cbranch_vccz .LBB0_3643
	s_barrier
